# stack_g + merged vmcnt/lgkmcnt waits ahead of the pre-MFMA barriers
# baseline (speedup 1.0000x reference)
;     __host__ __device__ bool next(int i, Unit& u) const { const int t = i / 3, b = i - 3 * t; Unit v; if (!StaticOrder::next(t, v)) return false; u.pm = v.pm; u.pn = 8 * b + v.pn; return true; }
; #define PG8_STAGE(bufoff, gbase, voff) do { const int so_ = (int)(unsigned)((const char*)(gbase) - base_##voff); _Pragma("unroll") for (int _i = 0; _i < 2; ++_i) \
;         __builtin_amdgcn_raw_ptr_buffer_load_lds(rs_##voff, (PG8_LAS unsigned*)(lds + (bufoff) + ldsw + _i * 8192), 16, (int)(voff)[_i], so_, 0, 0); } while (0)
; #define PG8_LDA(dst, b, h) do { _Pragma("unroll") for (int m = 0; m < 4; ++m) _Pragma("unroll") for (int k = 0; k < 2; ++k) dst[m][k] = *(const PG8_LAS bf16x8*)(lds + PG8_SA(b, h) + aoff + m * 2048 + k * 1024); } while (0)
; #define PG8_WAIT_V(n) asm volatile("s_waitcnt vmcnt(" #n ")" ::: "memory")
; #define PG8_WAIT_L(n) asm volatile("s_waitcnt lgkmcnt(" #n ")" ::: "memory")
; #define PG8_BAR __builtin_amdgcn_s_barrier()
; template <class Epi, class Sched, bool ALIGN_EPI = false, bool SP2 = false>
; __device__ __forceinline__ void gemm_phase(PG8_LAS unsigned char* lds, const Gemm g, const Sched& S, const Epi& E, int tid_in) {
;     ...
;         const bool has_next = S.next(ui + 1, nxt);
;         const char* nA = has_next ? (const char*)g.A + (size_t)nxt.pm * tstepA + (g.grp ? (size_t)(nxt.pn / g.grp) * g.agrp : (size_t)0) : cA; const char* nB = has_next ? (const char*)g.Bt + (size_t)nxt.pn * tstepB : cB;
;         for (int t = 0; t < nt; t += 2) {
;             const bool last = (t == nt - 2);
;             const char* a1 = cA + (size_t)(t + 1) * kstep;
;             const char* a2 = last ? nA : cA + (size_t)(t + 2) * kstep; const char* b2 = last ? nB : cB + (size_t)(t + 2) * kstep;
;             const char* a3 = a2 + kstep; const char* b3 = b2 + kstep;
;             if (last && has_next) S.a_ready(nxt);
;             if constexpr (SP2) {
;             PG8_LDB(B0, 0, 0); PG8_LDB(B1, 0, 1); PG8_SCHED; PG8_LDA(At, 0, 0); PG8_STAGE(PG8_SA(1, 1), a1 + hstepA, voffA);
;             PG8_WAIT_V(8); PG8_WAIT_L(0); PG8_BAR; PG8_MMA(0, 0, At, B0); PG8_MMA(0, 1, At, B1); PG8_BAR; PG8_SCHED;
;             PG8_LDA(At, 0, 1); PG8_STAGE(PG8_SB(0, 0), b2, voffB); PG8_STAGE(PG8_SB(0, 1), b2 + hstepB, voffB); PG8_STAGE(PG8_SA(0, 0), a2, voffA);
;             PG8_WAIT_V(8); PG8_WAIT_L(0); PG8_BAR; PG8_MMA(1, 0, At, B0); PG8_MMA(1, 1, At, B1); PG8_BAR; PG8_SCHED;
.LBB0_311:
	s_ashr_i32 s23, s22, 31
	s_lshl_b64 s[10:11], s[22:23], 20
	s_add_u32 s24, s4, s10
	s_addc_u32 s25, s26, s11
	s_and_b64 s[10:11], s[34:35], exec
	s_cselect_b32 s19, s24, s12
	s_ashr_i32 s15, s14, 31
	s_lshl_b64 s[10:11], s[14:15], 20
	s_add_u32 s10, s40, s10
	s_addc_u32 s11, s60, s11
	s_and_b64 s[20:21], s[34:35], exec
	s_cselect_b32 s15, s10, s16
	s_add_u32 s20, s16, 0x100
	v_mov_b32_e32 v2, 0
	s_addc_u32 s21, s17, 0
	s_mov_b32 s23, -2
	v_add_u32_e32 v0, 0x10000, v237
	ds_read_b128 v[130:133], v0
	ds_read_b128 v[134:137], v0 offset:1024
	ds_read_b128 v[138:141], v0 offset:2048
	ds_read_b128 v[142:145], v0 offset:3072
	v_add_u32_e32 v0, 0x14000, v237
	ds_read_b128 v[146:149], v0
	ds_read_b128 v[150:153], v0 offset:1024
	ds_read_b128 v[154:157], v0 offset:2048
	ds_read_b128 v[158:161], v0 offset:3072
	s_add_u32 s16, s12, 0x100
	s_addc_u32 s17, s13, 0
	s_sub_i32 s12, s12, s4
	s_add_i32 s12, s12, 0x80080
	s_sub_i32 s36, s12, 0x80000
	s_cmp_eq_u32 s23, 28
	s_cselect_b32 s13, s19, s16
	s_mov_b32 m0, s69
	ds_read_b128 v[162:165], v238
	ds_read_b128 v[166:169], v238 offset:1024
	ds_read_b128 v[170:173], v238 offset:2048
	ds_read_b128 v[174:177], v238 offset:3072
	ds_read_b128 v[178:181], v238 offset:4096
	ds_read_b128 v[182:185], v238 offset:5120
	ds_read_b128 v[186:189], v238 offset:6144
	ds_read_b128 v[190:193], v238 offset:7168
	s_mov_b32 m0, s78
	s_nop 0
	buffer_load_dwordx4 v211, s[4:7], s36 offen lds
	s_mov_b32 m0, s69
	s_nop 0
	buffer_load_dwordx4 v195, s[4:7], s12 offen lds
	s_mov_b32 m0, s67
	s_nop 0
	buffer_load_dwordx4 v211, s[4:7], s12 offen lds
	s_waitcnt vmcnt(8) lgkmcnt(0)
	s_setprio 1
	s_barrier
	v_mfma_f32_16x16x32_bf16 v[126:129], v[130:133], v[162:165], 0
	v_mfma_f32_16x16x32_bf16 v[122:125], v[138:141], v[162:165], 0
	v_mfma_f32_16x16x32_bf16 v[106:109], v[138:141], v[170:173], 0
	v_mfma_f32_16x16x32_bf16 v[110:113], v[130:133], v[170:173], 0
	v_mfma_f32_16x16x32_bf16 v[94:97], v[130:133], v[178:181], 0
	v_mfma_f32_16x16x32_bf16 v[90:93], v[138:141], v[178:181], 0
	v_mfma_f32_16x16x32_bf16 v[74:77], v[138:141], v[186:189], 0
	v_mfma_f32_16x16x32_bf16 v[78:81], v[130:133], v[186:189], 0
	v_mfma_f32_16x16x32_bf16 v[126:129], v[134:137], v[166:169], v[126:129]
	v_mfma_f32_16x16x32_bf16 v[122:125], v[142:145], v[166:169], v[122:125]
	v_mfma_f32_16x16x32_bf16 v[106:109], v[142:145], v[174:177], v[106:109]
	v_mfma_f32_16x16x32_bf16 v[110:113], v[134:137], v[174:177], v[110:113]
	v_mfma_f32_16x16x32_bf16 v[94:97], v[134:137], v[182:185], v[94:97]
	v_mfma_f32_16x16x32_bf16 v[90:93], v[142:145], v[182:185], v[90:93]
	v_mfma_f32_16x16x32_bf16 v[74:77], v[142:145], v[190:193], v[74:77]
	v_mfma_f32_16x16x32_bf16 v[78:81], v[134:137], v[190:193], v[78:81]
	v_mfma_f32_16x16x32_bf16 v[118:121], v[146:149], v[162:165], 0
	v_mfma_f32_16x16x32_bf16 v[114:117], v[154:157], v[162:165], 0
	v_mfma_f32_16x16x32_bf16 v[98:101], v[154:157], v[170:173], 0
	v_mfma_f32_16x16x32_bf16 v[102:105], v[146:149], v[170:173], 0
	v_mfma_f32_16x16x32_bf16 v[86:89], v[146:149], v[178:181], 0
	v_mfma_f32_16x16x32_bf16 v[82:85], v[154:157], v[178:181], 0
	v_mfma_f32_16x16x32_bf16 v[66:69], v[154:157], v[186:189], 0
	v_mfma_f32_16x16x32_bf16 v[70:73], v[146:149], v[186:189], 0
	v_mfma_f32_16x16x32_bf16 v[118:121], v[150:153], v[166:169], v[118:121]
	v_mfma_f32_16x16x32_bf16 v[114:117], v[158:161], v[166:169], v[114:117]
	v_mfma_f32_16x16x32_bf16 v[98:101], v[158:161], v[174:177], v[98:101]
	v_mfma_f32_16x16x32_bf16 v[102:105], v[150:153], v[174:177], v[102:105]
	v_mfma_f32_16x16x32_bf16 v[86:89], v[150:153], v[182:185], v[86:89]
	v_mfma_f32_16x16x32_bf16 v[82:85], v[158:161], v[182:185], v[82:85]
	v_mfma_f32_16x16x32_bf16 v[66:69], v[158:161], v[190:193], v[66:69]
	v_mfma_f32_16x16x32_bf16 v[70:73], v[150:153], v[190:193], v[70:73]
	s_barrier
	s_setprio 0
	s_cselect_b32 s12, s15, s20
	s_mov_b32 m0, s61
	s_mov_b32 s42, s6
	s_mov_b32 s43, s7
	s_sub_i32 s12, s12, s40
	ds_read_b128 v[162:165], v238 offset:16384
	ds_read_b128 v[166:169], v238 offset:17408
	ds_read_b128 v[170:173], v238 offset:18432
	ds_read_b128 v[174:177], v238 offset:19456
	ds_read_b128 v[178:181], v238 offset:20480
	ds_read_b128 v[182:185], v238 offset:21504
	ds_read_b128 v[186:189], v238 offset:22528
	ds_read_b128 v[190:193], v238 offset:23552
	buffer_load_dwordx4 v207, s[40:43], s12 offen lds
	s_mov_b32 m0, s62
	s_add_i32 s36, s12, 0x80000
	buffer_load_dwordx4 v224, s[40:43], s12 offen lds
	s_mov_b32 m0, s63
	s_sub_i32 s13, s13, s4
	buffer_load_dwordx4 v207, s[40:43], s36 offen lds
	s_mov_b32 m0, s71
	s_nop 0
	buffer_load_dwordx4 v224, s[40:43], s36 offen lds
	s_mov_b32 m0, s53
	s_nop 0
	buffer_load_dwordx4 v195, s[4:7], s13 offen lds
	s_waitcnt vmcnt(7) lgkmcnt(0)
	s_setprio 1
	s_barrier
; #define PG8_STAGE(bufoff, gbase, voff) do { const int so_ = (int)(unsigned)((const char*)(gbase) - base_##voff); _Pragma("unroll") for (int _i = 0; _i < 2; ++_i) \
;         __builtin_amdgcn_raw_ptr_buffer_load_lds(rs_##voff, (PG8_LAS unsigned*)(lds + (bufoff) + ldsw + _i * 8192), 16, (int)(voff)[_i], so_, 0, 0); } while (0)
; #define PG8_LDA(dst, b, h) do { _Pragma("unroll") for (int m = 0; m < 4; ++m) _Pragma("unroll") for (int k = 0; k < 2; ++k) dst[m][k] = *(const PG8_LAS bf16x8*)(lds + PG8_SA(b, h) + aoff + m * 2048 + k * 1024); } while (0)
; #define PG8_LDB(dst, b, h) do { _Pragma("unroll") for (int n = 0; n < 2; ++n) _Pragma("unroll") for (int k = 0; k < 2; ++k) dst[n][k] = *(const PG8_LAS bf16x8*)(lds + PG8_SB(b, h) + boff + n * 2048 + k * 1024); } while (0)
; #define PG8_MMA(ai, bj, At, Bt) do { __builtin_amdgcn_s_setprio(1); _Pragma("unroll") for (int m = 0; m < 4; ++m) _Pragma("unroll") for (int n = 0; n < 2; ++n) _Pragma("unroll") for (int k = 0; k < 2; ++k) \
;         acc[ai][bj][m][n] = __builtin_amdgcn_mfma_f32_16x16x32_bf16(Bt[n][k], At[m][k], acc[ai][bj][m][n], 0, 0, 0); __builtin_amdgcn_s_setprio(0); } while (0)
; #define PG8_WAIT_V(n) asm volatile("s_waitcnt vmcnt(" #n ")" ::: "memory")
; #define PG8_WAIT_L(n) asm volatile("s_waitcnt lgkmcnt(" #n ")" ::: "memory")
; #define PG8_BAR __builtin_amdgcn_s_barrier()
; #define PG8_SCHED __builtin_amdgcn_sched_barrier(0)
; template <class Epi, class Sched, bool ALIGN_EPI = false, bool SP2 = false>
; __device__ __forceinline__ void gemm_phase(PG8_LAS unsigned char* lds, const Gemm g, const Sched& S, const Epi& E, int tid_in) {
;     ...
;             PG8_WAIT_V(8); PG8_WAIT_L(0); PG8_BAR; PG8_MMA(1, 0, At, B0); PG8_MMA(1, 1, At, B1); PG8_BAR; PG8_SCHED;
;             PG8_LDB(B0, 1, 0); PG8_LDB(B1, 1, 1); PG8_SCHED; PG8_LDA(At, 1, 0); PG8_STAGE(PG8_SA(0, 1), a2 + hstepA, voffA);
;             PG8_WAIT_V(8); PG8_WAIT_L(0); PG8_BAR; PG8_MMA(0, 0, At, B0); PG8_MMA(0, 1, At, B1); PG8_BAR; PG8_SCHED;
	v_mfma_f32_16x16x32_bf16 v[62:65], v[130:133], v[162:165], 0
	v_mfma_f32_16x16x32_bf16 v[58:61], v[138:141], v[162:165], 0
	v_mfma_f32_16x16x32_bf16 v[42:45], v[138:141], v[170:173], 0
	v_mfma_f32_16x16x32_bf16 v[46:49], v[130:133], v[170:173], 0
	v_mfma_f32_16x16x32_bf16 v[30:33], v[130:133], v[178:181], 0
	v_mfma_f32_16x16x32_bf16 v[26:29], v[138:141], v[178:181], 0
	v_mfma_f32_16x16x32_bf16 v[10:13], v[138:141], v[186:189], 0
	v_mfma_f32_16x16x32_bf16 v[14:17], v[130:133], v[186:189], 0
	v_mfma_f32_16x16x32_bf16 v[62:65], v[134:137], v[166:169], v[62:65]
	v_mfma_f32_16x16x32_bf16 v[58:61], v[142:145], v[166:169], v[58:61]
	v_mfma_f32_16x16x32_bf16 v[42:45], v[142:145], v[174:177], v[42:45]
	v_mfma_f32_16x16x32_bf16 v[46:49], v[134:137], v[174:177], v[46:49]
	v_mfma_f32_16x16x32_bf16 v[30:33], v[134:137], v[182:185], v[30:33]
	v_mfma_f32_16x16x32_bf16 v[26:29], v[142:145], v[182:185], v[26:29]
	v_mfma_f32_16x16x32_bf16 v[10:13], v[142:145], v[190:193], v[10:13]
	v_mfma_f32_16x16x32_bf16 v[14:17], v[134:137], v[190:193], v[14:17]
	v_mfma_f32_16x16x32_bf16 v[54:57], v[146:149], v[162:165], 0
	v_mfma_f32_16x16x32_bf16 v[50:53], v[154:157], v[162:165], 0
	v_mfma_f32_16x16x32_bf16 v[34:37], v[154:157], v[170:173], 0
	v_mfma_f32_16x16x32_bf16 v[38:41], v[146:149], v[170:173], 0
	v_mfma_f32_16x16x32_bf16 v[22:25], v[146:149], v[178:181], 0
	v_mfma_f32_16x16x32_bf16 v[18:21], v[154:157], v[178:181], 0
	v_mfma_f32_16x16x32_bf16 v[2:5], v[154:157], v[186:189], 0
	v_mfma_f32_16x16x32_bf16 v[6:9], v[146:149], v[186:189], 0
	v_mfma_f32_16x16x32_bf16 v[54:57], v[150:153], v[166:169], v[54:57]
	v_mfma_f32_16x16x32_bf16 v[50:53], v[158:161], v[166:169], v[50:53]
	v_mfma_f32_16x16x32_bf16 v[34:37], v[158:161], v[174:177], v[34:37]
	v_mfma_f32_16x16x32_bf16 v[38:41], v[150:153], v[174:177], v[38:41]
	v_mfma_f32_16x16x32_bf16 v[22:25], v[150:153], v[182:185], v[22:25]
	v_mfma_f32_16x16x32_bf16 v[18:21], v[158:161], v[182:185], v[18:21]
	v_mfma_f32_16x16x32_bf16 v[2:5], v[158:161], v[190:193], v[2:5]
	v_mfma_f32_16x16x32_bf16 v[6:9], v[150:153], v[190:193], v[6:9]
	s_barrier
	s_setprio 0
	v_add_u32_e32 v0, 0x18000, v237
	ds_read_b128 v[130:133], v0
	ds_read_b128 v[134:137], v0 offset:1024
	ds_read_b128 v[138:141], v0 offset:2048
	ds_read_b128 v[142:145], v0 offset:3072
	v_add_u32_e32 v0, 0x1c000, v237
	ds_read_b128 v[146:149], v0
	ds_read_b128 v[150:153], v0 offset:1024
	ds_read_b128 v[154:157], v0 offset:2048
	ds_read_b128 v[158:161], v0 offset:3072
	s_add_i32 s36, s13, 0x80000
	s_mov_b32 m0, s73
	ds_read_b128 v[162:165], v238 offset:32768
	ds_read_b128 v[166:169], v238 offset:33792
	ds_read_b128 v[170:173], v238 offset:34816
	ds_read_b128 v[174:177], v238 offset:35840
	ds_read_b128 v[178:181], v238 offset:36864
	ds_read_b128 v[182:185], v238 offset:37888
	ds_read_b128 v[186:189], v238 offset:38912
	ds_read_b128 v[190:193], v238 offset:39936
	s_mov_b32 m0, s72
	s_nop 0
	buffer_load_dwordx4 v211, s[4:7], s13 offen lds
	s_mov_b32 m0, s73
	s_nop 0
	buffer_load_dwordx4 v195, s[4:7], s36 offen lds
	s_mov_b32 m0, s74
	s_nop 0
	buffer_load_dwordx4 v211, s[4:7], s36 offen lds
	s_waitcnt vmcnt(8) lgkmcnt(0)
	s_setprio 1
	s_barrier
	v_mfma_f32_16x16x32_bf16 v[126:129], v[130:133], v[162:165], v[126:129]
	v_mfma_f32_16x16x32_bf16 v[122:125], v[138:141], v[162:165], v[122:125]
	v_mfma_f32_16x16x32_bf16 v[106:109], v[138:141], v[170:173], v[106:109]
	v_mfma_f32_16x16x32_bf16 v[110:113], v[130:133], v[170:173], v[110:113]
	v_mfma_f32_16x16x32_bf16 v[94:97], v[130:133], v[178:181], v[94:97]
	v_mfma_f32_16x16x32_bf16 v[90:93], v[138:141], v[178:181], v[90:93]
	v_mfma_f32_16x16x32_bf16 v[74:77], v[138:141], v[186:189], v[74:77]
	v_mfma_f32_16x16x32_bf16 v[78:81], v[130:133], v[186:189], v[78:81]
	v_mfma_f32_16x16x32_bf16 v[126:129], v[134:137], v[166:169], v[126:129]
	v_mfma_f32_16x16x32_bf16 v[122:125], v[142:145], v[166:169], v[122:125]
	v_mfma_f32_16x16x32_bf16 v[106:109], v[142:145], v[174:177], v[106:109]
	v_mfma_f32_16x16x32_bf16 v[110:113], v[134:137], v[174:177], v[110:113]
	v_mfma_f32_16x16x32_bf16 v[94:97], v[134:137], v[182:185], v[94:97]
	v_mfma_f32_16x16x32_bf16 v[90:93], v[142:145], v[182:185], v[90:93]
	v_mfma_f32_16x16x32_bf16 v[74:77], v[142:145], v[190:193], v[74:77]
	v_mfma_f32_16x16x32_bf16 v[78:81], v[134:137], v[190:193], v[78:81]
	v_mfma_f32_16x16x32_bf16 v[118:121], v[146:149], v[162:165], v[118:121]
	v_mfma_f32_16x16x32_bf16 v[114:117], v[154:157], v[162:165], v[114:117]
	v_mfma_f32_16x16x32_bf16 v[98:101], v[154:157], v[170:173], v[98:101]
	v_mfma_f32_16x16x32_bf16 v[102:105], v[146:149], v[170:173], v[102:105]
	v_mfma_f32_16x16x32_bf16 v[86:89], v[146:149], v[178:181], v[86:89]
	v_mfma_f32_16x16x32_bf16 v[82:85], v[154:157], v[178:181], v[82:85]
	v_mfma_f32_16x16x32_bf16 v[66:69], v[154:157], v[186:189], v[66:69]
	v_mfma_f32_16x16x32_bf16 v[70:73], v[146:149], v[186:189], v[70:73]
	v_mfma_f32_16x16x32_bf16 v[118:121], v[150:153], v[166:169], v[118:121]
	v_mfma_f32_16x16x32_bf16 v[114:117], v[158:161], v[166:169], v[114:117]
	v_mfma_f32_16x16x32_bf16 v[98:101], v[158:161], v[174:177], v[98:101]
	v_mfma_f32_16x16x32_bf16 v[102:105], v[150:153], v[174:177], v[102:105]
	v_mfma_f32_16x16x32_bf16 v[86:89], v[150:153], v[182:185], v[86:89]
	v_mfma_f32_16x16x32_bf16 v[82:85], v[158:161], v[182:185], v[82:85]
	v_mfma_f32_16x16x32_bf16 v[66:69], v[158:161], v[190:193], v[66:69]
	v_mfma_f32_16x16x32_bf16 v[70:73], v[150:153], v[190:193], v[70:73]
	s_barrier
; #define PG8_STAGE(bufoff, gbase, voff) do { const int so_ = (int)(unsigned)((const char*)(gbase) - base_##voff); _Pragma("unroll") for (int _i = 0; _i < 2; ++_i) \
;         __builtin_amdgcn_raw_ptr_buffer_load_lds(rs_##voff, (PG8_LAS unsigned*)(lds + (bufoff) + ldsw + _i * 8192), 16, (int)(voff)[_i], so_, 0, 0); } while (0)
; #define PG8_LDA(dst, b, h) do { _Pragma("unroll") for (int m = 0; m < 4; ++m) _Pragma("unroll") for (int k = 0; k < 2; ++k) dst[m][k] = *(const PG8_LAS bf16x8*)(lds + PG8_SA(b, h) + aoff + m * 2048 + k * 1024); } while (0)
; #define PG8_LDB(dst, b, h) do { _Pragma("unroll") for (int n = 0; n < 2; ++n) _Pragma("unroll") for (int k = 0; k < 2; ++k) dst[n][k] = *(const PG8_LAS bf16x8*)(lds + PG8_SB(b, h) + boff + n * 2048 + k * 1024); } while (0)
; #define PG8_MMA(ai, bj, At, Bt) do { __builtin_amdgcn_s_setprio(1); _Pragma("unroll") for (int m = 0; m < 4; ++m) _Pragma("unroll") for (int n = 0; n < 2; ++n) _Pragma("unroll") for (int k = 0; k < 2; ++k) \
;         acc[ai][bj][m][n] = __builtin_amdgcn_mfma_f32_16x16x32_bf16(Bt[n][k], At[m][k], acc[ai][bj][m][n], 0, 0, 0); __builtin_amdgcn_s_setprio(0); } while (0)
; template <class Epi, class Sched, bool ALIGN_EPI = false, bool SP2 = false>
; __device__ __forceinline__ void gemm_phase(PG8_LAS unsigned char* lds, const Gemm g, const Sched& S, const Epi& E, int tid_in) {
;     ...
;             PG8_LDB(B0, 0, 0); PG8_LDB(B1, 0, 1); PG8_SCHED; PG8_LDA(At, 0, 0); PG8_STAGE(PG8_SA(1, 1), a1 + hstepA, voffA);
;             PG8_WAIT_V(8); PG8_WAIT_L(0); PG8_BAR; PG8_MMA(0, 0, At, B0); PG8_MMA(0, 1, At, B1); PG8_BAR; PG8_SCHED;
;             PG8_LDA(At, 0, 1); PG8_STAGE(PG8_SB(0, 0), b2, voffB); PG8_STAGE(PG8_SB(0, 1), b2 + hstepB, voffB); PG8_STAGE(PG8_SA(0, 0), a2, voffA);
;             PG8_WAIT_V(8); PG8_WAIT_L(0); PG8_BAR; PG8_MMA(1, 0, At, B0); PG8_MMA(1, 1, At, B1); PG8_BAR; PG8_SCHED;
;             PG8_LDB(B0, 1, 0); PG8_LDB(B1, 1, 1); PG8_SCHED; PG8_LDA(At, 1, 0); PG8_STAGE(PG8_SA(0, 1), a2 + hstepA, voffA);
;             PG8_WAIT_V(8); PG8_WAIT_L(0); PG8_BAR; PG8_MMA(0, 0, At, B0); PG8_MMA(0, 1, At, B1); PG8_BAR; PG8_SCHED;
;             PG8_LDA(At, 1, 1); PG8_STAGE(PG8_SB(1, 0), b3, voffB); PG8_STAGE(PG8_SB(1, 1), b3 + hstepB, voffB); PG8_STAGE(PG8_SA(1, 0), a3, voffA);
;             PG8_WAIT_V(8); PG8_WAIT_L(0); PG8_BAR; PG8_MMA(1, 0, At, B0); PG8_MMA(1, 1, At, B1); PG8_BAR; PG8_SCHED;
	s_setprio 0
	s_mov_b32 m0, s75
	s_add_i32 s36, s12, 0x80
	ds_read_b128 v[162:165], v238 offset:49152
	ds_read_b128 v[166:169], v238 offset:50176
	ds_read_b128 v[170:173], v238 offset:51200
	ds_read_b128 v[174:177], v238 offset:52224
	ds_read_b128 v[178:181], v238 offset:53248
	ds_read_b128 v[182:185], v238 offset:54272
	ds_read_b128 v[186:189], v238 offset:55296
	ds_read_b128 v[190:193], v238 offset:56320
	buffer_load_dwordx4 v207, s[40:43], s36 offen lds
	s_mov_b32 m0, s76
	s_add_i32 s12, s12, 0x80080
	buffer_load_dwordx4 v224, s[40:43], s36 offen lds
	s_mov_b32 m0, s79
	s_addk_i32 s13, 0x80
	buffer_load_dwordx4 v207, s[40:43], s12 offen lds
	s_mov_b32 m0, s68
	s_nop 0
	buffer_load_dwordx4 v224, s[40:43], s12 offen lds
	s_mov_b32 m0, s77
	s_nop 0
	buffer_load_dwordx4 v195, s[4:7], s13 offen lds
	s_waitcnt vmcnt(7) lgkmcnt(0)
	s_setprio 1
	s_barrier
	v_mfma_f32_16x16x32_bf16 v[62:65], v[130:133], v[162:165], v[62:65]
	v_mfma_f32_16x16x32_bf16 v[58:61], v[138:141], v[162:165], v[58:61]
	v_mfma_f32_16x16x32_bf16 v[42:45], v[138:141], v[170:173], v[42:45]
	v_mfma_f32_16x16x32_bf16 v[46:49], v[130:133], v[170:173], v[46:49]
	v_mfma_f32_16x16x32_bf16 v[30:33], v[130:133], v[178:181], v[30:33]
	v_mfma_f32_16x16x32_bf16 v[26:29], v[138:141], v[178:181], v[26:29]
	v_mfma_f32_16x16x32_bf16 v[10:13], v[138:141], v[186:189], v[10:13]
	v_mfma_f32_16x16x32_bf16 v[14:17], v[130:133], v[186:189], v[14:17]
	v_mfma_f32_16x16x32_bf16 v[62:65], v[134:137], v[166:169], v[62:65]
	v_mfma_f32_16x16x32_bf16 v[58:61], v[142:145], v[166:169], v[58:61]
	v_mfma_f32_16x16x32_bf16 v[42:45], v[142:145], v[174:177], v[42:45]
	v_mfma_f32_16x16x32_bf16 v[46:49], v[134:137], v[174:177], v[46:49]
	v_mfma_f32_16x16x32_bf16 v[30:33], v[134:137], v[182:185], v[30:33]
	v_mfma_f32_16x16x32_bf16 v[26:29], v[142:145], v[182:185], v[26:29]
	v_mfma_f32_16x16x32_bf16 v[10:13], v[142:145], v[190:193], v[10:13]
	v_mfma_f32_16x16x32_bf16 v[14:17], v[134:137], v[190:193], v[14:17]
	v_mfma_f32_16x16x32_bf16 v[54:57], v[146:149], v[162:165], v[54:57]
	v_mfma_f32_16x16x32_bf16 v[50:53], v[154:157], v[162:165], v[50:53]
	v_mfma_f32_16x16x32_bf16 v[34:37], v[154:157], v[170:173], v[34:37]
	v_mfma_f32_16x16x32_bf16 v[38:41], v[146:149], v[170:173], v[38:41]
	v_mfma_f32_16x16x32_bf16 v[22:25], v[146:149], v[178:181], v[22:25]
	v_mfma_f32_16x16x32_bf16 v[18:21], v[154:157], v[178:181], v[18:21]
	v_mfma_f32_16x16x32_bf16 v[2:5], v[154:157], v[186:189], v[2:5]
	v_mfma_f32_16x16x32_bf16 v[6:9], v[146:149], v[186:189], v[6:9]
	v_mfma_f32_16x16x32_bf16 v[54:57], v[150:153], v[166:169], v[54:57]
	v_mfma_f32_16x16x32_bf16 v[50:53], v[158:161], v[166:169], v[50:53]
	v_mfma_f32_16x16x32_bf16 v[34:37], v[158:161], v[174:177], v[34:37]
	v_mfma_f32_16x16x32_bf16 v[38:41], v[150:153], v[174:177], v[38:41]
	v_mfma_f32_16x16x32_bf16 v[22:25], v[150:153], v[182:185], v[22:25]
	v_mfma_f32_16x16x32_bf16 v[18:21], v[158:161], v[182:185], v[18:21]
	v_mfma_f32_16x16x32_bf16 v[2:5], v[158:161], v[190:193], v[2:5]
	v_mfma_f32_16x16x32_bf16 v[6:9], v[150:153], v[190:193], v[6:9]
	s_barrier
	s_setprio 0
	s_add_i32 s23, s23, 2
	s_add_u32 s20, s20, 0x100
	s_addc_u32 s21, s21, 0
	s_cmp_gt_u32 s23, 29
	s_mov_b64 s[12:13], s[16:17]
.LBB0_312:
	v_add_u32_e32 v0, 0x10000, v237
	ds_read_b128 v[130:133], v0
	ds_read_b128 v[134:137], v0 offset:1024
	ds_read_b128 v[138:141], v0 offset:2048
	ds_read_b128 v[142:145], v0 offset:3072
	v_add_u32_e32 v0, 0x14000, v237
	ds_read_b128 v[146:149], v0
	ds_read_b128 v[150:153], v0 offset:1024
	ds_read_b128 v[154:157], v0 offset:2048
	ds_read_b128 v[158:161], v0 offset:3072
	s_add_u32 s16, s12, 0x100
	s_addc_u32 s17, s13, 0
	s_sub_i32 s12, s12, s4
	s_add_i32 s12, s12, 0x80080
	s_sub_i32 s36, s12, 0x80000
	s_cmp_eq_u32 s23, 28
	s_cselect_b32 s13, s19, s16
	s_mov_b32 m0, s69
	ds_read_b128 v[162:165], v238
	ds_read_b128 v[166:169], v238 offset:1024
	ds_read_b128 v[170:173], v238 offset:2048
	ds_read_b128 v[174:177], v238 offset:3072
	ds_read_b128 v[178:181], v238 offset:4096
	ds_read_b128 v[182:185], v238 offset:5120
	ds_read_b128 v[186:189], v238 offset:6144
	ds_read_b128 v[190:193], v238 offset:7168
	s_mov_b32 m0, s78
	s_nop 0
	buffer_load_dwordx4 v211, s[4:7], s36 offen lds
	s_mov_b32 m0, s69
	s_nop 0
	buffer_load_dwordx4 v195, s[4:7], s12 offen lds
	s_mov_b32 m0, s67
	s_nop 0
	buffer_load_dwordx4 v211, s[4:7], s12 offen lds
	s_waitcnt vmcnt(8) lgkmcnt(0)
	s_setprio 1
	s_barrier
	v_mfma_f32_16x16x32_bf16 v[126:129], v[130:133], v[162:165], v[126:129]
	v_mfma_f32_16x16x32_bf16 v[122:125], v[138:141], v[162:165], v[122:125]
	v_mfma_f32_16x16x32_bf16 v[106:109], v[138:141], v[170:173], v[106:109]
	v_mfma_f32_16x16x32_bf16 v[110:113], v[130:133], v[170:173], v[110:113]
	v_mfma_f32_16x16x32_bf16 v[94:97], v[130:133], v[178:181], v[94:97]
	v_mfma_f32_16x16x32_bf16 v[90:93], v[138:141], v[178:181], v[90:93]
	v_mfma_f32_16x16x32_bf16 v[74:77], v[138:141], v[186:189], v[74:77]
	v_mfma_f32_16x16x32_bf16 v[78:81], v[130:133], v[186:189], v[78:81]
	v_mfma_f32_16x16x32_bf16 v[126:129], v[134:137], v[166:169], v[126:129]
	v_mfma_f32_16x16x32_bf16 v[122:125], v[142:145], v[166:169], v[122:125]
	v_mfma_f32_16x16x32_bf16 v[106:109], v[142:145], v[174:177], v[106:109]
	v_mfma_f32_16x16x32_bf16 v[110:113], v[134:137], v[174:177], v[110:113]
	v_mfma_f32_16x16x32_bf16 v[94:97], v[134:137], v[182:185], v[94:97]
	v_mfma_f32_16x16x32_bf16 v[90:93], v[142:145], v[182:185], v[90:93]
	v_mfma_f32_16x16x32_bf16 v[74:77], v[142:145], v[190:193], v[74:77]
	v_mfma_f32_16x16x32_bf16 v[78:81], v[134:137], v[190:193], v[78:81]
	v_mfma_f32_16x16x32_bf16 v[118:121], v[146:149], v[162:165], v[118:121]
	v_mfma_f32_16x16x32_bf16 v[114:117], v[154:157], v[162:165], v[114:117]
	v_mfma_f32_16x16x32_bf16 v[98:101], v[154:157], v[170:173], v[98:101]
	v_mfma_f32_16x16x32_bf16 v[102:105], v[146:149], v[170:173], v[102:105]
	v_mfma_f32_16x16x32_bf16 v[86:89], v[146:149], v[178:181], v[86:89]
	v_mfma_f32_16x16x32_bf16 v[82:85], v[154:157], v[178:181], v[82:85]
	v_mfma_f32_16x16x32_bf16 v[66:69], v[154:157], v[186:189], v[66:69]
	v_mfma_f32_16x16x32_bf16 v[70:73], v[146:149], v[186:189], v[70:73]
	v_mfma_f32_16x16x32_bf16 v[118:121], v[150:153], v[166:169], v[118:121]
	v_mfma_f32_16x16x32_bf16 v[114:117], v[158:161], v[166:169], v[114:117]
	v_mfma_f32_16x16x32_bf16 v[98:101], v[158:161], v[174:177], v[98:101]
	v_mfma_f32_16x16x32_bf16 v[102:105], v[150:153], v[174:177], v[102:105]
	v_mfma_f32_16x16x32_bf16 v[86:89], v[150:153], v[182:185], v[86:89]
	v_mfma_f32_16x16x32_bf16 v[82:85], v[158:161], v[182:185], v[82:85]
	v_mfma_f32_16x16x32_bf16 v[66:69], v[158:161], v[190:193], v[66:69]
	v_mfma_f32_16x16x32_bf16 v[70:73], v[150:153], v[190:193], v[70:73]
	s_barrier
; #define PG8_STAGE(bufoff, gbase, voff) do { const int so_ = (int)(unsigned)((const char*)(gbase) - base_##voff); _Pragma("unroll") for (int _i = 0; _i < 2; ++_i) \
;         __builtin_amdgcn_raw_ptr_buffer_load_lds(rs_##voff, (PG8_LAS unsigned*)(lds + (bufoff) + ldsw + _i * 8192), 16, (int)(voff)[_i], so_, 0, 0); } while (0)
; #define PG8_LDA(dst, b, h) do { _Pragma("unroll") for (int m = 0; m < 4; ++m) _Pragma("unroll") for (int k = 0; k < 2; ++k) dst[m][k] = *(const PG8_LAS bf16x8*)(lds + PG8_SA(b, h) + aoff + m * 2048 + k * 1024); } while (0)
; #define PG8_LDB(dst, b, h) do { _Pragma("unroll") for (int n = 0; n < 2; ++n) _Pragma("unroll") for (int k = 0; k < 2; ++k) dst[n][k] = *(const PG8_LAS bf16x8*)(lds + PG8_SB(b, h) + boff + n * 2048 + k * 1024); } while (0)
; #define PG8_MMA(ai, bj, At, Bt) do { __builtin_amdgcn_s_setprio(1); _Pragma("unroll") for (int m = 0; m < 4; ++m) _Pragma("unroll") for (int n = 0; n < 2; ++n) _Pragma("unroll") for (int k = 0; k < 2; ++k) \
;         acc[ai][bj][m][n] = __builtin_amdgcn_mfma_f32_16x16x32_bf16(Bt[n][k], At[m][k], acc[ai][bj][m][n], 0, 0, 0); __builtin_amdgcn_s_setprio(0); } while (0)
; #define PG8_WAIT_V(n) asm volatile("s_waitcnt vmcnt(" #n ")" ::: "memory")
; #define PG8_WAIT_L(n) asm volatile("s_waitcnt lgkmcnt(" #n ")" ::: "memory")
; #define PG8_BAR __builtin_amdgcn_s_barrier()
; #define PG8_SCHED __builtin_amdgcn_sched_barrier(0)
; template <class Epi, class Sched, bool ALIGN_EPI = false, bool SP2 = false>
; __device__ __forceinline__ void gemm_phase(PG8_LAS unsigned char* lds, const Gemm g, const Sched& S, const Epi& E, int tid_in) {
;     ...
;             PG8_LDA(At, 0, 1); PG8_STAGE(PG8_SB(0, 0), b2, voffB); PG8_STAGE(PG8_SB(0, 1), b2 + hstepB, voffB); PG8_STAGE(PG8_SA(0, 0), a2, voffA);
;             PG8_WAIT_V(8); PG8_WAIT_L(0); PG8_BAR; PG8_MMA(1, 0, At, B0); PG8_MMA(1, 1, At, B1); PG8_BAR; PG8_SCHED;
;             PG8_LDB(B0, 1, 0); PG8_LDB(B1, 1, 1); PG8_SCHED; PG8_LDA(At, 1, 0); PG8_STAGE(PG8_SA(0, 1), a2 + hstepA, voffA);
;             PG8_WAIT_V(8); PG8_WAIT_L(0); PG8_BAR; PG8_MMA(0, 0, At, B0); PG8_MMA(0, 1, At, B1); PG8_BAR; PG8_SCHED;
	s_setprio 0
	s_cselect_b32 s12, s15, s20
	s_mov_b32 m0, s61
	s_mov_b32 s42, s6
	s_mov_b32 s43, s7
	s_sub_i32 s12, s12, s40
	ds_read_b128 v[162:165], v238 offset:16384
	ds_read_b128 v[166:169], v238 offset:17408
	ds_read_b128 v[170:173], v238 offset:18432
	ds_read_b128 v[174:177], v238 offset:19456
	ds_read_b128 v[178:181], v238 offset:20480
	ds_read_b128 v[182:185], v238 offset:21504
	ds_read_b128 v[186:189], v238 offset:22528
	ds_read_b128 v[190:193], v238 offset:23552
	buffer_load_dwordx4 v207, s[40:43], s12 offen lds
	s_mov_b32 m0, s62
	s_add_i32 s36, s12, 0x80000
	buffer_load_dwordx4 v224, s[40:43], s12 offen lds
	s_mov_b32 m0, s63
	s_sub_i32 s13, s13, s4
	buffer_load_dwordx4 v207, s[40:43], s36 offen lds
	s_mov_b32 m0, s71
	s_nop 0
	buffer_load_dwordx4 v224, s[40:43], s36 offen lds
	s_mov_b32 m0, s53
	s_nop 0
	buffer_load_dwordx4 v195, s[4:7], s13 offen lds
	s_waitcnt vmcnt(7) lgkmcnt(0)
	s_setprio 1
	s_barrier
	v_mfma_f32_16x16x32_bf16 v[62:65], v[130:133], v[162:165], v[62:65]
	v_mfma_f32_16x16x32_bf16 v[58:61], v[138:141], v[162:165], v[58:61]
	v_mfma_f32_16x16x32_bf16 v[42:45], v[138:141], v[170:173], v[42:45]
	v_mfma_f32_16x16x32_bf16 v[46:49], v[130:133], v[170:173], v[46:49]
	v_mfma_f32_16x16x32_bf16 v[30:33], v[130:133], v[178:181], v[30:33]
	v_mfma_f32_16x16x32_bf16 v[26:29], v[138:141], v[178:181], v[26:29]
	v_mfma_f32_16x16x32_bf16 v[10:13], v[138:141], v[186:189], v[10:13]
	v_mfma_f32_16x16x32_bf16 v[14:17], v[130:133], v[186:189], v[14:17]
	v_mfma_f32_16x16x32_bf16 v[62:65], v[134:137], v[166:169], v[62:65]
	v_mfma_f32_16x16x32_bf16 v[58:61], v[142:145], v[166:169], v[58:61]
	v_mfma_f32_16x16x32_bf16 v[42:45], v[142:145], v[174:177], v[42:45]
	v_mfma_f32_16x16x32_bf16 v[46:49], v[134:137], v[174:177], v[46:49]
	v_mfma_f32_16x16x32_bf16 v[30:33], v[134:137], v[182:185], v[30:33]
	v_mfma_f32_16x16x32_bf16 v[26:29], v[142:145], v[182:185], v[26:29]
	v_mfma_f32_16x16x32_bf16 v[10:13], v[142:145], v[190:193], v[10:13]
	v_mfma_f32_16x16x32_bf16 v[14:17], v[134:137], v[190:193], v[14:17]
	v_mfma_f32_16x16x32_bf16 v[54:57], v[146:149], v[162:165], v[54:57]
	v_mfma_f32_16x16x32_bf16 v[50:53], v[154:157], v[162:165], v[50:53]
	v_mfma_f32_16x16x32_bf16 v[34:37], v[154:157], v[170:173], v[34:37]
	v_mfma_f32_16x16x32_bf16 v[38:41], v[146:149], v[170:173], v[38:41]
	v_mfma_f32_16x16x32_bf16 v[22:25], v[146:149], v[178:181], v[22:25]
	v_mfma_f32_16x16x32_bf16 v[18:21], v[154:157], v[178:181], v[18:21]
	v_mfma_f32_16x16x32_bf16 v[2:5], v[154:157], v[186:189], v[2:5]
	v_mfma_f32_16x16x32_bf16 v[6:9], v[146:149], v[186:189], v[6:9]
	v_mfma_f32_16x16x32_bf16 v[54:57], v[150:153], v[166:169], v[54:57]
	v_mfma_f32_16x16x32_bf16 v[50:53], v[158:161], v[166:169], v[50:53]
	v_mfma_f32_16x16x32_bf16 v[34:37], v[158:161], v[174:177], v[34:37]
	v_mfma_f32_16x16x32_bf16 v[38:41], v[150:153], v[174:177], v[38:41]
	v_mfma_f32_16x16x32_bf16 v[22:25], v[150:153], v[182:185], v[22:25]
	v_mfma_f32_16x16x32_bf16 v[18:21], v[158:161], v[182:185], v[18:21]
	v_mfma_f32_16x16x32_bf16 v[2:5], v[158:161], v[190:193], v[2:5]
	v_mfma_f32_16x16x32_bf16 v[6:9], v[150:153], v[190:193], v[6:9]
	s_barrier
	s_setprio 0
	v_add_u32_e32 v0, 0x18000, v237
	ds_read_b128 v[130:133], v0
	ds_read_b128 v[134:137], v0 offset:1024
	ds_read_b128 v[138:141], v0 offset:2048
	ds_read_b128 v[142:145], v0 offset:3072
	v_add_u32_e32 v0, 0x1c000, v237
	ds_read_b128 v[146:149], v0
	ds_read_b128 v[150:153], v0 offset:1024
	ds_read_b128 v[154:157], v0 offset:2048
	ds_read_b128 v[158:161], v0 offset:3072
	s_add_i32 s36, s13, 0x80000
	s_mov_b32 m0, s73
	ds_read_b128 v[162:165], v238 offset:32768
	ds_read_b128 v[166:169], v238 offset:33792
	ds_read_b128 v[170:173], v238 offset:34816
	ds_read_b128 v[174:177], v238 offset:35840
	ds_read_b128 v[178:181], v238 offset:36864
	ds_read_b128 v[182:185], v238 offset:37888
	ds_read_b128 v[186:189], v238 offset:38912
	ds_read_b128 v[190:193], v238 offset:39936
	s_mov_b32 m0, s72
	s_nop 0
	buffer_load_dwordx4 v211, s[4:7], s13 offen lds
	s_mov_b32 m0, s73
	s_nop 0
	buffer_load_dwordx4 v195, s[4:7], s36 offen lds
	s_mov_b32 m0, s74
	s_nop 0
	buffer_load_dwordx4 v211, s[4:7], s36 offen lds
	s_waitcnt vmcnt(8) lgkmcnt(0)
	s_setprio 1
	s_barrier
; #define PG8_STAGE(bufoff, gbase, voff) do { const int so_ = (int)(unsigned)((const char*)(gbase) - base_##voff); _Pragma("unroll") for (int _i = 0; _i < 2; ++_i) \
;         __builtin_amdgcn_raw_ptr_buffer_load_lds(rs_##voff, (PG8_LAS unsigned*)(lds + (bufoff) + ldsw + _i * 8192), 16, (int)(voff)[_i], so_, 0, 0); } while (0)
; #define PG8_WAIT_V(n) asm volatile("s_waitcnt vmcnt(" #n ")" ::: "memory")
; template <class Epi, class Sched, bool ALIGN_EPI = false, bool SP2 = false>
; __device__ __forceinline__ void gemm_phase(PG8_LAS unsigned char* lds, const Gemm g, const Sched& S, const Epi& E, int tid_in) {
;     ...
;             PG8_WAIT_V(8); PG8_WAIT_L(0); PG8_BAR; PG8_MMA(0, 0, At, B0); PG8_MMA(0, 1, At, B1); PG8_BAR; PG8_SCHED;
;             PG8_LDA(At, 1, 1); PG8_STAGE(PG8_SB(1, 0), b3, voffB); PG8_STAGE(PG8_SB(1, 1), b3 + hstepB, voffB); PG8_STAGE(PG8_SA(1, 0), a3, voffA);
;             PG8_WAIT_V(8); PG8_WAIT_L(0); PG8_BAR; PG8_MMA(1, 0, At, B0); PG8_MMA(1, 1, At, B1); PG8_BAR; PG8_SCHED;
;             } else {
;             PG8_LDB(B0, 0, 0); PG8_SCHED; PG8_LDA(At, 0, 0); PG8_STAGE(PG8_SA(1, 1), a1 + hstepA, voffA);
;             PG8_WAIT_L(8); PG8_BAR; PG8_WAIT_L(0); PG8_MMA(0, 0, At, B0); PG8_BAR; PG8_SCHED;
;             PG8_LDB(B1, 0, 1); PG8_STAGE(PG8_SB(0, 0), b2, voffB);
;             PG8_BAR; PG8_WAIT_L(0); PG8_MMA(0, 1, At, B1); PG8_BAR;
;             PG8_LDA(At, 0, 1); PG8_STAGE(PG8_SA(0, 0), a2, voffA);
;             PG8_BAR; PG8_WAIT_L(0); PG8_MMA(1, 0, At, B0); PG8_BAR; PG8_SCHED;
;             PG8_STAGE(PG8_SB(0, 1), b2 + hstepB, voffB);
;             PG8_WAIT_V(6); PG8_BAR; PG8_MMA(1, 1, At, B1); PG8_BAR;
;             PG8_LDB(B0, 1, 0); PG8_SCHED; PG8_LDA(At, 1, 0); PG8_STAGE(PG8_SA(0, 1), a2 + hstepA, voffA);
;             PG8_WAIT_L(8); PG8_BAR; PG8_WAIT_L(0); PG8_MMA(0, 0, At, B0); PG8_BAR; PG8_SCHED;
;             PG8_LDB(B1, 1, 1); PG8_STAGE(PG8_SB(1, 0), b3, voffB);
;             PG8_BAR; PG8_WAIT_L(0); PG8_MMA(0, 1, At, B1); PG8_BAR;
;             PG8_LDA(At, 1, 1); PG8_STAGE(PG8_SA(1, 0), a3, voffA);
;             PG8_BAR; PG8_WAIT_L(0); PG8_MMA(1, 0, At, B0); PG8_BAR; PG8_SCHED;
;             PG8_STAGE(PG8_SB(1, 1), b3 + hstepB, voffB);
;             PG8_WAIT_V(6); PG8_BAR; PG8_MMA(1, 1, At, B1); PG8_BAR;
;             }
;         }
;         if constexpr (ALIGN_EPI) { if (wr == 0) PG8_BAR; }
	v_mfma_f32_16x16x32_bf16 v[126:129], v[130:133], v[162:165], v[126:129]
	v_mfma_f32_16x16x32_bf16 v[122:125], v[138:141], v[162:165], v[122:125]
	v_mfma_f32_16x16x32_bf16 v[106:109], v[138:141], v[170:173], v[106:109]
	v_mfma_f32_16x16x32_bf16 v[110:113], v[130:133], v[170:173], v[110:113]
	v_mfma_f32_16x16x32_bf16 v[94:97], v[130:133], v[178:181], v[94:97]
	v_mfma_f32_16x16x32_bf16 v[90:93], v[138:141], v[178:181], v[90:93]
	v_mfma_f32_16x16x32_bf16 v[74:77], v[138:141], v[186:189], v[74:77]
	v_mfma_f32_16x16x32_bf16 v[78:81], v[130:133], v[186:189], v[78:81]
	v_mfma_f32_16x16x32_bf16 v[126:129], v[134:137], v[166:169], v[126:129]
	v_mfma_f32_16x16x32_bf16 v[122:125], v[142:145], v[166:169], v[122:125]
	v_mfma_f32_16x16x32_bf16 v[106:109], v[142:145], v[174:177], v[106:109]
	v_mfma_f32_16x16x32_bf16 v[110:113], v[134:137], v[174:177], v[110:113]
	v_mfma_f32_16x16x32_bf16 v[94:97], v[134:137], v[182:185], v[94:97]
	v_mfma_f32_16x16x32_bf16 v[90:93], v[142:145], v[182:185], v[90:93]
	v_mfma_f32_16x16x32_bf16 v[74:77], v[142:145], v[190:193], v[74:77]
	v_mfma_f32_16x16x32_bf16 v[78:81], v[134:137], v[190:193], v[78:81]
	v_mfma_f32_16x16x32_bf16 v[118:121], v[146:149], v[162:165], v[118:121]
	v_mfma_f32_16x16x32_bf16 v[114:117], v[154:157], v[162:165], v[114:117]
	v_mfma_f32_16x16x32_bf16 v[98:101], v[154:157], v[170:173], v[98:101]
	v_mfma_f32_16x16x32_bf16 v[102:105], v[146:149], v[170:173], v[102:105]
	v_mfma_f32_16x16x32_bf16 v[86:89], v[146:149], v[178:181], v[86:89]
	v_mfma_f32_16x16x32_bf16 v[82:85], v[154:157], v[178:181], v[82:85]
	v_mfma_f32_16x16x32_bf16 v[66:69], v[154:157], v[186:189], v[66:69]
	v_mfma_f32_16x16x32_bf16 v[70:73], v[146:149], v[186:189], v[70:73]
	v_mfma_f32_16x16x32_bf16 v[118:121], v[150:153], v[166:169], v[118:121]
	v_mfma_f32_16x16x32_bf16 v[114:117], v[158:161], v[166:169], v[114:117]
	v_mfma_f32_16x16x32_bf16 v[98:101], v[158:161], v[174:177], v[98:101]
	v_mfma_f32_16x16x32_bf16 v[102:105], v[150:153], v[174:177], v[102:105]
	v_mfma_f32_16x16x32_bf16 v[86:89], v[150:153], v[182:185], v[86:89]
	v_mfma_f32_16x16x32_bf16 v[82:85], v[158:161], v[182:185], v[82:85]
	v_mfma_f32_16x16x32_bf16 v[66:69], v[158:161], v[190:193], v[66:69]
	v_mfma_f32_16x16x32_bf16 v[70:73], v[150:153], v[190:193], v[70:73]
	s_barrier
	s_setprio 0
	s_mov_b32 m0, s75
	s_add_i32 s36, s12, 0x80
	ds_read_b128 v[162:165], v238 offset:49152
	ds_read_b128 v[166:169], v238 offset:50176
	ds_read_b128 v[170:173], v238 offset:51200
	ds_read_b128 v[174:177], v238 offset:52224
	ds_read_b128 v[178:181], v238 offset:53248
	ds_read_b128 v[182:185], v238 offset:54272
	ds_read_b128 v[186:189], v238 offset:55296
	ds_read_b128 v[190:193], v238 offset:56320
	buffer_load_dwordx4 v207, s[40:43], s36 offen lds
	s_mov_b32 m0, s76
	s_add_i32 s12, s12, 0x80080
	buffer_load_dwordx4 v224, s[40:43], s36 offen lds
	s_mov_b32 m0, s79
	s_addk_i32 s13, 0x80
	buffer_load_dwordx4 v207, s[40:43], s12 offen lds
	s_mov_b32 m0, s68
	s_nop 0
	buffer_load_dwordx4 v224, s[40:43], s12 offen lds
	s_mov_b32 m0, s77
	s_nop 0
	buffer_load_dwordx4 v195, s[4:7], s13 offen lds
	s_waitcnt vmcnt(7) lgkmcnt(0)
	s_setprio 1
	s_barrier
	v_mfma_f32_16x16x32_bf16 v[62:65], v[130:133], v[162:165], v[62:65]
	v_mfma_f32_16x16x32_bf16 v[58:61], v[138:141], v[162:165], v[58:61]
	v_mfma_f32_16x16x32_bf16 v[42:45], v[138:141], v[170:173], v[42:45]
	v_mfma_f32_16x16x32_bf16 v[46:49], v[130:133], v[170:173], v[46:49]
	v_mfma_f32_16x16x32_bf16 v[30:33], v[130:133], v[178:181], v[30:33]
	v_mfma_f32_16x16x32_bf16 v[26:29], v[138:141], v[178:181], v[26:29]
	v_mfma_f32_16x16x32_bf16 v[10:13], v[138:141], v[186:189], v[10:13]
	v_mfma_f32_16x16x32_bf16 v[14:17], v[130:133], v[186:189], v[14:17]
	v_mfma_f32_16x16x32_bf16 v[62:65], v[134:137], v[166:169], v[62:65]
	v_mfma_f32_16x16x32_bf16 v[58:61], v[142:145], v[166:169], v[58:61]
	v_mfma_f32_16x16x32_bf16 v[42:45], v[142:145], v[174:177], v[42:45]
	v_mfma_f32_16x16x32_bf16 v[46:49], v[134:137], v[174:177], v[46:49]
	v_mfma_f32_16x16x32_bf16 v[30:33], v[134:137], v[182:185], v[30:33]
	v_mfma_f32_16x16x32_bf16 v[26:29], v[142:145], v[182:185], v[26:29]
	v_mfma_f32_16x16x32_bf16 v[10:13], v[142:145], v[190:193], v[10:13]
	v_mfma_f32_16x16x32_bf16 v[14:17], v[134:137], v[190:193], v[14:17]
	v_mfma_f32_16x16x32_bf16 v[54:57], v[146:149], v[162:165], v[54:57]
	v_mfma_f32_16x16x32_bf16 v[50:53], v[154:157], v[162:165], v[50:53]
	v_mfma_f32_16x16x32_bf16 v[34:37], v[154:157], v[170:173], v[34:37]
	v_mfma_f32_16x16x32_bf16 v[38:41], v[146:149], v[170:173], v[38:41]
	v_mfma_f32_16x16x32_bf16 v[22:25], v[146:149], v[178:181], v[22:25]
	v_mfma_f32_16x16x32_bf16 v[18:21], v[154:157], v[178:181], v[18:21]
	v_mfma_f32_16x16x32_bf16 v[2:5], v[154:157], v[186:189], v[2:5]
	v_mfma_f32_16x16x32_bf16 v[6:9], v[146:149], v[186:189], v[6:9]
	v_mfma_f32_16x16x32_bf16 v[54:57], v[150:153], v[166:169], v[54:57]
	v_mfma_f32_16x16x32_bf16 v[50:53], v[158:161], v[166:169], v[50:53]
	v_mfma_f32_16x16x32_bf16 v[34:37], v[158:161], v[174:177], v[34:37]
	v_mfma_f32_16x16x32_bf16 v[38:41], v[150:153], v[174:177], v[38:41]
	v_mfma_f32_16x16x32_bf16 v[22:25], v[150:153], v[182:185], v[22:25]
	v_mfma_f32_16x16x32_bf16 v[18:21], v[158:161], v[182:185], v[18:21]
	v_mfma_f32_16x16x32_bf16 v[2:5], v[158:161], v[190:193], v[2:5]
	v_mfma_f32_16x16x32_bf16 v[6:9], v[150:153], v[190:193], v[6:9]
	s_barrier
	s_setprio 0
	s_add_i32 s23, s23, 2
	s_add_u32 s20, s20, 0x100
	s_addc_u32 s21, s21, 0
	s_cmp_gt_u32 s23, 29
	s_mov_b64 s[12:13], s[16:17]
	s_cbranch_scc0 .LBB0_312
	s_and_b64 vcc, exec, s[48:49]
	s_cbranch_vccz .LBB0_315
	s_barrier

; #define PG8_STAGE(bufoff, gbase, voff) do { const int so_ = (int)(unsigned)((const char*)(gbase) - base_##voff); _Pragma("unroll") for (int _i = 0; _i < 2; ++_i) \
;         __builtin_amdgcn_raw_ptr_buffer_load_lds(rs_##voff, (PG8_LAS unsigned*)(lds + (bufoff) + ldsw + _i * 8192), 16, (int)(voff)[_i], so_, 0, 0); } while (0)
; #define PG8_LDA(dst, b, h) do { _Pragma("unroll") for (int m = 0; m < 4; ++m) _Pragma("unroll") for (int k = 0; k < 2; ++k) dst[m][k] = *(const PG8_LAS bf16x8*)(lds + PG8_SA(b, h) + aoff + m * 2048 + k * 1024); } while (0)
; #define PG8_LDB(dst, b, h) do { _Pragma("unroll") for (int n = 0; n < 2; ++n) _Pragma("unroll") for (int k = 0; k < 2; ++k) dst[n][k] = *(const PG8_LAS bf16x8*)(lds + PG8_SB(b, h) + boff + n * 2048 + k * 1024); } while (0)
; #define PG8_MMA(ai, bj, At, Bt) do { __builtin_amdgcn_s_setprio(1); _Pragma("unroll") for (int m = 0; m < 4; ++m) _Pragma("unroll") for (int n = 0; n < 2; ++n) _Pragma("unroll") for (int k = 0; k < 2; ++k) \
;         acc[ai][bj][m][n] = __builtin_amdgcn_mfma_f32_16x16x32_bf16(Bt[n][k], At[m][k], acc[ai][bj][m][n], 0, 0, 0); __builtin_amdgcn_s_setprio(0); } while (0)
; #define PG8_WAIT_V(n) asm volatile("s_waitcnt vmcnt(" #n ")" ::: "memory")
; #define PG8_WAIT_L(n) asm volatile("s_waitcnt lgkmcnt(" #n ")" ::: "memory")
; #define PG8_BAR __builtin_amdgcn_s_barrier()
; #define PG8_SCHED __builtin_amdgcn_sched_barrier(0)
; template <class Epi, class Sched, bool ALIGN_EPI = false, bool SP2 = false>
; __device__ __forceinline__ void gemm_phase(PG8_LAS unsigned char* lds, const Gemm g, const Sched& S, const Epi& E, int tid_in) {
;     ...
;             PG8_LDB(B0, 0, 0); PG8_LDB(B1, 0, 1); PG8_SCHED; PG8_LDA(At, 0, 0); PG8_STAGE(PG8_SA(1, 1), a1 + hstepA, voffA);
;             PG8_WAIT_V(8); PG8_WAIT_L(0); PG8_BAR; PG8_MMA(0, 0, At, B0); PG8_MMA(0, 1, At, B1); PG8_BAR; PG8_SCHED;
;             PG8_LDA(At, 0, 1); PG8_STAGE(PG8_SB(0, 0), b2, voffB); PG8_STAGE(PG8_SB(0, 1), b2 + hstepB, voffB); PG8_STAGE(PG8_SA(0, 0), a2, voffA);
;             PG8_WAIT_V(8); PG8_WAIT_L(0); PG8_BAR; PG8_MMA(1, 0, At, B0); PG8_MMA(1, 1, At, B1); PG8_BAR; PG8_SCHED;
.LBB0_1037:
	v_add_u32_e32 v0, 0x10000, v236
	ds_read_b128 v[132:135], v0
	ds_read_b128 v[136:139], v0 offset:1024
	ds_read_b128 v[140:143], v0 offset:2048
	ds_read_b128 v[144:147], v0 offset:3072
	v_add_u32_e32 v0, 0x14000, v236
	ds_read_b128 v[148:151], v0
	ds_read_b128 v[152:155], v0 offset:1024
	ds_read_b128 v[156:159], v0 offset:2048
	ds_read_b128 v[160:163], v0 offset:3072
	s_add_u32 s16, s12, 0x100
	s_addc_u32 s17, s13, 0
	s_sub_i32 s12, s12, s4
	s_add_i32 s12, s12, 0xc0080
	s_sub_i32 s39, s12, 0xc0000
	s_cmp_eq_u32 s38, 12
	s_cselect_b32 s13, s24, s16
	s_mov_b32 m0, s76
	ds_read_b128 v[164:167], v237
	ds_read_b128 v[168:171], v237 offset:1024
	ds_read_b128 v[172:175], v237 offset:2048
	ds_read_b128 v[176:179], v237 offset:3072
	ds_read_b128 v[180:183], v237 offset:4096
	ds_read_b128 v[184:187], v237 offset:5120
	ds_read_b128 v[188:191], v237 offset:6144
	ds_read_b128 v[192:195], v237 offset:7168
	s_mov_b32 m0, s73
	s_nop 0
	buffer_load_dwordx4 v222, s[4:7], s39 offen lds
	s_mov_b32 m0, s76
	s_nop 0
	buffer_load_dwordx4 v220, s[4:7], s12 offen lds
	s_mov_b32 m0, s77
	s_nop 0
	buffer_load_dwordx4 v222, s[4:7], s12 offen lds
	s_waitcnt vmcnt(8) lgkmcnt(0)
	s_setprio 1
	s_barrier
	v_mfma_f32_16x16x32_bf16 v[128:131], v[132:135], v[164:167], v[128:131]
	v_mfma_f32_16x16x32_bf16 v[124:127], v[140:143], v[164:167], v[124:127]
	v_mfma_f32_16x16x32_bf16 v[116:119], v[140:143], v[172:175], v[116:119]
	v_mfma_f32_16x16x32_bf16 v[120:123], v[132:135], v[172:175], v[120:123]
	v_mfma_f32_16x16x32_bf16 v[112:115], v[132:135], v[180:183], v[112:115]
	v_mfma_f32_16x16x32_bf16 v[108:111], v[140:143], v[180:183], v[108:111]
	v_mfma_f32_16x16x32_bf16 v[100:103], v[140:143], v[188:191], v[100:103]
	v_mfma_f32_16x16x32_bf16 v[104:107], v[132:135], v[188:191], v[104:107]
	v_mfma_f32_16x16x32_bf16 v[128:131], v[136:139], v[168:171], v[128:131]
	v_mfma_f32_16x16x32_bf16 v[124:127], v[144:147], v[168:171], v[124:127]
	v_mfma_f32_16x16x32_bf16 v[116:119], v[144:147], v[176:179], v[116:119]
	v_mfma_f32_16x16x32_bf16 v[120:123], v[136:139], v[176:179], v[120:123]
	v_mfma_f32_16x16x32_bf16 v[112:115], v[136:139], v[184:187], v[112:115]
	v_mfma_f32_16x16x32_bf16 v[108:111], v[144:147], v[184:187], v[108:111]
	v_mfma_f32_16x16x32_bf16 v[100:103], v[144:147], v[192:195], v[100:103]
	v_mfma_f32_16x16x32_bf16 v[104:107], v[136:139], v[192:195], v[104:107]
	v_mfma_f32_16x16x32_bf16 v[96:99], v[148:151], v[164:167], v[96:99]
	v_mfma_f32_16x16x32_bf16 v[92:95], v[156:159], v[164:167], v[92:95]
	v_mfma_f32_16x16x32_bf16 v[84:87], v[156:159], v[172:175], v[84:87]
	v_mfma_f32_16x16x32_bf16 v[88:91], v[148:151], v[172:175], v[88:91]
	v_mfma_f32_16x16x32_bf16 v[80:83], v[148:151], v[180:183], v[80:83]
	v_mfma_f32_16x16x32_bf16 v[76:79], v[156:159], v[180:183], v[76:79]
	v_mfma_f32_16x16x32_bf16 v[68:71], v[156:159], v[188:191], v[68:71]
	v_mfma_f32_16x16x32_bf16 v[72:75], v[148:151], v[188:191], v[72:75]
	v_mfma_f32_16x16x32_bf16 v[96:99], v[152:155], v[168:171], v[96:99]
	v_mfma_f32_16x16x32_bf16 v[92:95], v[160:163], v[168:171], v[92:95]
	v_mfma_f32_16x16x32_bf16 v[84:87], v[160:163], v[176:179], v[84:87]
	v_mfma_f32_16x16x32_bf16 v[88:91], v[152:155], v[176:179], v[88:91]
	v_mfma_f32_16x16x32_bf16 v[80:83], v[152:155], v[184:187], v[80:83]
	v_mfma_f32_16x16x32_bf16 v[76:79], v[160:163], v[184:187], v[76:79]
	v_mfma_f32_16x16x32_bf16 v[68:71], v[160:163], v[192:195], v[68:71]
	v_mfma_f32_16x16x32_bf16 v[72:75], v[152:155], v[192:195], v[72:75]
	s_barrier
	s_setprio 0
	s_cselect_b32 s12, s18, s19
	s_mov_b32 m0, s26
	s_mov_b32 s46, s6
	s_mov_b32 s47, s7
	s_sub_i32 s12, s12, s44
	ds_read_b128 v[164:167], v237 offset:16384
	ds_read_b128 v[168:171], v237 offset:17408
	ds_read_b128 v[172:175], v237 offset:18432
	ds_read_b128 v[176:179], v237 offset:19456
	ds_read_b128 v[180:183], v237 offset:20480
	ds_read_b128 v[184:187], v237 offset:21504
	ds_read_b128 v[188:191], v237 offset:22528
	ds_read_b128 v[192:195], v237 offset:23552
	buffer_load_dwordx4 v221, s[44:47], s12 offen lds
	s_mov_b32 m0, s53
	s_add_i32 s39, s12, 0x40000
	buffer_load_dwordx4 v223, s[44:47], s12 offen lds
	s_mov_b32 m0, s60
	s_sub_i32 s13, s13, s4
	buffer_load_dwordx4 v221, s[44:47], s39 offen lds
	s_mov_b32 m0, s61
	s_nop 0
	buffer_load_dwordx4 v223, s[44:47], s39 offen lds
	s_mov_b32 m0, s21
	s_nop 0
	buffer_load_dwordx4 v220, s[4:7], s13 offen lds
	s_waitcnt vmcnt(7) lgkmcnt(0)
	s_setprio 1
	s_barrier
	v_mfma_f32_16x16x32_bf16 v[64:67], v[132:135], v[164:167], v[64:67]
	v_mfma_f32_16x16x32_bf16 v[60:63], v[140:143], v[164:167], v[60:63]
	v_mfma_f32_16x16x32_bf16 v[52:55], v[140:143], v[172:175], v[52:55]
	v_mfma_f32_16x16x32_bf16 v[56:59], v[132:135], v[172:175], v[56:59]
	v_mfma_f32_16x16x32_bf16 v[48:51], v[132:135], v[180:183], v[48:51]
	v_mfma_f32_16x16x32_bf16 v[44:47], v[140:143], v[180:183], v[44:47]
	v_mfma_f32_16x16x32_bf16 v[36:39], v[140:143], v[188:191], v[36:39]
	v_mfma_f32_16x16x32_bf16 v[40:43], v[132:135], v[188:191], v[40:43]
	v_mfma_f32_16x16x32_bf16 v[64:67], v[136:139], v[168:171], v[64:67]
	v_mfma_f32_16x16x32_bf16 v[60:63], v[144:147], v[168:171], v[60:63]
	v_mfma_f32_16x16x32_bf16 v[52:55], v[144:147], v[176:179], v[52:55]
	v_mfma_f32_16x16x32_bf16 v[56:59], v[136:139], v[176:179], v[56:59]
	v_mfma_f32_16x16x32_bf16 v[48:51], v[136:139], v[184:187], v[48:51]
	v_mfma_f32_16x16x32_bf16 v[44:47], v[144:147], v[184:187], v[44:47]
	v_mfma_f32_16x16x32_bf16 v[36:39], v[144:147], v[192:195], v[36:39]
	v_mfma_f32_16x16x32_bf16 v[40:43], v[136:139], v[192:195], v[40:43]
	v_mfma_f32_16x16x32_bf16 v[32:35], v[148:151], v[164:167], v[32:35]
	v_mfma_f32_16x16x32_bf16 v[28:31], v[156:159], v[164:167], v[28:31]
	v_mfma_f32_16x16x32_bf16 v[20:23], v[156:159], v[172:175], v[20:23]
	v_mfma_f32_16x16x32_bf16 v[24:27], v[148:151], v[172:175], v[24:27]
	v_mfma_f32_16x16x32_bf16 v[16:19], v[148:151], v[180:183], v[16:19]
	v_mfma_f32_16x16x32_bf16 v[12:15], v[156:159], v[180:183], v[12:15]
	v_mfma_f32_16x16x32_bf16 v[2:5], v[156:159], v[188:191], v[4:7]
	v_mfma_f32_16x16x32_bf16 v[8:11], v[148:151], v[188:191], v[8:11]
	v_mfma_f32_16x16x32_bf16 v[32:35], v[152:155], v[168:171], v[32:35]
	v_mfma_f32_16x16x32_bf16 v[28:31], v[160:163], v[168:171], v[28:31]
	v_mfma_f32_16x16x32_bf16 v[20:23], v[160:163], v[176:179], v[20:23]
	v_mfma_f32_16x16x32_bf16 v[24:27], v[152:155], v[176:179], v[24:27]
	v_mfma_f32_16x16x32_bf16 v[16:19], v[152:155], v[184:187], v[16:19]
	v_mfma_f32_16x16x32_bf16 v[12:15], v[160:163], v[184:187], v[12:15]
	v_mfma_f32_16x16x32_bf16 v[2:5], v[160:163], v[192:195], v[2:5]
	v_mfma_f32_16x16x32_bf16 v[8:11], v[152:155], v[192:195], v[8:11]
	s_barrier
; #define PG8_STAGE(bufoff, gbase, voff) do { const int so_ = (int)(unsigned)((const char*)(gbase) - base_##voff); _Pragma("unroll") for (int _i = 0; _i < 2; ++_i) \
;         __builtin_amdgcn_raw_ptr_buffer_load_lds(rs_##voff, (PG8_LAS unsigned*)(lds + (bufoff) + ldsw + _i * 8192), 16, (int)(voff)[_i], so_, 0, 0); } while (0)
; #define PG8_LDA(dst, b, h) do { _Pragma("unroll") for (int m = 0; m < 4; ++m) _Pragma("unroll") for (int k = 0; k < 2; ++k) dst[m][k] = *(const PG8_LAS bf16x8*)(lds + PG8_SA(b, h) + aoff + m * 2048 + k * 1024); } while (0)
; #define PG8_LDB(dst, b, h) do { _Pragma("unroll") for (int n = 0; n < 2; ++n) _Pragma("unroll") for (int k = 0; k < 2; ++k) dst[n][k] = *(const PG8_LAS bf16x8*)(lds + PG8_SB(b, h) + boff + n * 2048 + k * 1024); } while (0)
; #define PG8_MMA(ai, bj, At, Bt) do { __builtin_amdgcn_s_setprio(1); _Pragma("unroll") for (int m = 0; m < 4; ++m) _Pragma("unroll") for (int n = 0; n < 2; ++n) _Pragma("unroll") for (int k = 0; k < 2; ++k) \
;         acc[ai][bj][m][n] = __builtin_amdgcn_mfma_f32_16x16x32_bf16(Bt[n][k], At[m][k], acc[ai][bj][m][n], 0, 0, 0); __builtin_amdgcn_s_setprio(0); } while (0)
; #define PG8_WAIT_V(n) asm volatile("s_waitcnt vmcnt(" #n ")" ::: "memory")
; #define PG8_WAIT_L(n) asm volatile("s_waitcnt lgkmcnt(" #n ")" ::: "memory")
; #define PG8_BAR __builtin_amdgcn_s_barrier()
; #define PG8_SCHED __builtin_amdgcn_sched_barrier(0)
; template <class Epi, class Sched, bool ALIGN_EPI = false, bool SP2 = false>
; __device__ __forceinline__ void gemm_phase(PG8_LAS unsigned char* lds, const Gemm g, const Sched& S, const Epi& E, int tid_in) {
;     ...
;             PG8_LDB(B0, 1, 0); PG8_LDB(B1, 1, 1); PG8_SCHED; PG8_LDA(At, 1, 0); PG8_STAGE(PG8_SA(0, 1), a2 + hstepA, voffA);
;             PG8_WAIT_V(8); PG8_WAIT_L(0); PG8_BAR; PG8_MMA(0, 0, At, B0); PG8_MMA(0, 1, At, B1); PG8_BAR; PG8_SCHED;
;             PG8_LDA(At, 1, 1); PG8_STAGE(PG8_SB(1, 0), b3, voffB); PG8_STAGE(PG8_SB(1, 1), b3 + hstepB, voffB); PG8_STAGE(PG8_SA(1, 0), a3, voffA);
;             PG8_WAIT_V(8); PG8_WAIT_L(0); PG8_BAR; PG8_MMA(1, 0, At, B0); PG8_MMA(1, 1, At, B1); PG8_BAR; PG8_SCHED;
	s_setprio 0
	v_add_u32_e32 v0, 0x18000, v236
	ds_read_b128 v[132:135], v0
	ds_read_b128 v[136:139], v0 offset:1024
	ds_read_b128 v[140:143], v0 offset:2048
	ds_read_b128 v[144:147], v0 offset:3072
	v_add_u32_e32 v0, 0x1c000, v236
	ds_read_b128 v[148:151], v0
	ds_read_b128 v[152:155], v0 offset:1024
	ds_read_b128 v[156:159], v0 offset:2048
	ds_read_b128 v[160:163], v0 offset:3072
	s_add_i32 s39, s13, 0xc0000
	s_mov_b32 m0, s63
	ds_read_b128 v[164:167], v237 offset:32768
	ds_read_b128 v[168:171], v237 offset:33792
	ds_read_b128 v[172:175], v237 offset:34816
	ds_read_b128 v[176:179], v237 offset:35840
	ds_read_b128 v[180:183], v237 offset:36864
	ds_read_b128 v[184:187], v237 offset:37888
	ds_read_b128 v[188:191], v237 offset:38912
	ds_read_b128 v[192:195], v237 offset:39936
	s_mov_b32 m0, s62
	s_nop 0
	buffer_load_dwordx4 v222, s[4:7], s13 offen lds
	s_mov_b32 m0, s63
	s_nop 0
	buffer_load_dwordx4 v220, s[4:7], s39 offen lds
	s_mov_b32 m0, s66
	s_nop 0
	buffer_load_dwordx4 v222, s[4:7], s39 offen lds
	s_waitcnt vmcnt(8) lgkmcnt(0)
	s_setprio 1
	s_barrier
	v_mfma_f32_16x16x32_bf16 v[128:131], v[132:135], v[164:167], v[128:131]
	v_mfma_f32_16x16x32_bf16 v[124:127], v[140:143], v[164:167], v[124:127]
	v_mfma_f32_16x16x32_bf16 v[116:119], v[140:143], v[172:175], v[116:119]
	v_mfma_f32_16x16x32_bf16 v[120:123], v[132:135], v[172:175], v[120:123]
	v_mfma_f32_16x16x32_bf16 v[112:115], v[132:135], v[180:183], v[112:115]
	v_mfma_f32_16x16x32_bf16 v[108:111], v[140:143], v[180:183], v[108:111]
	v_mfma_f32_16x16x32_bf16 v[100:103], v[140:143], v[188:191], v[100:103]
	v_mfma_f32_16x16x32_bf16 v[104:107], v[132:135], v[188:191], v[104:107]
	v_mfma_f32_16x16x32_bf16 v[128:131], v[136:139], v[168:171], v[128:131]
	v_mfma_f32_16x16x32_bf16 v[124:127], v[144:147], v[168:171], v[124:127]
	v_mfma_f32_16x16x32_bf16 v[116:119], v[144:147], v[176:179], v[116:119]
	v_mfma_f32_16x16x32_bf16 v[120:123], v[136:139], v[176:179], v[120:123]
	v_mfma_f32_16x16x32_bf16 v[112:115], v[136:139], v[184:187], v[112:115]
	v_mfma_f32_16x16x32_bf16 v[108:111], v[144:147], v[184:187], v[108:111]
	v_mfma_f32_16x16x32_bf16 v[100:103], v[144:147], v[192:195], v[100:103]
	v_mfma_f32_16x16x32_bf16 v[104:107], v[136:139], v[192:195], v[104:107]
	v_mfma_f32_16x16x32_bf16 v[96:99], v[148:151], v[164:167], v[96:99]
	v_mfma_f32_16x16x32_bf16 v[92:95], v[156:159], v[164:167], v[92:95]
	v_mfma_f32_16x16x32_bf16 v[84:87], v[156:159], v[172:175], v[84:87]
	v_mfma_f32_16x16x32_bf16 v[88:91], v[148:151], v[172:175], v[88:91]
	v_mfma_f32_16x16x32_bf16 v[80:83], v[148:151], v[180:183], v[80:83]
	v_mfma_f32_16x16x32_bf16 v[76:79], v[156:159], v[180:183], v[76:79]
	v_mfma_f32_16x16x32_bf16 v[68:71], v[156:159], v[188:191], v[68:71]
	v_mfma_f32_16x16x32_bf16 v[72:75], v[148:151], v[188:191], v[72:75]
	v_mfma_f32_16x16x32_bf16 v[96:99], v[152:155], v[168:171], v[96:99]
	v_mfma_f32_16x16x32_bf16 v[92:95], v[160:163], v[168:171], v[92:95]
	v_mfma_f32_16x16x32_bf16 v[84:87], v[160:163], v[176:179], v[84:87]
	v_mfma_f32_16x16x32_bf16 v[88:91], v[152:155], v[176:179], v[88:91]
	v_mfma_f32_16x16x32_bf16 v[80:83], v[152:155], v[184:187], v[80:83]
	v_mfma_f32_16x16x32_bf16 v[76:79], v[160:163], v[184:187], v[76:79]
	v_mfma_f32_16x16x32_bf16 v[68:71], v[160:163], v[192:195], v[68:71]
	v_mfma_f32_16x16x32_bf16 v[72:75], v[152:155], v[192:195], v[72:75]
	s_barrier
	s_setprio 0
	s_mov_b32 m0, s69
	s_add_i32 s39, s12, 0x80
	ds_read_b128 v[164:167], v237 offset:49152
	ds_read_b128 v[168:171], v237 offset:50176
	ds_read_b128 v[172:175], v237 offset:51200
	ds_read_b128 v[176:179], v237 offset:52224
	ds_read_b128 v[180:183], v237 offset:53248
	ds_read_b128 v[184:187], v237 offset:54272
	ds_read_b128 v[188:191], v237 offset:55296
	ds_read_b128 v[192:195], v237 offset:56320
	buffer_load_dwordx4 v221, s[44:47], s39 offen lds
	s_mov_b32 m0, s71
	s_add_i32 s12, s12, 0x40080
	buffer_load_dwordx4 v223, s[44:47], s39 offen lds
	s_mov_b32 m0, s74
	s_addk_i32 s13, 0x80
	buffer_load_dwordx4 v221, s[44:47], s12 offen lds
	s_mov_b32 m0, s75
	s_nop 0
	buffer_load_dwordx4 v223, s[44:47], s12 offen lds
	s_mov_b32 m0, s72
	s_nop 0
	buffer_load_dwordx4 v220, s[4:7], s13 offen lds
	s_waitcnt vmcnt(7) lgkmcnt(0)
	s_setprio 1
	s_barrier
	v_mfma_f32_16x16x32_bf16 v[64:67], v[132:135], v[164:167], v[64:67]
	v_mfma_f32_16x16x32_bf16 v[60:63], v[140:143], v[164:167], v[60:63]
	v_mfma_f32_16x16x32_bf16 v[52:55], v[140:143], v[172:175], v[52:55]
	v_mfma_f32_16x16x32_bf16 v[56:59], v[132:135], v[172:175], v[56:59]
	v_mfma_f32_16x16x32_bf16 v[48:51], v[132:135], v[180:183], v[48:51]
	v_mfma_f32_16x16x32_bf16 v[44:47], v[140:143], v[180:183], v[44:47]
	v_mfma_f32_16x16x32_bf16 v[36:39], v[140:143], v[188:191], v[36:39]
	v_mfma_f32_16x16x32_bf16 v[40:43], v[132:135], v[188:191], v[40:43]
	v_mfma_f32_16x16x32_bf16 v[64:67], v[136:139], v[168:171], v[64:67]
	v_mfma_f32_16x16x32_bf16 v[60:63], v[144:147], v[168:171], v[60:63]
	v_mfma_f32_16x16x32_bf16 v[52:55], v[144:147], v[176:179], v[52:55]
	v_mfma_f32_16x16x32_bf16 v[56:59], v[136:139], v[176:179], v[56:59]
	v_mfma_f32_16x16x32_bf16 v[48:51], v[136:139], v[184:187], v[48:51]
	v_mfma_f32_16x16x32_bf16 v[44:47], v[144:147], v[184:187], v[44:47]
	v_mfma_f32_16x16x32_bf16 v[36:39], v[144:147], v[192:195], v[36:39]
	v_mfma_f32_16x16x32_bf16 v[40:43], v[136:139], v[192:195], v[40:43]
	v_mfma_f32_16x16x32_bf16 v[32:35], v[148:151], v[164:167], v[32:35]
	v_mfma_f32_16x16x32_bf16 v[28:31], v[156:159], v[164:167], v[28:31]
	v_mfma_f32_16x16x32_bf16 v[20:23], v[156:159], v[172:175], v[20:23]
	v_mfma_f32_16x16x32_bf16 v[24:27], v[148:151], v[172:175], v[24:27]
	v_mfma_f32_16x16x32_bf16 v[16:19], v[148:151], v[180:183], v[16:19]
	v_mfma_f32_16x16x32_bf16 v[12:15], v[156:159], v[180:183], v[12:15]
	v_mfma_f32_16x16x32_bf16 v[2:5], v[156:159], v[188:191], v[2:5]
	v_mfma_f32_16x16x32_bf16 v[6:9], v[148:151], v[188:191], v[8:11]
	v_mfma_f32_16x16x32_bf16 v[32:35], v[152:155], v[168:171], v[32:35]
	v_mfma_f32_16x16x32_bf16 v[28:31], v[160:163], v[168:171], v[28:31]
	v_mfma_f32_16x16x32_bf16 v[20:23], v[160:163], v[176:179], v[20:23]
	v_mfma_f32_16x16x32_bf16 v[24:27], v[152:155], v[176:179], v[24:27]
	v_mfma_f32_16x16x32_bf16 v[16:19], v[152:155], v[184:187], v[16:19]
	v_mfma_f32_16x16x32_bf16 v[12:15], v[160:163], v[184:187], v[12:15]
	v_mfma_f32_16x16x32_bf16 v[4:7], v[160:163], v[192:195], v[2:5]
	v_mfma_f32_16x16x32_bf16 v[8:11], v[152:155], v[192:195], v[6:9]
	s_barrier
	s_setprio 0
	s_add_i32 s38, s38, 2
	s_add_u32 s19, s19, 0x100
	s_addc_u32 s23, s23, 0
	s_cmp_gt_u32 s38, 13
	s_mov_b64 s[12:13], s[16:17]
	s_cbranch_scc0 .LBB0_1037
	s_and_b64 vcc, exec, s[14:15]
	s_cbranch_vccz .LBB0_1040
	s_barrier

; #define PG8_STAGE(bufoff, gbase, voff) do { const int so_ = (int)(unsigned)((const char*)(gbase) - base_##voff); _Pragma("unroll") for (int _i = 0; _i < 2; ++_i) \
;         __builtin_amdgcn_raw_ptr_buffer_load_lds(rs_##voff, (PG8_LAS unsigned*)(lds + (bufoff) + ldsw + _i * 8192), 16, (int)(voff)[_i], so_, 0, 0); } while (0)
; #define PG8_LDA(dst, b, h) do { _Pragma("unroll") for (int m = 0; m < 4; ++m) _Pragma("unroll") for (int k = 0; k < 2; ++k) dst[m][k] = *(const PG8_LAS bf16x8*)(lds + PG8_SA(b, h) + aoff + m * 2048 + k * 1024); } while (0)
; #define PG8_LDB(dst, b, h) do { _Pragma("unroll") for (int n = 0; n < 2; ++n) _Pragma("unroll") for (int k = 0; k < 2; ++k) dst[n][k] = *(const PG8_LAS bf16x8*)(lds + PG8_SB(b, h) + boff + n * 2048 + k * 1024); } while (0)
; #define PG8_MMA(ai, bj, At, Bt) do { __builtin_amdgcn_s_setprio(1); _Pragma("unroll") for (int m = 0; m < 4; ++m) _Pragma("unroll") for (int n = 0; n < 2; ++n) _Pragma("unroll") for (int k = 0; k < 2; ++k) \
;         acc[ai][bj][m][n] = __builtin_amdgcn_mfma_f32_16x16x32_bf16(Bt[n][k], At[m][k], acc[ai][bj][m][n], 0, 0, 0); __builtin_amdgcn_s_setprio(0); } while (0)
; #define PG8_WAIT_V(n) asm volatile("s_waitcnt vmcnt(" #n ")" ::: "memory")
; #define PG8_WAIT_L(n) asm volatile("s_waitcnt lgkmcnt(" #n ")" ::: "memory")
; #define PG8_BAR __builtin_amdgcn_s_barrier()
; #define PG8_SCHED __builtin_amdgcn_sched_barrier(0)
; template <class Epi, class Sched, bool ALIGN_EPI = false, bool SP2 = false>
; __device__ __forceinline__ void gemm_phase(PG8_LAS unsigned char* lds, const Gemm g, const Sched& S, const Epi& E, int tid_in) {
;     ...
;             PG8_LDB(B0, 0, 0); PG8_LDB(B1, 0, 1); PG8_SCHED; PG8_LDA(At, 0, 0); PG8_STAGE(PG8_SA(1, 1), a1 + hstepA, voffA);
;             PG8_WAIT_V(8); PG8_WAIT_L(0); PG8_BAR; PG8_MMA(0, 0, At, B0); PG8_MMA(0, 1, At, B1); PG8_BAR; PG8_SCHED;
;             PG8_LDA(At, 0, 1); PG8_STAGE(PG8_SB(0, 0), b2, voffB); PG8_STAGE(PG8_SB(0, 1), b2 + hstepB, voffB); PG8_STAGE(PG8_SA(0, 0), a2, voffA);
;             PG8_WAIT_V(8); PG8_WAIT_L(0); PG8_BAR; PG8_MMA(1, 0, At, B0); PG8_MMA(1, 1, At, B1); PG8_BAR; PG8_SCHED;
.LBB0_1265:
	v_add_u32_e32 v133, 0x10000, v131
	ds_read_b128 v[134:137], v133
	ds_read_b128 v[138:141], v133 offset:1024
	ds_read_b128 v[142:145], v133 offset:2048
	ds_read_b128 v[146:149], v133 offset:3072
	v_add_u32_e32 v133, 0x14000, v131
	ds_read_b128 v[150:153], v133
	ds_read_b128 v[154:157], v133 offset:1024
	ds_read_b128 v[158:161], v133 offset:2048
	ds_read_b128 v[166:169], v133 offset:3072
	s_add_i32 s42, s18, s44
	s_add_i32 s21, s14, s44
	s_add_i32 s79, s12, s44
	s_addk_i32 s42, 0xff80
	s_sub_i32 vcc_lo, s42, 0x80000
	s_cmp_eq_u32 s19, 28
	s_cselect_b32 s21, s15, s21
	s_mov_b32 m0, s75
	ds_read_b128 v[170:173], v132
	ds_read_b128 v[174:177], v132 offset:1024
	ds_read_b128 v[178:181], v132 offset:2048
	ds_read_b128 v[182:185], v132 offset:3072
	ds_read_b128 v[186:189], v132 offset:4096
	ds_read_b128 v[190:193], v132 offset:5120
	ds_read_b128 v[200:203], v132 offset:6144
	ds_read_b128 v[206:209], v132 offset:7168
	s_mov_b32 m0, s72
	s_nop 0
	buffer_load_dwordx4 v130, s[4:7], vcc_lo offen lds
	s_mov_b32 m0, s75
	s_nop 0
	buffer_load_dwordx4 v0, s[4:7], s42 offen lds
	s_mov_b32 m0, s76
	s_nop 0
	buffer_load_dwordx4 v130, s[4:7], s42 offen lds
	s_waitcnt vmcnt(8) lgkmcnt(0)
	s_setprio 1
	s_barrier
	v_mfma_f32_16x16x32_bf16 v[34:37], v[134:137], v[170:173], v[34:37]
	v_mfma_f32_16x16x32_bf16 v[18:21], v[142:145], v[170:173], v[18:21]
	v_mfma_f32_16x16x32_bf16 v[78:81], v[142:145], v[178:181], v[78:81]
	v_mfma_f32_16x16x32_bf16 v[86:89], v[134:137], v[178:181], v[86:89]
	v_mfma_f32_16x16x32_bf16 v[106:109], v[134:137], v[186:189], v[106:109]
	v_mfma_f32_16x16x32_bf16 v[102:105], v[142:145], v[186:189], v[102:105]
	v_mfma_f32_16x16x32_bf16 v[122:125], v[142:145], v[200:203], v[122:125]
	v_mfma_f32_16x16x32_bf16 v[126:129], v[134:137], v[200:203], v[126:129]
	v_mfma_f32_16x16x32_bf16 v[34:37], v[138:141], v[174:177], v[34:37]
	v_mfma_f32_16x16x32_bf16 v[18:21], v[146:149], v[174:177], v[18:21]
	v_mfma_f32_16x16x32_bf16 v[78:81], v[146:149], v[182:185], v[78:81]
	v_mfma_f32_16x16x32_bf16 v[86:89], v[138:141], v[182:185], v[86:89]
	v_mfma_f32_16x16x32_bf16 v[106:109], v[138:141], v[190:193], v[106:109]
	v_mfma_f32_16x16x32_bf16 v[102:105], v[146:149], v[190:193], v[102:105]
	v_mfma_f32_16x16x32_bf16 v[122:125], v[146:149], v[206:209], v[122:125]
	v_mfma_f32_16x16x32_bf16 v[126:129], v[138:141], v[206:209], v[126:129]
	v_mfma_f32_16x16x32_bf16 v[14:17], v[150:153], v[170:173], v[14:17]
	v_mfma_f32_16x16x32_bf16 v[38:41], v[158:161], v[170:173], v[38:41]
	v_mfma_f32_16x16x32_bf16 v[90:93], v[158:161], v[178:181], v[90:93]
	v_mfma_f32_16x16x32_bf16 v[74:77], v[150:153], v[178:181], v[74:77]
	v_mfma_f32_16x16x32_bf16 v[98:101], v[150:153], v[186:189], v[98:101]
	v_mfma_f32_16x16x32_bf16 v[110:113], v[158:161], v[186:189], v[110:113]
	v_mfma_f32_16x16x32_bf16 v[114:117], v[158:161], v[200:203], v[114:117]
	v_mfma_f32_16x16x32_bf16 v[118:121], v[150:153], v[200:203], v[118:121]
	v_mfma_f32_16x16x32_bf16 v[14:17], v[154:157], v[174:177], v[14:17]
	v_mfma_f32_16x16x32_bf16 v[38:41], v[166:169], v[174:177], v[38:41]
	v_mfma_f32_16x16x32_bf16 v[90:93], v[166:169], v[182:185], v[90:93]
	v_mfma_f32_16x16x32_bf16 v[74:77], v[154:157], v[182:185], v[74:77]
	v_mfma_f32_16x16x32_bf16 v[98:101], v[154:157], v[190:193], v[98:101]
	v_mfma_f32_16x16x32_bf16 v[110:113], v[166:169], v[190:193], v[110:113]
	v_mfma_f32_16x16x32_bf16 v[114:117], v[166:169], v[206:209], v[114:117]
	v_mfma_f32_16x16x32_bf16 v[118:121], v[154:157], v[206:209], v[118:121]
	s_barrier
	s_setprio 0
	s_cselect_b32 s79, s17, s79
	s_mov_b32 m0, s49
	s_mov_b32 s42, s6
	s_mov_b32 s43, s7
	s_sub_i32 s79, s79, s40
	ds_read_b128 v[170:173], v132 offset:16384
	ds_read_b128 v[174:177], v132 offset:17408
	ds_read_b128 v[178:181], v132 offset:18432
	ds_read_b128 v[182:185], v132 offset:19456
	ds_read_b128 v[186:189], v132 offset:20480
	ds_read_b128 v[190:193], v132 offset:21504
	ds_read_b128 v[200:203], v132 offset:22528
	ds_read_b128 v[206:209], v132 offset:23552
	buffer_load_dwordx4 v0, s[40:43], s79 offen lds
	s_mov_b32 m0, s60
	s_add_i32 vcc_lo, s79, 0x80000
	buffer_load_dwordx4 v130, s[40:43], s79 offen lds
	s_mov_b32 m0, s61
	s_sub_i32 s21, s21, s4
	buffer_load_dwordx4 v0, s[40:43], vcc_lo offen lds
	s_mov_b32 m0, s62
	s_nop 0
	buffer_load_dwordx4 v130, s[40:43], vcc_lo offen lds
	s_mov_b32 m0, s35
	s_nop 0
	buffer_load_dwordx4 v0, s[4:7], s21 offen lds
	s_waitcnt vmcnt(7) lgkmcnt(0)
	s_setprio 1
	s_barrier
	v_mfma_f32_16x16x32_bf16 v[50:53], v[134:137], v[170:173], v[50:53]
	v_mfma_f32_16x16x32_bf16 v[30:33], v[142:145], v[170:173], v[30:33]
	v_mfma_f32_16x16x32_bf16 v[58:61], v[142:145], v[178:181], v[58:61]
	v_mfma_f32_16x16x32_bf16 v[62:65], v[134:137], v[178:181], v[62:65]
	v_mfma_f32_16x16x32_bf16 v[94:97], v[134:137], v[186:189], v[94:97]
	v_mfma_f32_16x16x32_bf16 v[82:85], v[142:145], v[186:189], v[82:85]
	v_mfma_f32_16x16x32_bf16 v[26:29], v[142:145], v[200:203], v[26:29]
	v_mfma_f32_16x16x32_bf16 v[46:49], v[134:137], v[200:203], v[46:49]
	v_mfma_f32_16x16x32_bf16 v[50:53], v[138:141], v[174:177], v[50:53]
	v_mfma_f32_16x16x32_bf16 v[30:33], v[146:149], v[174:177], v[30:33]
	v_mfma_f32_16x16x32_bf16 v[58:61], v[146:149], v[182:185], v[58:61]
	v_mfma_f32_16x16x32_bf16 v[62:65], v[138:141], v[182:185], v[62:65]
	v_mfma_f32_16x16x32_bf16 v[94:97], v[138:141], v[190:193], v[94:97]
	v_mfma_f32_16x16x32_bf16 v[82:85], v[146:149], v[190:193], v[82:85]
	v_mfma_f32_16x16x32_bf16 v[26:29], v[146:149], v[206:209], v[26:29]
	v_mfma_f32_16x16x32_bf16 v[46:49], v[138:141], v[206:209], v[46:49]
	v_mfma_f32_16x16x32_bf16 v[22:25], v[150:153], v[170:173], v[22:25]
	v_mfma_f32_16x16x32_bf16 v[10:13], v[158:161], v[170:173], v[10:13]
	v_mfma_f32_16x16x32_bf16 v[66:69], v[158:161], v[178:181], v[66:69]
	v_mfma_f32_16x16x32_bf16 v[54:57], v[150:153], v[178:181], v[54:57]
	v_mfma_f32_16x16x32_bf16 v[70:73], v[150:153], v[186:189], v[70:73]
	v_mfma_f32_16x16x32_bf16 v[42:45], v[158:161], v[186:189], v[42:45]
	v_mfma_f32_16x16x32_bf16 v[2:5], v[158:161], v[200:203], v[2:5]
	v_mfma_f32_16x16x32_bf16 v[6:9], v[150:153], v[200:203], v[6:9]
	v_mfma_f32_16x16x32_bf16 v[22:25], v[154:157], v[174:177], v[22:25]
	v_mfma_f32_16x16x32_bf16 v[10:13], v[166:169], v[174:177], v[10:13]
	v_mfma_f32_16x16x32_bf16 v[66:69], v[166:169], v[182:185], v[66:69]
	v_mfma_f32_16x16x32_bf16 v[54:57], v[154:157], v[182:185], v[54:57]
	v_mfma_f32_16x16x32_bf16 v[70:73], v[154:157], v[190:193], v[70:73]
	v_mfma_f32_16x16x32_bf16 v[42:45], v[166:169], v[190:193], v[42:45]
	v_mfma_f32_16x16x32_bf16 v[2:5], v[166:169], v[206:209], v[2:5]
	v_mfma_f32_16x16x32_bf16 v[6:9], v[154:157], v[206:209], v[6:9]
	s_barrier
; #define PG8_STAGE(bufoff, gbase, voff) do { const int so_ = (int)(unsigned)((const char*)(gbase) - base_##voff); _Pragma("unroll") for (int _i = 0; _i < 2; ++_i) \
;         __builtin_amdgcn_raw_ptr_buffer_load_lds(rs_##voff, (PG8_LAS unsigned*)(lds + (bufoff) + ldsw + _i * 8192), 16, (int)(voff)[_i], so_, 0, 0); } while (0)
; #define PG8_LDA(dst, b, h) do { _Pragma("unroll") for (int m = 0; m < 4; ++m) _Pragma("unroll") for (int k = 0; k < 2; ++k) dst[m][k] = *(const PG8_LAS bf16x8*)(lds + PG8_SA(b, h) + aoff + m * 2048 + k * 1024); } while (0)
; #define PG8_LDB(dst, b, h) do { _Pragma("unroll") for (int n = 0; n < 2; ++n) _Pragma("unroll") for (int k = 0; k < 2; ++k) dst[n][k] = *(const PG8_LAS bf16x8*)(lds + PG8_SB(b, h) + boff + n * 2048 + k * 1024); } while (0)
; #define PG8_MMA(ai, bj, At, Bt) do { __builtin_amdgcn_s_setprio(1); _Pragma("unroll") for (int m = 0; m < 4; ++m) _Pragma("unroll") for (int n = 0; n < 2; ++n) _Pragma("unroll") for (int k = 0; k < 2; ++k) \
;         acc[ai][bj][m][n] = __builtin_amdgcn_mfma_f32_16x16x32_bf16(Bt[n][k], At[m][k], acc[ai][bj][m][n], 0, 0, 0); __builtin_amdgcn_s_setprio(0); } while (0)
; #define PG8_WAIT_V(n) asm volatile("s_waitcnt vmcnt(" #n ")" ::: "memory")
; #define PG8_WAIT_L(n) asm volatile("s_waitcnt lgkmcnt(" #n ")" ::: "memory")
; #define PG8_BAR __builtin_amdgcn_s_barrier()
; #define PG8_SCHED __builtin_amdgcn_sched_barrier(0)
; template <class Epi, class Sched, bool ALIGN_EPI = false, bool SP2 = false>
; __device__ __forceinline__ void gemm_phase(PG8_LAS unsigned char* lds, const Gemm g, const Sched& S, const Epi& E, int tid_in) {
;     ...
;             PG8_LDB(B0, 1, 0); PG8_LDB(B1, 1, 1); PG8_SCHED; PG8_LDA(At, 1, 0); PG8_STAGE(PG8_SA(0, 1), a2 + hstepA, voffA);
;             PG8_WAIT_V(8); PG8_WAIT_L(0); PG8_BAR; PG8_MMA(0, 0, At, B0); PG8_MMA(0, 1, At, B1); PG8_BAR; PG8_SCHED;
;             PG8_LDA(At, 1, 1); PG8_STAGE(PG8_SB(1, 0), b3, voffB); PG8_STAGE(PG8_SB(1, 1), b3 + hstepB, voffB); PG8_STAGE(PG8_SA(1, 0), a3, voffA);
;             PG8_WAIT_V(8); PG8_WAIT_L(0); PG8_BAR; PG8_MMA(1, 0, At, B0); PG8_MMA(1, 1, At, B1); PG8_BAR; PG8_SCHED;
	s_setprio 0
	v_add_u32_e32 v133, 0x18000, v131
	ds_read_b128 v[134:137], v133
	ds_read_b128 v[138:141], v133 offset:1024
	ds_read_b128 v[142:145], v133 offset:2048
	ds_read_b128 v[146:149], v133 offset:3072
	v_add_u32_e32 v133, 0x1c000, v131
	ds_read_b128 v[150:153], v133
	ds_read_b128 v[154:157], v133 offset:1024
	ds_read_b128 v[158:161], v133 offset:2048
	ds_read_b128 v[166:169], v133 offset:3072
	s_add_i32 vcc_lo, s21, 0x80000
	s_mov_b32 m0, s66
	ds_read_b128 v[170:173], v132 offset:32768
	ds_read_b128 v[174:177], v132 offset:33792
	ds_read_b128 v[178:181], v132 offset:34816
	ds_read_b128 v[182:185], v132 offset:35840
	ds_read_b128 v[186:189], v132 offset:36864
	ds_read_b128 v[190:193], v132 offset:37888
	ds_read_b128 v[200:203], v132 offset:38912
	ds_read_b128 v[206:209], v132 offset:39936
	s_mov_b32 m0, s63
	s_nop 0
	buffer_load_dwordx4 v130, s[4:7], s21 offen lds
	s_mov_b32 m0, s66
	s_nop 0
	buffer_load_dwordx4 v0, s[4:7], vcc_lo offen lds
	s_mov_b32 m0, s67
	s_nop 0
	buffer_load_dwordx4 v130, s[4:7], vcc_lo offen lds
	s_waitcnt vmcnt(8) lgkmcnt(0)
	s_setprio 1
	s_barrier
	v_mfma_f32_16x16x32_bf16 v[34:37], v[134:137], v[170:173], v[34:37]
	v_mfma_f32_16x16x32_bf16 v[18:21], v[142:145], v[170:173], v[18:21]
	v_mfma_f32_16x16x32_bf16 v[78:81], v[142:145], v[178:181], v[78:81]
	v_mfma_f32_16x16x32_bf16 v[86:89], v[134:137], v[178:181], v[86:89]
	v_mfma_f32_16x16x32_bf16 v[106:109], v[134:137], v[186:189], v[106:109]
	v_mfma_f32_16x16x32_bf16 v[102:105], v[142:145], v[186:189], v[102:105]
	v_mfma_f32_16x16x32_bf16 v[122:125], v[142:145], v[200:203], v[122:125]
	v_mfma_f32_16x16x32_bf16 v[126:129], v[134:137], v[200:203], v[126:129]
	v_mfma_f32_16x16x32_bf16 v[34:37], v[138:141], v[174:177], v[34:37]
	v_mfma_f32_16x16x32_bf16 v[18:21], v[146:149], v[174:177], v[18:21]
	v_mfma_f32_16x16x32_bf16 v[78:81], v[146:149], v[182:185], v[78:81]
	v_mfma_f32_16x16x32_bf16 v[86:89], v[138:141], v[182:185], v[86:89]
	v_mfma_f32_16x16x32_bf16 v[106:109], v[138:141], v[190:193], v[106:109]
	v_mfma_f32_16x16x32_bf16 v[102:105], v[146:149], v[190:193], v[102:105]
	v_mfma_f32_16x16x32_bf16 v[122:125], v[146:149], v[206:209], v[122:125]
	v_mfma_f32_16x16x32_bf16 v[126:129], v[138:141], v[206:209], v[126:129]
	v_mfma_f32_16x16x32_bf16 v[14:17], v[150:153], v[170:173], v[14:17]
	v_mfma_f32_16x16x32_bf16 v[38:41], v[158:161], v[170:173], v[38:41]
	v_mfma_f32_16x16x32_bf16 v[90:93], v[158:161], v[178:181], v[90:93]
	v_mfma_f32_16x16x32_bf16 v[74:77], v[150:153], v[178:181], v[74:77]
	v_mfma_f32_16x16x32_bf16 v[98:101], v[150:153], v[186:189], v[98:101]
	v_mfma_f32_16x16x32_bf16 v[110:113], v[158:161], v[186:189], v[110:113]
	v_mfma_f32_16x16x32_bf16 v[114:117], v[158:161], v[200:203], v[114:117]
	v_mfma_f32_16x16x32_bf16 v[118:121], v[150:153], v[200:203], v[118:121]
	v_mfma_f32_16x16x32_bf16 v[14:17], v[154:157], v[174:177], v[14:17]
	v_mfma_f32_16x16x32_bf16 v[38:41], v[166:169], v[174:177], v[38:41]
	v_mfma_f32_16x16x32_bf16 v[90:93], v[166:169], v[182:185], v[90:93]
	v_mfma_f32_16x16x32_bf16 v[74:77], v[154:157], v[182:185], v[74:77]
	v_mfma_f32_16x16x32_bf16 v[98:101], v[154:157], v[190:193], v[98:101]
	v_mfma_f32_16x16x32_bf16 v[110:113], v[166:169], v[190:193], v[110:113]
	v_mfma_f32_16x16x32_bf16 v[114:117], v[166:169], v[206:209], v[114:117]
	v_mfma_f32_16x16x32_bf16 v[118:121], v[154:157], v[206:209], v[118:121]
	s_barrier
	s_setprio 0
	s_mov_b32 m0, s68
	s_add_i32 vcc_lo, s79, 0x80
	ds_read_b128 v[170:173], v132 offset:49152
	ds_read_b128 v[174:177], v132 offset:50176
	ds_read_b128 v[178:181], v132 offset:51200
	ds_read_b128 v[182:185], v132 offset:52224
	ds_read_b128 v[186:189], v132 offset:53248
	ds_read_b128 v[190:193], v132 offset:54272
	ds_read_b128 v[200:203], v132 offset:55296
	ds_read_b128 v[206:209], v132 offset:56320
	buffer_load_dwordx4 v0, s[40:43], vcc_lo offen lds
	s_mov_b32 m0, s69
	s_add_i32 s79, s79, 0x80080
	buffer_load_dwordx4 v130, s[40:43], vcc_lo offen lds
	s_mov_b32 m0, s73
	s_addk_i32 s21, 0x80
	buffer_load_dwordx4 v0, s[40:43], s79 offen lds
	s_mov_b32 m0, s74
	s_nop 0
	buffer_load_dwordx4 v130, s[40:43], s79 offen lds
	s_mov_b32 m0, s71
	s_nop 0
	buffer_load_dwordx4 v0, s[4:7], s21 offen lds
	s_waitcnt vmcnt(7) lgkmcnt(0)
	s_setprio 1
	s_barrier
;     static __device__ __forceinline__ bool last_of_chain(const Unit& u) { return (u.pn >> 3) == 2; }
; template <class Epi, class Sched, bool ALIGN_EPI = false, bool SP2 = false>
; __device__ __forceinline__ void gemm_phase(PG8_LAS unsigned char* lds, const Gemm g, const Sched& S, const Epi& E, int tid_in) {
;     ...
;             PG8_WAIT_V(8); PG8_WAIT_L(0); PG8_BAR; PG8_MMA(1, 0, At, B0); PG8_MMA(1, 1, At, B1); PG8_BAR; PG8_SCHED;
;             } else {
;             PG8_LDB(B0, 0, 0); PG8_SCHED; PG8_LDA(At, 0, 0); PG8_STAGE(PG8_SA(1, 1), a1 + hstepA, voffA);
;             PG8_WAIT_L(8); PG8_BAR; PG8_WAIT_L(0); PG8_MMA(0, 0, At, B0); PG8_BAR; PG8_SCHED;
;             PG8_LDB(B1, 0, 1); PG8_STAGE(PG8_SB(0, 0), b2, voffB);
;             PG8_BAR; PG8_WAIT_L(0); PG8_MMA(0, 1, At, B1); PG8_BAR;
;             PG8_LDA(At, 0, 1); PG8_STAGE(PG8_SA(0, 0), a2, voffA);
;             PG8_BAR; PG8_WAIT_L(0); PG8_MMA(1, 0, At, B0); PG8_BAR; PG8_SCHED;
;             PG8_STAGE(PG8_SB(0, 1), b2 + hstepB, voffB);
;             PG8_WAIT_V(6); PG8_BAR; PG8_MMA(1, 1, At, B1); PG8_BAR;
;             PG8_LDB(B0, 1, 0); PG8_SCHED; PG8_LDA(At, 1, 0); PG8_STAGE(PG8_SA(0, 1), a2 + hstepA, voffA);
;             PG8_WAIT_L(8); PG8_BAR; PG8_WAIT_L(0); PG8_MMA(0, 0, At, B0); PG8_BAR; PG8_SCHED;
;             PG8_LDB(B1, 1, 1); PG8_STAGE(PG8_SB(1, 0), b3, voffB);
;             PG8_BAR; PG8_WAIT_L(0); PG8_MMA(0, 1, At, B1); PG8_BAR;
;             PG8_LDA(At, 1, 1); PG8_STAGE(PG8_SA(1, 0), a3, voffA);
;             PG8_BAR; PG8_WAIT_L(0); PG8_MMA(1, 0, At, B0); PG8_BAR; PG8_SCHED;
;             PG8_STAGE(PG8_SB(1, 1), b3 + hstepB, voffB);
;             PG8_WAIT_V(6); PG8_BAR; PG8_MMA(1, 1, At, B1); PG8_BAR;
;             }
;         }
;         if constexpr (ALIGN_EPI) { if (wr == 0) PG8_BAR; }
;         if constexpr (!Epi::AFTER_DRAIN) { E(acc, cur, wr, wc, fr, fq); S.done(cur); }
;         if (!has_next) break;
;         bool zero_acc = true; if constexpr (Epi::CHAIN) zero_acc = Epi::last_of_chain(cur);
;         if (zero_acc) {
; #pragma unroll
;         for (int a = 0; a < 2; ++a)
; #pragma unroll
;             for (int b = 0; b < 2; ++b)
; #pragma unroll
;                 for (int m = 0; m < 4; ++m)
; #pragma unroll
;                     for (int n = 0; n < 2; ++n) acc[a][b][m][n] = (f32x4){0.f, 0.f, 0.f, 0.f};
;         }
;         cur = nxt; cA = nA; cB = nB; ++ui;
	v_mfma_f32_16x16x32_bf16 v[50:53], v[134:137], v[170:173], v[50:53]
	v_mfma_f32_16x16x32_bf16 v[30:33], v[142:145], v[170:173], v[30:33]
	v_mfma_f32_16x16x32_bf16 v[58:61], v[142:145], v[178:181], v[58:61]
	v_mfma_f32_16x16x32_bf16 v[62:65], v[134:137], v[178:181], v[62:65]
	v_mfma_f32_16x16x32_bf16 v[94:97], v[134:137], v[186:189], v[94:97]
	v_mfma_f32_16x16x32_bf16 v[82:85], v[142:145], v[186:189], v[82:85]
	v_mfma_f32_16x16x32_bf16 v[26:29], v[142:145], v[200:203], v[26:29]
	v_mfma_f32_16x16x32_bf16 v[46:49], v[134:137], v[200:203], v[46:49]
	v_mfma_f32_16x16x32_bf16 v[50:53], v[138:141], v[174:177], v[50:53]
	v_mfma_f32_16x16x32_bf16 v[30:33], v[146:149], v[174:177], v[30:33]
	v_mfma_f32_16x16x32_bf16 v[58:61], v[146:149], v[182:185], v[58:61]
	v_mfma_f32_16x16x32_bf16 v[62:65], v[138:141], v[182:185], v[62:65]
	v_mfma_f32_16x16x32_bf16 v[94:97], v[138:141], v[190:193], v[94:97]
	v_mfma_f32_16x16x32_bf16 v[82:85], v[146:149], v[190:193], v[82:85]
	v_mfma_f32_16x16x32_bf16 v[26:29], v[146:149], v[206:209], v[26:29]
	v_mfma_f32_16x16x32_bf16 v[46:49], v[138:141], v[206:209], v[46:49]
	v_mfma_f32_16x16x32_bf16 v[22:25], v[150:153], v[170:173], v[22:25]
	v_mfma_f32_16x16x32_bf16 v[10:13], v[158:161], v[170:173], v[10:13]
	v_mfma_f32_16x16x32_bf16 v[66:69], v[158:161], v[178:181], v[66:69]
	v_mfma_f32_16x16x32_bf16 v[54:57], v[150:153], v[178:181], v[54:57]
	v_mfma_f32_16x16x32_bf16 v[70:73], v[150:153], v[186:189], v[70:73]
	v_mfma_f32_16x16x32_bf16 v[42:45], v[158:161], v[186:189], v[42:45]
	v_mfma_f32_16x16x32_bf16 v[2:5], v[158:161], v[200:203], v[2:5]
	v_mfma_f32_16x16x32_bf16 v[6:9], v[150:153], v[200:203], v[6:9]
	v_mfma_f32_16x16x32_bf16 v[22:25], v[154:157], v[174:177], v[22:25]
	v_mfma_f32_16x16x32_bf16 v[10:13], v[166:169], v[174:177], v[10:13]
	v_mfma_f32_16x16x32_bf16 v[66:69], v[166:169], v[182:185], v[66:69]
	v_mfma_f32_16x16x32_bf16 v[54:57], v[154:157], v[182:185], v[54:57]
	v_mfma_f32_16x16x32_bf16 v[70:73], v[154:157], v[190:193], v[70:73]
	v_mfma_f32_16x16x32_bf16 v[42:45], v[166:169], v[190:193], v[42:45]
	v_mfma_f32_16x16x32_bf16 v[2:5], v[166:169], v[206:209], v[2:5]
	v_mfma_f32_16x16x32_bf16 v[6:9], v[154:157], v[206:209], v[6:9]
	s_barrier
	s_setprio 0
	s_add_i32 s19, s19, 2
	s_add_u32 s44, s44, 0x100
	s_addc_u32 s45, s45, 0
	s_cmp_gt_u32 s19, 29
	s_cbranch_scc0 .LBB0_1265
	s_andn2_b64 vcc, exec, s[38:39]
	s_cbranch_vccnz .LBB0_1257
	v_mov_b32_e32 v2, 0
	s_mov_b64 s[12:13], s[24:25]
	s_mov_b32 s10, s16
	s_mov_b32 s48, s20
	s_mov_b64 s[14:15], s[22:23]
	s_mov_b32 s13, s78
	v_mov_b32_e32 v3, v2
	v_mov_b32_e32 v4, v2
	v_mov_b32_e32 v5, v2
	v_mov_b32_e32 v6, v2
	v_mov_b32_e32 v7, v2
	v_mov_b32_e32 v8, v2
	v_mov_b32_e32 v9, v2
	v_mov_b32_e32 v42, v2
	v_mov_b32_e32 v43, v2
	v_mov_b32_e32 v44, v2
	v_mov_b32_e32 v45, v2
	v_mov_b32_e32 v70, v2
	v_mov_b32_e32 v71, v2
	v_mov_b32_e32 v72, v2
	v_mov_b32_e32 v73, v2
	v_mov_b32_e32 v66, v2
	v_mov_b32_e32 v67, v2
	v_mov_b32_e32 v68, v2
	v_mov_b32_e32 v69, v2
	v_mov_b32_e32 v54, v2
	v_mov_b32_e32 v55, v2
	v_mov_b32_e32 v56, v2
	v_mov_b32_e32 v57, v2
	v_mov_b32_e32 v10, v2
	v_mov_b32_e32 v11, v2
	v_mov_b32_e32 v12, v2
	v_mov_b32_e32 v13, v2
	v_mov_b32_e32 v22, v2
	v_mov_b32_e32 v23, v2
	v_mov_b32_e32 v24, v2
	v_mov_b32_e32 v25, v2
	v_mov_b32_e32 v26, v2
	v_mov_b32_e32 v27, v2
	v_mov_b32_e32 v28, v2
	v_mov_b32_e32 v29, v2
	v_mov_b32_e32 v46, v2
	v_mov_b32_e32 v47, v2
	v_mov_b32_e32 v48, v2
	v_mov_b32_e32 v49, v2
	v_mov_b32_e32 v82, v2
	v_mov_b32_e32 v83, v2
	v_mov_b32_e32 v84, v2
	v_mov_b32_e32 v85, v2
	v_mov_b32_e32 v94, v2
	v_mov_b32_e32 v95, v2
	v_mov_b32_e32 v96, v2
	v_mov_b32_e32 v97, v2
	v_mov_b32_e32 v58, v2
	v_mov_b32_e32 v59, v2
	v_mov_b32_e32 v60, v2
	v_mov_b32_e32 v61, v2
	v_mov_b32_e32 v62, v2
	v_mov_b32_e32 v63, v2
	v_mov_b32_e32 v64, v2
	v_mov_b32_e32 v65, v2
	v_mov_b32_e32 v30, v2
	v_mov_b32_e32 v31, v2
	v_mov_b32_e32 v32, v2
	v_mov_b32_e32 v33, v2
	v_mov_b32_e32 v50, v2
	v_mov_b32_e32 v51, v2
	v_mov_b32_e32 v52, v2
	v_mov_b32_e32 v53, v2
	v_mov_b32_e32 v114, v2
	v_mov_b32_e32 v115, v2
	v_mov_b32_e32 v116, v2
	v_mov_b32_e32 v117, v2
	v_mov_b32_e32 v118, v2
	v_mov_b32_e32 v119, v2
	v_mov_b32_e32 v120, v2
	v_mov_b32_e32 v121, v2
	v_mov_b32_e32 v110, v2
	v_mov_b32_e32 v111, v2
	v_mov_b32_e32 v112, v2
	v_mov_b32_e32 v113, v2
	v_mov_b32_e32 v98, v2
	v_mov_b32_e32 v99, v2
	v_mov_b32_e32 v100, v2
	v_mov_b32_e32 v101, v2
	v_mov_b32_e32 v90, v2
	v_mov_b32_e32 v91, v2
	v_mov_b32_e32 v92, v2
	v_mov_b32_e32 v93, v2
	v_mov_b32_e32 v74, v2
	v_mov_b32_e32 v75, v2
	v_mov_b32_e32 v76, v2
	v_mov_b32_e32 v77, v2
	v_mov_b32_e32 v38, v2
	v_mov_b32_e32 v39, v2
	v_mov_b32_e32 v40, v2
	v_mov_b32_e32 v41, v2
	v_mov_b32_e32 v14, v2
	v_mov_b32_e32 v15, v2
	v_mov_b32_e32 v16, v2
	v_mov_b32_e32 v17, v2
	v_mov_b32_e32 v122, v2
	v_mov_b32_e32 v123, v2
	v_mov_b32_e32 v124, v2
	v_mov_b32_e32 v125, v2
	v_mov_b32_e32 v126, v2
	v_mov_b32_e32 v127, v2
	v_mov_b32_e32 v128, v2
	v_mov_b32_e32 v129, v2
	v_mov_b32_e32 v102, v2
	v_mov_b32_e32 v103, v2
	v_mov_b32_e32 v104, v2
	v_mov_b32_e32 v105, v2
	v_mov_b32_e32 v106, v2
	v_mov_b32_e32 v107, v2
	v_mov_b32_e32 v108, v2
	v_mov_b32_e32 v109, v2
	v_mov_b32_e32 v78, v2
	v_mov_b32_e32 v79, v2
	v_mov_b32_e32 v80, v2
	v_mov_b32_e32 v81, v2
	v_mov_b32_e32 v86, v2
	v_mov_b32_e32 v87, v2
	v_mov_b32_e32 v88, v2
	v_mov_b32_e32 v89, v2
	v_mov_b32_e32 v18, v2
	v_mov_b32_e32 v19, v2
	v_mov_b32_e32 v20, v2
	v_mov_b32_e32 v21, v2
	v_mov_b32_e32 v34, v2
	v_mov_b32_e32 v35, v2
	v_mov_b32_e32 v36, v2
	v_mov_b32_e32 v37, v2
	s_branch .LBB0_1257

;     __host__ __device__ bool next(int i, Unit& u) const { const int t = i / 3, b = i - 3 * t; Unit v; if (!StaticOrder::next(t, v)) return false; u.pm = v.pm; u.pn = 8 * b + v.pn; return true; }
; #define PG8_STAGE(bufoff, gbase, voff) do { const int so_ = (int)(unsigned)((const char*)(gbase) - base_##voff); _Pragma("unroll") for (int _i = 0; _i < 2; ++_i) \
;         __builtin_amdgcn_raw_ptr_buffer_load_lds(rs_##voff, (PG8_LAS unsigned*)(lds + (bufoff) + ldsw + _i * 8192), 16, (int)(voff)[_i], so_, 0, 0); } while (0)
; #define PG8_LDA(dst, b, h) do { _Pragma("unroll") for (int m = 0; m < 4; ++m) _Pragma("unroll") for (int k = 0; k < 2; ++k) dst[m][k] = *(const PG8_LAS bf16x8*)(lds + PG8_SA(b, h) + aoff + m * 2048 + k * 1024); } while (0)
; #define PG8_WAIT_V(n) asm volatile("s_waitcnt vmcnt(" #n ")" ::: "memory")
; #define PG8_WAIT_L(n) asm volatile("s_waitcnt lgkmcnt(" #n ")" ::: "memory")
; #define PG8_BAR __builtin_amdgcn_s_barrier()
; template <class Epi, class Sched, bool ALIGN_EPI = false, bool SP2 = false>
; __device__ __forceinline__ void gemm_phase(PG8_LAS unsigned char* lds, const Gemm g, const Sched& S, const Epi& E, int tid_in) {
;     ...
;         const bool has_next = S.next(ui + 1, nxt);
;         const char* nA = has_next ? (const char*)g.A + (size_t)nxt.pm * tstepA + (g.grp ? (size_t)(nxt.pn / g.grp) * g.agrp : (size_t)0) : cA; const char* nB = has_next ? (const char*)g.Bt + (size_t)nxt.pn * tstepB : cB;
;         for (int t = 0; t < nt; t += 2) {
;             const bool last = (t == nt - 2);
;             const char* a1 = cA + (size_t)(t + 1) * kstep;
;             const char* a2 = last ? nA : cA + (size_t)(t + 2) * kstep; const char* b2 = last ? nB : cB + (size_t)(t + 2) * kstep;
;             const char* a3 = a2 + kstep; const char* b3 = b2 + kstep;
;             if (last && has_next) S.a_ready(nxt);
;             if constexpr (SP2) {
;             PG8_LDB(B0, 0, 0); PG8_LDB(B1, 0, 1); PG8_SCHED; PG8_LDA(At, 0, 0); PG8_STAGE(PG8_SA(1, 1), a1 + hstepA, voffA);
;             PG8_WAIT_V(8); PG8_WAIT_L(0); PG8_BAR; PG8_MMA(0, 0, At, B0); PG8_MMA(0, 1, At, B1); PG8_BAR; PG8_SCHED;
;             PG8_LDA(At, 0, 1); PG8_STAGE(PG8_SB(0, 0), b2, voffB); PG8_STAGE(PG8_SB(0, 1), b2 + hstepB, voffB); PG8_STAGE(PG8_SA(0, 0), a2, voffA);
;             PG8_WAIT_V(8); PG8_WAIT_L(0); PG8_BAR; PG8_MMA(1, 0, At, B0); PG8_MMA(1, 1, At, B1); PG8_BAR; PG8_SCHED;
.LBB0_1513:
	s_ashr_i32 s21, s20, 31
	s_lshl_b64 s[18:19], s[20:21], 20
	s_add_u32 s22, s4, s18
	s_addc_u32 s23, s9, s19
	s_and_b64 s[18:19], s[36:37], exec
	s_cselect_b32 s18, s22, s16
	s_ashr_i32 s15, s14, 31
	s_lshl_b64 s[24:25], s[14:15], 20
	s_add_u32 s24, s40, s24
	s_addc_u32 s25, s26, s25
	s_and_b64 s[42:43], s[36:37], exec
	s_cselect_b32 s15, s24, s38
	s_add_u32 s19, s38, 0x100
	v_mov_b32_e32 v2, 0
	s_addc_u32 s21, s39, 0
	s_mov_b32 s73, -2
	v_add_u32_e32 v141, 0x10000, v139
	ds_read_b128 v[130:133], v141
	ds_read_b128 v[142:145], v141 offset:1024
	ds_read_b128 v[146:149], v141 offset:2048
	ds_read_b128 v[150:153], v141 offset:3072
	v_add_u32_e32 v141, 0x14000, v139
	ds_read_b128 v[154:157], v141
	ds_read_b128 v[158:161], v141 offset:1024
	ds_read_b128 v[162:165], v141 offset:2048
	ds_read_b128 v[166:169], v141 offset:3072
	s_add_u32 s38, s16, 0x100
	s_addc_u32 s39, s17, 0
	s_sub_i32 s16, s16, s4
	s_add_i32 s16, s16, 0x80080
	s_sub_i32 s74, s16, 0x80000
	s_cmp_eq_u32 s73, 28
	s_cselect_b32 s17, s18, s38
	s_mov_b32 m0, s67
	ds_read_b128 v[170:173], v140
	ds_read_b128 v[174:177], v140 offset:1024
	ds_read_b128 v[178:181], v140 offset:2048
	ds_read_b128 v[182:185], v140 offset:3072
	ds_read_b128 v[186:189], v140 offset:4096
	ds_read_b128 v[190:193], v140 offset:5120
	ds_read_b128 v[200:203], v140 offset:6144
	ds_read_b128 v[206:209], v140 offset:7168
	s_mov_b32 m0, s62
	s_nop 0
	buffer_load_dwordx4 v135, s[4:7], s74 offen lds
	s_mov_b32 m0, s67
	s_nop 0
	buffer_load_dwordx4 v0, s[4:7], s16 offen lds
	s_mov_b32 m0, s68
	s_nop 0
	buffer_load_dwordx4 v135, s[4:7], s16 offen lds
	s_waitcnt vmcnt(8) lgkmcnt(0)
	s_setprio 1
	s_barrier
	v_mfma_f32_16x16x32_bf16 v[126:129], v[130:133], v[170:173], 0
	v_mfma_f32_16x16x32_bf16 v[122:125], v[146:149], v[170:173], 0
	v_mfma_f32_16x16x32_bf16 v[106:109], v[146:149], v[178:181], 0
	v_mfma_f32_16x16x32_bf16 v[110:113], v[130:133], v[178:181], 0
	v_mfma_f32_16x16x32_bf16 v[94:97], v[130:133], v[186:189], 0
	v_mfma_f32_16x16x32_bf16 v[90:93], v[146:149], v[186:189], 0
	v_mfma_f32_16x16x32_bf16 v[74:77], v[146:149], v[200:203], 0
	v_mfma_f32_16x16x32_bf16 v[78:81], v[130:133], v[200:203], 0
	v_mfma_f32_16x16x32_bf16 v[126:129], v[142:145], v[174:177], v[126:129]
	v_mfma_f32_16x16x32_bf16 v[122:125], v[150:153], v[174:177], v[122:125]
	v_mfma_f32_16x16x32_bf16 v[106:109], v[150:153], v[182:185], v[106:109]
	v_mfma_f32_16x16x32_bf16 v[110:113], v[142:145], v[182:185], v[110:113]
	v_mfma_f32_16x16x32_bf16 v[94:97], v[142:145], v[190:193], v[94:97]
	v_mfma_f32_16x16x32_bf16 v[90:93], v[150:153], v[190:193], v[90:93]
	v_mfma_f32_16x16x32_bf16 v[74:77], v[150:153], v[206:209], v[74:77]
	v_mfma_f32_16x16x32_bf16 v[78:81], v[142:145], v[206:209], v[78:81]
	v_mfma_f32_16x16x32_bf16 v[118:121], v[154:157], v[170:173], 0
	v_mfma_f32_16x16x32_bf16 v[114:117], v[162:165], v[170:173], 0
	v_mfma_f32_16x16x32_bf16 v[98:101], v[162:165], v[178:181], 0
	v_mfma_f32_16x16x32_bf16 v[102:105], v[154:157], v[178:181], 0
	v_mfma_f32_16x16x32_bf16 v[86:89], v[154:157], v[186:189], 0
	v_mfma_f32_16x16x32_bf16 v[82:85], v[162:165], v[186:189], 0
	v_mfma_f32_16x16x32_bf16 v[66:69], v[162:165], v[200:203], 0
	v_mfma_f32_16x16x32_bf16 v[70:73], v[154:157], v[200:203], 0
	v_mfma_f32_16x16x32_bf16 v[118:121], v[158:161], v[174:177], v[118:121]
	v_mfma_f32_16x16x32_bf16 v[114:117], v[166:169], v[174:177], v[114:117]
	v_mfma_f32_16x16x32_bf16 v[98:101], v[166:169], v[182:185], v[98:101]
	v_mfma_f32_16x16x32_bf16 v[102:105], v[158:161], v[182:185], v[102:105]
	v_mfma_f32_16x16x32_bf16 v[86:89], v[158:161], v[190:193], v[86:89]
	v_mfma_f32_16x16x32_bf16 v[82:85], v[166:169], v[190:193], v[82:85]
	v_mfma_f32_16x16x32_bf16 v[66:69], v[166:169], v[206:209], v[66:69]
	v_mfma_f32_16x16x32_bf16 v[70:73], v[158:161], v[206:209], v[70:73]
	s_barrier
	s_setprio 0
	s_cselect_b32 s16, s15, s19
	s_mov_b32 m0, s35
	s_mov_b32 s42, s6
	s_mov_b32 s43, s7
	s_sub_i32 s16, s16, s40
	ds_read_b128 v[170:173], v140 offset:16384
	ds_read_b128 v[174:177], v140 offset:17408
	ds_read_b128 v[178:181], v140 offset:18432
	ds_read_b128 v[182:185], v140 offset:19456
	ds_read_b128 v[186:189], v140 offset:20480
	ds_read_b128 v[190:193], v140 offset:21504
	ds_read_b128 v[200:203], v140 offset:22528
	ds_read_b128 v[206:209], v140 offset:23552
	buffer_load_dwordx4 v134, s[40:43], s16 offen lds
	s_mov_b32 m0, s44
	s_add_i32 s74, s16, 0x80000
	buffer_load_dwordx4 v136, s[40:43], s16 offen lds
	s_mov_b32 m0, s45
	s_sub_i32 s17, s17, s4
	buffer_load_dwordx4 v134, s[40:43], s74 offen lds
	s_mov_b32 m0, s46
	s_nop 0
	buffer_load_dwordx4 v136, s[40:43], s74 offen lds
	s_mov_b32 m0, s34
	s_nop 0
	buffer_load_dwordx4 v0, s[4:7], s17 offen lds
	s_waitcnt vmcnt(7) lgkmcnt(0)
	s_setprio 1
	s_barrier
; #define PG8_STAGE(bufoff, gbase, voff) do { const int so_ = (int)(unsigned)((const char*)(gbase) - base_##voff); _Pragma("unroll") for (int _i = 0; _i < 2; ++_i) \
;         __builtin_amdgcn_raw_ptr_buffer_load_lds(rs_##voff, (PG8_LAS unsigned*)(lds + (bufoff) + ldsw + _i * 8192), 16, (int)(voff)[_i], so_, 0, 0); } while (0)
; #define PG8_LDA(dst, b, h) do { _Pragma("unroll") for (int m = 0; m < 4; ++m) _Pragma("unroll") for (int k = 0; k < 2; ++k) dst[m][k] = *(const PG8_LAS bf16x8*)(lds + PG8_SA(b, h) + aoff + m * 2048 + k * 1024); } while (0)
; #define PG8_LDB(dst, b, h) do { _Pragma("unroll") for (int n = 0; n < 2; ++n) _Pragma("unroll") for (int k = 0; k < 2; ++k) dst[n][k] = *(const PG8_LAS bf16x8*)(lds + PG8_SB(b, h) + boff + n * 2048 + k * 1024); } while (0)
; #define PG8_MMA(ai, bj, At, Bt) do { __builtin_amdgcn_s_setprio(1); _Pragma("unroll") for (int m = 0; m < 4; ++m) _Pragma("unroll") for (int n = 0; n < 2; ++n) _Pragma("unroll") for (int k = 0; k < 2; ++k) \
;         acc[ai][bj][m][n] = __builtin_amdgcn_mfma_f32_16x16x32_bf16(Bt[n][k], At[m][k], acc[ai][bj][m][n], 0, 0, 0); __builtin_amdgcn_s_setprio(0); } while (0)
; #define PG8_WAIT_V(n) asm volatile("s_waitcnt vmcnt(" #n ")" ::: "memory")
; #define PG8_WAIT_L(n) asm volatile("s_waitcnt lgkmcnt(" #n ")" ::: "memory")
; #define PG8_BAR __builtin_amdgcn_s_barrier()
; #define PG8_SCHED __builtin_amdgcn_sched_barrier(0)
; template <class Epi, class Sched, bool ALIGN_EPI = false, bool SP2 = false>
; __device__ __forceinline__ void gemm_phase(PG8_LAS unsigned char* lds, const Gemm g, const Sched& S, const Epi& E, int tid_in) {
;     ...
;             PG8_WAIT_V(8); PG8_WAIT_L(0); PG8_BAR; PG8_MMA(0, 0, At, B0); PG8_MMA(0, 1, At, B1); PG8_BAR; PG8_SCHED;
;             PG8_LDA(At, 0, 1); PG8_STAGE(PG8_SB(0, 0), b2, voffB); PG8_STAGE(PG8_SB(0, 1), b2 + hstepB, voffB); PG8_STAGE(PG8_SA(0, 0), a2, voffA);
;             PG8_WAIT_V(8); PG8_WAIT_L(0); PG8_BAR; PG8_MMA(1, 0, At, B0); PG8_MMA(1, 1, At, B1); PG8_BAR; PG8_SCHED;
;             PG8_LDB(B0, 1, 0); PG8_LDB(B1, 1, 1); PG8_SCHED; PG8_LDA(At, 1, 0); PG8_STAGE(PG8_SA(0, 1), a2 + hstepA, voffA);
;             PG8_WAIT_V(8); PG8_WAIT_L(0); PG8_BAR; PG8_MMA(0, 0, At, B0); PG8_MMA(0, 1, At, B1); PG8_BAR; PG8_SCHED;
	v_mfma_f32_16x16x32_bf16 v[62:65], v[130:133], v[170:173], 0
	v_mfma_f32_16x16x32_bf16 v[58:61], v[146:149], v[170:173], 0
	v_mfma_f32_16x16x32_bf16 v[42:45], v[146:149], v[178:181], 0
	v_mfma_f32_16x16x32_bf16 v[46:49], v[130:133], v[178:181], 0
	v_mfma_f32_16x16x32_bf16 v[30:33], v[130:133], v[186:189], 0
	v_mfma_f32_16x16x32_bf16 v[26:29], v[146:149], v[186:189], 0
	v_mfma_f32_16x16x32_bf16 v[10:13], v[146:149], v[200:203], 0
	v_mfma_f32_16x16x32_bf16 v[14:17], v[130:133], v[200:203], 0
	v_mfma_f32_16x16x32_bf16 v[62:65], v[142:145], v[174:177], v[62:65]
	v_mfma_f32_16x16x32_bf16 v[58:61], v[150:153], v[174:177], v[58:61]
	v_mfma_f32_16x16x32_bf16 v[42:45], v[150:153], v[182:185], v[42:45]
	v_mfma_f32_16x16x32_bf16 v[46:49], v[142:145], v[182:185], v[46:49]
	v_mfma_f32_16x16x32_bf16 v[30:33], v[142:145], v[190:193], v[30:33]
	v_mfma_f32_16x16x32_bf16 v[26:29], v[150:153], v[190:193], v[26:29]
	v_mfma_f32_16x16x32_bf16 v[10:13], v[150:153], v[206:209], v[10:13]
	v_mfma_f32_16x16x32_bf16 v[14:17], v[142:145], v[206:209], v[14:17]
	v_mfma_f32_16x16x32_bf16 v[54:57], v[154:157], v[170:173], 0
	v_mfma_f32_16x16x32_bf16 v[50:53], v[162:165], v[170:173], 0
	v_mfma_f32_16x16x32_bf16 v[34:37], v[162:165], v[178:181], 0
	v_mfma_f32_16x16x32_bf16 v[38:41], v[154:157], v[178:181], 0
	v_mfma_f32_16x16x32_bf16 v[22:25], v[154:157], v[186:189], 0
	v_mfma_f32_16x16x32_bf16 v[18:21], v[162:165], v[186:189], 0
	v_mfma_f32_16x16x32_bf16 v[2:5], v[162:165], v[200:203], 0
	v_mfma_f32_16x16x32_bf16 v[6:9], v[154:157], v[200:203], 0
	v_mfma_f32_16x16x32_bf16 v[54:57], v[158:161], v[174:177], v[54:57]
	v_mfma_f32_16x16x32_bf16 v[50:53], v[166:169], v[174:177], v[50:53]
	v_mfma_f32_16x16x32_bf16 v[34:37], v[166:169], v[182:185], v[34:37]
	v_mfma_f32_16x16x32_bf16 v[38:41], v[158:161], v[182:185], v[38:41]
	v_mfma_f32_16x16x32_bf16 v[22:25], v[158:161], v[190:193], v[22:25]
	v_mfma_f32_16x16x32_bf16 v[18:21], v[166:169], v[190:193], v[18:21]
	v_mfma_f32_16x16x32_bf16 v[2:5], v[166:169], v[206:209], v[2:5]
	v_mfma_f32_16x16x32_bf16 v[6:9], v[158:161], v[206:209], v[6:9]
	s_barrier
	s_setprio 0
	v_add_u32_e32 v141, 0x18000, v139
	ds_read_b128 v[130:133], v141
	ds_read_b128 v[142:145], v141 offset:1024
	ds_read_b128 v[146:149], v141 offset:2048
	ds_read_b128 v[150:153], v141 offset:3072
	v_add_u32_e32 v141, 0x1c000, v139
	ds_read_b128 v[154:157], v141
	ds_read_b128 v[158:161], v141 offset:1024
	ds_read_b128 v[162:165], v141 offset:2048
	ds_read_b128 v[166:169], v141 offset:3072
	s_add_i32 s74, s17, 0x80000
	s_mov_b32 m0, s48
	ds_read_b128 v[170:173], v140 offset:32768
	ds_read_b128 v[174:177], v140 offset:33792
	ds_read_b128 v[178:181], v140 offset:34816
	ds_read_b128 v[182:185], v140 offset:35840
	ds_read_b128 v[186:189], v140 offset:36864
	ds_read_b128 v[190:193], v140 offset:37888
	ds_read_b128 v[200:203], v140 offset:38912
	ds_read_b128 v[206:209], v140 offset:39936
	s_mov_b32 m0, s47
	s_nop 0
	buffer_load_dwordx4 v135, s[4:7], s17 offen lds
	s_mov_b32 m0, s48
	s_nop 0
	buffer_load_dwordx4 v0, s[4:7], s74 offen lds
	s_mov_b32 m0, s49
	s_nop 0
	buffer_load_dwordx4 v135, s[4:7], s74 offen lds
	s_waitcnt vmcnt(8) lgkmcnt(0)
	s_setprio 1
	s_barrier
	v_mfma_f32_16x16x32_bf16 v[126:129], v[130:133], v[170:173], v[126:129]
	v_mfma_f32_16x16x32_bf16 v[122:125], v[146:149], v[170:173], v[122:125]
	v_mfma_f32_16x16x32_bf16 v[106:109], v[146:149], v[178:181], v[106:109]
	v_mfma_f32_16x16x32_bf16 v[110:113], v[130:133], v[178:181], v[110:113]
	v_mfma_f32_16x16x32_bf16 v[94:97], v[130:133], v[186:189], v[94:97]
	v_mfma_f32_16x16x32_bf16 v[90:93], v[146:149], v[186:189], v[90:93]
	v_mfma_f32_16x16x32_bf16 v[74:77], v[146:149], v[200:203], v[74:77]
	v_mfma_f32_16x16x32_bf16 v[78:81], v[130:133], v[200:203], v[78:81]
	v_mfma_f32_16x16x32_bf16 v[126:129], v[142:145], v[174:177], v[126:129]
	v_mfma_f32_16x16x32_bf16 v[122:125], v[150:153], v[174:177], v[122:125]
	v_mfma_f32_16x16x32_bf16 v[106:109], v[150:153], v[182:185], v[106:109]
	v_mfma_f32_16x16x32_bf16 v[110:113], v[142:145], v[182:185], v[110:113]
	v_mfma_f32_16x16x32_bf16 v[94:97], v[142:145], v[190:193], v[94:97]
	v_mfma_f32_16x16x32_bf16 v[90:93], v[150:153], v[190:193], v[90:93]
	v_mfma_f32_16x16x32_bf16 v[74:77], v[150:153], v[206:209], v[74:77]
	v_mfma_f32_16x16x32_bf16 v[78:81], v[142:145], v[206:209], v[78:81]
	v_mfma_f32_16x16x32_bf16 v[118:121], v[154:157], v[170:173], v[118:121]
	v_mfma_f32_16x16x32_bf16 v[114:117], v[162:165], v[170:173], v[114:117]
	v_mfma_f32_16x16x32_bf16 v[98:101], v[162:165], v[178:181], v[98:101]
	v_mfma_f32_16x16x32_bf16 v[102:105], v[154:157], v[178:181], v[102:105]
	v_mfma_f32_16x16x32_bf16 v[86:89], v[154:157], v[186:189], v[86:89]
	v_mfma_f32_16x16x32_bf16 v[82:85], v[162:165], v[186:189], v[82:85]
	v_mfma_f32_16x16x32_bf16 v[66:69], v[162:165], v[200:203], v[66:69]
	v_mfma_f32_16x16x32_bf16 v[70:73], v[154:157], v[200:203], v[70:73]
	v_mfma_f32_16x16x32_bf16 v[118:121], v[158:161], v[174:177], v[118:121]
	v_mfma_f32_16x16x32_bf16 v[114:117], v[166:169], v[174:177], v[114:117]
	v_mfma_f32_16x16x32_bf16 v[98:101], v[166:169], v[182:185], v[98:101]
	v_mfma_f32_16x16x32_bf16 v[102:105], v[158:161], v[182:185], v[102:105]
	v_mfma_f32_16x16x32_bf16 v[86:89], v[158:161], v[190:193], v[86:89]
	v_mfma_f32_16x16x32_bf16 v[82:85], v[166:169], v[190:193], v[82:85]
	v_mfma_f32_16x16x32_bf16 v[66:69], v[166:169], v[206:209], v[66:69]
	v_mfma_f32_16x16x32_bf16 v[70:73], v[158:161], v[206:209], v[70:73]
	s_barrier
; #define PG8_STAGE(bufoff, gbase, voff) do { const int so_ = (int)(unsigned)((const char*)(gbase) - base_##voff); _Pragma("unroll") for (int _i = 0; _i < 2; ++_i) \
;         __builtin_amdgcn_raw_ptr_buffer_load_lds(rs_##voff, (PG8_LAS unsigned*)(lds + (bufoff) + ldsw + _i * 8192), 16, (int)(voff)[_i], so_, 0, 0); } while (0)
; #define PG8_LDA(dst, b, h) do { _Pragma("unroll") for (int m = 0; m < 4; ++m) _Pragma("unroll") for (int k = 0; k < 2; ++k) dst[m][k] = *(const PG8_LAS bf16x8*)(lds + PG8_SA(b, h) + aoff + m * 2048 + k * 1024); } while (0)
; #define PG8_LDB(dst, b, h) do { _Pragma("unroll") for (int n = 0; n < 2; ++n) _Pragma("unroll") for (int k = 0; k < 2; ++k) dst[n][k] = *(const PG8_LAS bf16x8*)(lds + PG8_SB(b, h) + boff + n * 2048 + k * 1024); } while (0)
; #define PG8_MMA(ai, bj, At, Bt) do { __builtin_amdgcn_s_setprio(1); _Pragma("unroll") for (int m = 0; m < 4; ++m) _Pragma("unroll") for (int n = 0; n < 2; ++n) _Pragma("unroll") for (int k = 0; k < 2; ++k) \
;         acc[ai][bj][m][n] = __builtin_amdgcn_mfma_f32_16x16x32_bf16(Bt[n][k], At[m][k], acc[ai][bj][m][n], 0, 0, 0); __builtin_amdgcn_s_setprio(0); } while (0)
; template <class Epi, class Sched, bool ALIGN_EPI = false, bool SP2 = false>
; __device__ __forceinline__ void gemm_phase(PG8_LAS unsigned char* lds, const Gemm g, const Sched& S, const Epi& E, int tid_in) {
;     ...
;             PG8_LDB(B0, 0, 0); PG8_LDB(B1, 0, 1); PG8_SCHED; PG8_LDA(At, 0, 0); PG8_STAGE(PG8_SA(1, 1), a1 + hstepA, voffA);
;             PG8_WAIT_V(8); PG8_WAIT_L(0); PG8_BAR; PG8_MMA(0, 0, At, B0); PG8_MMA(0, 1, At, B1); PG8_BAR; PG8_SCHED;
;             PG8_LDA(At, 0, 1); PG8_STAGE(PG8_SB(0, 0), b2, voffB); PG8_STAGE(PG8_SB(0, 1), b2 + hstepB, voffB); PG8_STAGE(PG8_SA(0, 0), a2, voffA);
;             PG8_WAIT_V(8); PG8_WAIT_L(0); PG8_BAR; PG8_MMA(1, 0, At, B0); PG8_MMA(1, 1, At, B1); PG8_BAR; PG8_SCHED;
;             PG8_LDB(B0, 1, 0); PG8_LDB(B1, 1, 1); PG8_SCHED; PG8_LDA(At, 1, 0); PG8_STAGE(PG8_SA(0, 1), a2 + hstepA, voffA);
;             PG8_WAIT_V(8); PG8_WAIT_L(0); PG8_BAR; PG8_MMA(0, 0, At, B0); PG8_MMA(0, 1, At, B1); PG8_BAR; PG8_SCHED;
;             PG8_LDA(At, 1, 1); PG8_STAGE(PG8_SB(1, 0), b3, voffB); PG8_STAGE(PG8_SB(1, 1), b3 + hstepB, voffB); PG8_STAGE(PG8_SA(1, 0), a3, voffA);
;             PG8_WAIT_V(8); PG8_WAIT_L(0); PG8_BAR; PG8_MMA(1, 0, At, B0); PG8_MMA(1, 1, At, B1); PG8_BAR; PG8_SCHED;
	s_setprio 0
	s_mov_b32 m0, s53
	s_add_i32 s74, s16, 0x80
	ds_read_b128 v[170:173], v140 offset:49152
	ds_read_b128 v[174:177], v140 offset:50176
	ds_read_b128 v[178:181], v140 offset:51200
	ds_read_b128 v[182:185], v140 offset:52224
	ds_read_b128 v[186:189], v140 offset:53248
	ds_read_b128 v[190:193], v140 offset:54272
	ds_read_b128 v[200:203], v140 offset:55296
	ds_read_b128 v[206:209], v140 offset:56320
	buffer_load_dwordx4 v134, s[40:43], s74 offen lds
	s_mov_b32 m0, s60
	s_add_i32 s16, s16, 0x80080
	buffer_load_dwordx4 v136, s[40:43], s74 offen lds
	s_mov_b32 m0, s63
	s_addk_i32 s17, 0x80
	buffer_load_dwordx4 v134, s[40:43], s16 offen lds
	s_mov_b32 m0, s66
	s_nop 0
	buffer_load_dwordx4 v136, s[40:43], s16 offen lds
	s_mov_b32 m0, s61
	s_nop 0
	buffer_load_dwordx4 v0, s[4:7], s17 offen lds
	s_waitcnt vmcnt(7) lgkmcnt(0)
	s_setprio 1
	s_barrier
	v_mfma_f32_16x16x32_bf16 v[62:65], v[130:133], v[170:173], v[62:65]
	v_mfma_f32_16x16x32_bf16 v[58:61], v[146:149], v[170:173], v[58:61]
	v_mfma_f32_16x16x32_bf16 v[42:45], v[146:149], v[178:181], v[42:45]
	v_mfma_f32_16x16x32_bf16 v[46:49], v[130:133], v[178:181], v[46:49]
	v_mfma_f32_16x16x32_bf16 v[30:33], v[130:133], v[186:189], v[30:33]
	v_mfma_f32_16x16x32_bf16 v[26:29], v[146:149], v[186:189], v[26:29]
	v_mfma_f32_16x16x32_bf16 v[10:13], v[146:149], v[200:203], v[10:13]
	v_mfma_f32_16x16x32_bf16 v[14:17], v[130:133], v[200:203], v[14:17]
	v_mfma_f32_16x16x32_bf16 v[62:65], v[142:145], v[174:177], v[62:65]
	v_mfma_f32_16x16x32_bf16 v[58:61], v[150:153], v[174:177], v[58:61]
	v_mfma_f32_16x16x32_bf16 v[42:45], v[150:153], v[182:185], v[42:45]
	v_mfma_f32_16x16x32_bf16 v[46:49], v[142:145], v[182:185], v[46:49]
	v_mfma_f32_16x16x32_bf16 v[30:33], v[142:145], v[190:193], v[30:33]
	v_mfma_f32_16x16x32_bf16 v[26:29], v[150:153], v[190:193], v[26:29]
	v_mfma_f32_16x16x32_bf16 v[10:13], v[150:153], v[206:209], v[10:13]
	v_mfma_f32_16x16x32_bf16 v[14:17], v[142:145], v[206:209], v[14:17]
	v_mfma_f32_16x16x32_bf16 v[54:57], v[154:157], v[170:173], v[54:57]
	v_mfma_f32_16x16x32_bf16 v[50:53], v[162:165], v[170:173], v[50:53]
	v_mfma_f32_16x16x32_bf16 v[34:37], v[162:165], v[178:181], v[34:37]
	v_mfma_f32_16x16x32_bf16 v[38:41], v[154:157], v[178:181], v[38:41]
	v_mfma_f32_16x16x32_bf16 v[22:25], v[154:157], v[186:189], v[22:25]
	v_mfma_f32_16x16x32_bf16 v[18:21], v[162:165], v[186:189], v[18:21]
	v_mfma_f32_16x16x32_bf16 v[2:5], v[162:165], v[200:203], v[2:5]
	v_mfma_f32_16x16x32_bf16 v[6:9], v[154:157], v[200:203], v[6:9]
	v_mfma_f32_16x16x32_bf16 v[54:57], v[158:161], v[174:177], v[54:57]
	v_mfma_f32_16x16x32_bf16 v[50:53], v[166:169], v[174:177], v[50:53]
	v_mfma_f32_16x16x32_bf16 v[34:37], v[166:169], v[182:185], v[34:37]
	v_mfma_f32_16x16x32_bf16 v[38:41], v[158:161], v[182:185], v[38:41]
	v_mfma_f32_16x16x32_bf16 v[22:25], v[158:161], v[190:193], v[22:25]
	v_mfma_f32_16x16x32_bf16 v[18:21], v[166:169], v[190:193], v[18:21]
	v_mfma_f32_16x16x32_bf16 v[2:5], v[166:169], v[206:209], v[2:5]
	v_mfma_f32_16x16x32_bf16 v[6:9], v[158:161], v[206:209], v[6:9]
	s_barrier
	s_setprio 0
	s_add_i32 s73, s73, 2
	s_add_u32 s19, s19, 0x100
	s_addc_u32 s21, s21, 0
	s_cmp_gt_u32 s73, 29
	s_mov_b64 s[16:17], s[38:39]
.LBB0_1514:
	v_add_u32_e32 v141, 0x10000, v139
	ds_read_b128 v[130:133], v141
	ds_read_b128 v[142:145], v141 offset:1024
	ds_read_b128 v[146:149], v141 offset:2048
	ds_read_b128 v[150:153], v141 offset:3072
	v_add_u32_e32 v141, 0x14000, v139
	ds_read_b128 v[154:157], v141
	ds_read_b128 v[158:161], v141 offset:1024
	ds_read_b128 v[162:165], v141 offset:2048
	ds_read_b128 v[166:169], v141 offset:3072
	s_add_u32 s38, s16, 0x100
	s_addc_u32 s39, s17, 0
	s_sub_i32 s16, s16, s4
	s_add_i32 s16, s16, 0x80080
	s_sub_i32 s74, s16, 0x80000
	s_cmp_eq_u32 s73, 28
	s_cselect_b32 s17, s18, s38
	s_mov_b32 m0, s67
	ds_read_b128 v[170:173], v140
	ds_read_b128 v[174:177], v140 offset:1024
	ds_read_b128 v[178:181], v140 offset:2048
	ds_read_b128 v[182:185], v140 offset:3072
	ds_read_b128 v[186:189], v140 offset:4096
	ds_read_b128 v[190:193], v140 offset:5120
	ds_read_b128 v[200:203], v140 offset:6144
	ds_read_b128 v[206:209], v140 offset:7168
	s_mov_b32 m0, s62
	s_nop 0
	buffer_load_dwordx4 v135, s[4:7], s74 offen lds
	s_mov_b32 m0, s67
	s_nop 0
	buffer_load_dwordx4 v0, s[4:7], s16 offen lds
	s_mov_b32 m0, s68
	s_nop 0
	buffer_load_dwordx4 v135, s[4:7], s16 offen lds
	s_waitcnt vmcnt(8) lgkmcnt(0)
	s_setprio 1
	s_barrier
	v_mfma_f32_16x16x32_bf16 v[126:129], v[130:133], v[170:173], v[126:129]
	v_mfma_f32_16x16x32_bf16 v[122:125], v[146:149], v[170:173], v[122:125]
	v_mfma_f32_16x16x32_bf16 v[106:109], v[146:149], v[178:181], v[106:109]
	v_mfma_f32_16x16x32_bf16 v[110:113], v[130:133], v[178:181], v[110:113]
	v_mfma_f32_16x16x32_bf16 v[94:97], v[130:133], v[186:189], v[94:97]
	v_mfma_f32_16x16x32_bf16 v[90:93], v[146:149], v[186:189], v[90:93]
	v_mfma_f32_16x16x32_bf16 v[74:77], v[146:149], v[200:203], v[74:77]
	v_mfma_f32_16x16x32_bf16 v[78:81], v[130:133], v[200:203], v[78:81]
	v_mfma_f32_16x16x32_bf16 v[126:129], v[142:145], v[174:177], v[126:129]
	v_mfma_f32_16x16x32_bf16 v[122:125], v[150:153], v[174:177], v[122:125]
	v_mfma_f32_16x16x32_bf16 v[106:109], v[150:153], v[182:185], v[106:109]
	v_mfma_f32_16x16x32_bf16 v[110:113], v[142:145], v[182:185], v[110:113]
	v_mfma_f32_16x16x32_bf16 v[94:97], v[142:145], v[190:193], v[94:97]
	v_mfma_f32_16x16x32_bf16 v[90:93], v[150:153], v[190:193], v[90:93]
	v_mfma_f32_16x16x32_bf16 v[74:77], v[150:153], v[206:209], v[74:77]
	v_mfma_f32_16x16x32_bf16 v[78:81], v[142:145], v[206:209], v[78:81]
	v_mfma_f32_16x16x32_bf16 v[118:121], v[154:157], v[170:173], v[118:121]
	v_mfma_f32_16x16x32_bf16 v[114:117], v[162:165], v[170:173], v[114:117]
	v_mfma_f32_16x16x32_bf16 v[98:101], v[162:165], v[178:181], v[98:101]
	v_mfma_f32_16x16x32_bf16 v[102:105], v[154:157], v[178:181], v[102:105]
	v_mfma_f32_16x16x32_bf16 v[86:89], v[154:157], v[186:189], v[86:89]
	v_mfma_f32_16x16x32_bf16 v[82:85], v[162:165], v[186:189], v[82:85]
	v_mfma_f32_16x16x32_bf16 v[66:69], v[162:165], v[200:203], v[66:69]
	v_mfma_f32_16x16x32_bf16 v[70:73], v[154:157], v[200:203], v[70:73]
	v_mfma_f32_16x16x32_bf16 v[118:121], v[158:161], v[174:177], v[118:121]
	v_mfma_f32_16x16x32_bf16 v[114:117], v[166:169], v[174:177], v[114:117]
	v_mfma_f32_16x16x32_bf16 v[98:101], v[166:169], v[182:185], v[98:101]
	v_mfma_f32_16x16x32_bf16 v[102:105], v[158:161], v[182:185], v[102:105]
	v_mfma_f32_16x16x32_bf16 v[86:89], v[158:161], v[190:193], v[86:89]
	v_mfma_f32_16x16x32_bf16 v[82:85], v[166:169], v[190:193], v[82:85]
	v_mfma_f32_16x16x32_bf16 v[66:69], v[166:169], v[206:209], v[66:69]
	v_mfma_f32_16x16x32_bf16 v[70:73], v[158:161], v[206:209], v[70:73]
	s_barrier
; #define PG8_STAGE(bufoff, gbase, voff) do { const int so_ = (int)(unsigned)((const char*)(gbase) - base_##voff); _Pragma("unroll") for (int _i = 0; _i < 2; ++_i) \
;         __builtin_amdgcn_raw_ptr_buffer_load_lds(rs_##voff, (PG8_LAS unsigned*)(lds + (bufoff) + ldsw + _i * 8192), 16, (int)(voff)[_i], so_, 0, 0); } while (0)
; #define PG8_LDA(dst, b, h) do { _Pragma("unroll") for (int m = 0; m < 4; ++m) _Pragma("unroll") for (int k = 0; k < 2; ++k) dst[m][k] = *(const PG8_LAS bf16x8*)(lds + PG8_SA(b, h) + aoff + m * 2048 + k * 1024); } while (0)
; #define PG8_LDB(dst, b, h) do { _Pragma("unroll") for (int n = 0; n < 2; ++n) _Pragma("unroll") for (int k = 0; k < 2; ++k) dst[n][k] = *(const PG8_LAS bf16x8*)(lds + PG8_SB(b, h) + boff + n * 2048 + k * 1024); } while (0)
; #define PG8_MMA(ai, bj, At, Bt) do { __builtin_amdgcn_s_setprio(1); _Pragma("unroll") for (int m = 0; m < 4; ++m) _Pragma("unroll") for (int n = 0; n < 2; ++n) _Pragma("unroll") for (int k = 0; k < 2; ++k) \
;         acc[ai][bj][m][n] = __builtin_amdgcn_mfma_f32_16x16x32_bf16(Bt[n][k], At[m][k], acc[ai][bj][m][n], 0, 0, 0); __builtin_amdgcn_s_setprio(0); } while (0)
; #define PG8_WAIT_V(n) asm volatile("s_waitcnt vmcnt(" #n ")" ::: "memory")
; #define PG8_WAIT_L(n) asm volatile("s_waitcnt lgkmcnt(" #n ")" ::: "memory")
; #define PG8_BAR __builtin_amdgcn_s_barrier()
; #define PG8_SCHED __builtin_amdgcn_sched_barrier(0)
; template <class Epi, class Sched, bool ALIGN_EPI = false, bool SP2 = false>
; __device__ __forceinline__ void gemm_phase(PG8_LAS unsigned char* lds, const Gemm g, const Sched& S, const Epi& E, int tid_in) {
;     ...
;             PG8_WAIT_V(8); PG8_WAIT_L(0); PG8_BAR; PG8_MMA(0, 0, At, B0); PG8_MMA(0, 1, At, B1); PG8_BAR; PG8_SCHED;
;             PG8_LDA(At, 0, 1); PG8_STAGE(PG8_SB(0, 0), b2, voffB); PG8_STAGE(PG8_SB(0, 1), b2 + hstepB, voffB); PG8_STAGE(PG8_SA(0, 0), a2, voffA);
;             PG8_WAIT_V(8); PG8_WAIT_L(0); PG8_BAR; PG8_MMA(1, 0, At, B0); PG8_MMA(1, 1, At, B1); PG8_BAR; PG8_SCHED;
;             PG8_LDB(B0, 1, 0); PG8_LDB(B1, 1, 1); PG8_SCHED; PG8_LDA(At, 1, 0); PG8_STAGE(PG8_SA(0, 1), a2 + hstepA, voffA);
	s_setprio 0
	s_cselect_b32 s16, s15, s19
	s_mov_b32 m0, s35
	s_mov_b32 s42, s6
	s_mov_b32 s43, s7
	s_sub_i32 s16, s16, s40
	ds_read_b128 v[170:173], v140 offset:16384
	ds_read_b128 v[174:177], v140 offset:17408
	ds_read_b128 v[178:181], v140 offset:18432
	ds_read_b128 v[182:185], v140 offset:19456
	ds_read_b128 v[186:189], v140 offset:20480
	ds_read_b128 v[190:193], v140 offset:21504
	ds_read_b128 v[200:203], v140 offset:22528
	ds_read_b128 v[206:209], v140 offset:23552
	buffer_load_dwordx4 v134, s[40:43], s16 offen lds
	s_mov_b32 m0, s44
	s_add_i32 s74, s16, 0x80000
	buffer_load_dwordx4 v136, s[40:43], s16 offen lds
	s_mov_b32 m0, s45
	s_sub_i32 s17, s17, s4
	buffer_load_dwordx4 v134, s[40:43], s74 offen lds
	s_mov_b32 m0, s46
	s_nop 0
	buffer_load_dwordx4 v136, s[40:43], s74 offen lds
	s_mov_b32 m0, s34
	s_nop 0
	buffer_load_dwordx4 v0, s[4:7], s17 offen lds
	s_waitcnt vmcnt(7) lgkmcnt(0)
	s_setprio 1
	s_barrier
	v_mfma_f32_16x16x32_bf16 v[62:65], v[130:133], v[170:173], v[62:65]
	v_mfma_f32_16x16x32_bf16 v[58:61], v[146:149], v[170:173], v[58:61]
	v_mfma_f32_16x16x32_bf16 v[42:45], v[146:149], v[178:181], v[42:45]
	v_mfma_f32_16x16x32_bf16 v[46:49], v[130:133], v[178:181], v[46:49]
	v_mfma_f32_16x16x32_bf16 v[30:33], v[130:133], v[186:189], v[30:33]
	v_mfma_f32_16x16x32_bf16 v[26:29], v[146:149], v[186:189], v[26:29]
	v_mfma_f32_16x16x32_bf16 v[10:13], v[146:149], v[200:203], v[10:13]
	v_mfma_f32_16x16x32_bf16 v[14:17], v[130:133], v[200:203], v[14:17]
	v_mfma_f32_16x16x32_bf16 v[62:65], v[142:145], v[174:177], v[62:65]
	v_mfma_f32_16x16x32_bf16 v[58:61], v[150:153], v[174:177], v[58:61]
	v_mfma_f32_16x16x32_bf16 v[42:45], v[150:153], v[182:185], v[42:45]
	v_mfma_f32_16x16x32_bf16 v[46:49], v[142:145], v[182:185], v[46:49]
	v_mfma_f32_16x16x32_bf16 v[30:33], v[142:145], v[190:193], v[30:33]
	v_mfma_f32_16x16x32_bf16 v[26:29], v[150:153], v[190:193], v[26:29]
	v_mfma_f32_16x16x32_bf16 v[10:13], v[150:153], v[206:209], v[10:13]
	v_mfma_f32_16x16x32_bf16 v[14:17], v[142:145], v[206:209], v[14:17]
	v_mfma_f32_16x16x32_bf16 v[54:57], v[154:157], v[170:173], v[54:57]
	v_mfma_f32_16x16x32_bf16 v[50:53], v[162:165], v[170:173], v[50:53]
	v_mfma_f32_16x16x32_bf16 v[34:37], v[162:165], v[178:181], v[34:37]
	v_mfma_f32_16x16x32_bf16 v[38:41], v[154:157], v[178:181], v[38:41]
	v_mfma_f32_16x16x32_bf16 v[22:25], v[154:157], v[186:189], v[22:25]
	v_mfma_f32_16x16x32_bf16 v[18:21], v[162:165], v[186:189], v[18:21]
	v_mfma_f32_16x16x32_bf16 v[2:5], v[162:165], v[200:203], v[2:5]
	v_mfma_f32_16x16x32_bf16 v[6:9], v[154:157], v[200:203], v[6:9]
	v_mfma_f32_16x16x32_bf16 v[54:57], v[158:161], v[174:177], v[54:57]
	v_mfma_f32_16x16x32_bf16 v[50:53], v[166:169], v[174:177], v[50:53]
	v_mfma_f32_16x16x32_bf16 v[34:37], v[166:169], v[182:185], v[34:37]
	v_mfma_f32_16x16x32_bf16 v[38:41], v[158:161], v[182:185], v[38:41]
	v_mfma_f32_16x16x32_bf16 v[22:25], v[158:161], v[190:193], v[22:25]
	v_mfma_f32_16x16x32_bf16 v[18:21], v[166:169], v[190:193], v[18:21]
	v_mfma_f32_16x16x32_bf16 v[2:5], v[166:169], v[206:209], v[2:5]
	v_mfma_f32_16x16x32_bf16 v[6:9], v[158:161], v[206:209], v[6:9]
	s_barrier
	s_setprio 0
	v_add_u32_e32 v141, 0x18000, v139
	ds_read_b128 v[130:133], v141
	ds_read_b128 v[142:145], v141 offset:1024
	ds_read_b128 v[146:149], v141 offset:2048
	ds_read_b128 v[150:153], v141 offset:3072
	v_add_u32_e32 v141, 0x1c000, v139
	ds_read_b128 v[154:157], v141
	ds_read_b128 v[158:161], v141 offset:1024
	ds_read_b128 v[162:165], v141 offset:2048
	ds_read_b128 v[166:169], v141 offset:3072
	s_add_i32 s74, s17, 0x80000
	s_mov_b32 m0, s48
	ds_read_b128 v[170:173], v140 offset:32768
	ds_read_b128 v[174:177], v140 offset:33792
	ds_read_b128 v[178:181], v140 offset:34816
	ds_read_b128 v[182:185], v140 offset:35840
	ds_read_b128 v[186:189], v140 offset:36864
	ds_read_b128 v[190:193], v140 offset:37888
	ds_read_b128 v[200:203], v140 offset:38912
	ds_read_b128 v[206:209], v140 offset:39936
	s_mov_b32 m0, s47
	s_nop 0
	buffer_load_dwordx4 v135, s[4:7], s17 offen lds
	s_mov_b32 m0, s48
	s_nop 0
	buffer_load_dwordx4 v0, s[4:7], s74 offen lds
	s_mov_b32 m0, s49
	s_nop 0
	buffer_load_dwordx4 v135, s[4:7], s74 offen lds
	s_waitcnt vmcnt(8) lgkmcnt(0)
	s_setprio 1
	s_barrier
; #define PG8_STAGE(bufoff, gbase, voff) do { const int so_ = (int)(unsigned)((const char*)(gbase) - base_##voff); _Pragma("unroll") for (int _i = 0; _i < 2; ++_i) \
;         __builtin_amdgcn_raw_ptr_buffer_load_lds(rs_##voff, (PG8_LAS unsigned*)(lds + (bufoff) + ldsw + _i * 8192), 16, (int)(voff)[_i], so_, 0, 0); } while (0)
; #define PG8_LDA(dst, b, h) do { _Pragma("unroll") for (int m = 0; m < 4; ++m) _Pragma("unroll") for (int k = 0; k < 2; ++k) dst[m][k] = *(const PG8_LAS bf16x8*)(lds + PG8_SA(b, h) + aoff + m * 2048 + k * 1024); } while (0)
; #define PG8_LDB(dst, b, h) do { _Pragma("unroll") for (int n = 0; n < 2; ++n) _Pragma("unroll") for (int k = 0; k < 2; ++k) dst[n][k] = *(const PG8_LAS bf16x8*)(lds + PG8_SB(b, h) + boff + n * 2048 + k * 1024); } while (0)
; #define PG8_MMA(ai, bj, At, Bt) do { __builtin_amdgcn_s_setprio(1); _Pragma("unroll") for (int m = 0; m < 4; ++m) _Pragma("unroll") for (int n = 0; n < 2; ++n) _Pragma("unroll") for (int k = 0; k < 2; ++k) \
;         acc[ai][bj][m][n] = __builtin_amdgcn_mfma_f32_16x16x32_bf16(Bt[n][k], At[m][k], acc[ai][bj][m][n], 0, 0, 0); __builtin_amdgcn_s_setprio(0); } while (0)
; #define PG8_WAIT_V(n) asm volatile("s_waitcnt vmcnt(" #n ")" ::: "memory")
; #define PG8_WAIT_L(n) asm volatile("s_waitcnt lgkmcnt(" #n ")" ::: "memory")
; #define PG8_BAR __builtin_amdgcn_s_barrier()
; #define PG8_SCHED __builtin_amdgcn_sched_barrier(0)
; template <class Epi, class Sched, bool ALIGN_EPI = false, bool SP2 = false>
; __device__ __forceinline__ void gemm_phase(PG8_LAS unsigned char* lds, const Gemm g, const Sched& S, const Epi& E, int tid_in) {
;     ...
;             PG8_LDB(B0, 1, 0); PG8_LDB(B1, 1, 1); PG8_SCHED; PG8_LDA(At, 1, 0); PG8_STAGE(PG8_SA(0, 1), a2 + hstepA, voffA);
;             PG8_WAIT_V(8); PG8_WAIT_L(0); PG8_BAR; PG8_MMA(0, 0, At, B0); PG8_MMA(0, 1, At, B1); PG8_BAR; PG8_SCHED;
;             PG8_LDA(At, 1, 1); PG8_STAGE(PG8_SB(1, 0), b3, voffB); PG8_STAGE(PG8_SB(1, 1), b3 + hstepB, voffB); PG8_STAGE(PG8_SA(1, 0), a3, voffA);
;             PG8_WAIT_V(8); PG8_WAIT_L(0); PG8_BAR; PG8_MMA(1, 0, At, B0); PG8_MMA(1, 1, At, B1); PG8_BAR; PG8_SCHED;
;     ...
;         if constexpr (ALIGN_EPI) { if (wr == 0) PG8_BAR; }
;         if constexpr (!Epi::AFTER_DRAIN) { E(acc, cur, wr, wc, fr, fq); S.done(cur); }
	v_mfma_f32_16x16x32_bf16 v[126:129], v[130:133], v[170:173], v[126:129]
	v_mfma_f32_16x16x32_bf16 v[122:125], v[146:149], v[170:173], v[122:125]
	v_mfma_f32_16x16x32_bf16 v[106:109], v[146:149], v[178:181], v[106:109]
	v_mfma_f32_16x16x32_bf16 v[110:113], v[130:133], v[178:181], v[110:113]
	v_mfma_f32_16x16x32_bf16 v[94:97], v[130:133], v[186:189], v[94:97]
	v_mfma_f32_16x16x32_bf16 v[90:93], v[146:149], v[186:189], v[90:93]
	v_mfma_f32_16x16x32_bf16 v[74:77], v[146:149], v[200:203], v[74:77]
	v_mfma_f32_16x16x32_bf16 v[78:81], v[130:133], v[200:203], v[78:81]
	v_mfma_f32_16x16x32_bf16 v[126:129], v[142:145], v[174:177], v[126:129]
	v_mfma_f32_16x16x32_bf16 v[122:125], v[150:153], v[174:177], v[122:125]
	v_mfma_f32_16x16x32_bf16 v[106:109], v[150:153], v[182:185], v[106:109]
	v_mfma_f32_16x16x32_bf16 v[110:113], v[142:145], v[182:185], v[110:113]
	v_mfma_f32_16x16x32_bf16 v[94:97], v[142:145], v[190:193], v[94:97]
	v_mfma_f32_16x16x32_bf16 v[90:93], v[150:153], v[190:193], v[90:93]
	v_mfma_f32_16x16x32_bf16 v[74:77], v[150:153], v[206:209], v[74:77]
	v_mfma_f32_16x16x32_bf16 v[78:81], v[142:145], v[206:209], v[78:81]
	v_mfma_f32_16x16x32_bf16 v[118:121], v[154:157], v[170:173], v[118:121]
	v_mfma_f32_16x16x32_bf16 v[114:117], v[162:165], v[170:173], v[114:117]
	v_mfma_f32_16x16x32_bf16 v[98:101], v[162:165], v[178:181], v[98:101]
	v_mfma_f32_16x16x32_bf16 v[102:105], v[154:157], v[178:181], v[102:105]
	v_mfma_f32_16x16x32_bf16 v[86:89], v[154:157], v[186:189], v[86:89]
	v_mfma_f32_16x16x32_bf16 v[82:85], v[162:165], v[186:189], v[82:85]
	v_mfma_f32_16x16x32_bf16 v[66:69], v[162:165], v[200:203], v[66:69]
	v_mfma_f32_16x16x32_bf16 v[70:73], v[154:157], v[200:203], v[70:73]
	v_mfma_f32_16x16x32_bf16 v[118:121], v[158:161], v[174:177], v[118:121]
	v_mfma_f32_16x16x32_bf16 v[114:117], v[166:169], v[174:177], v[114:117]
	v_mfma_f32_16x16x32_bf16 v[98:101], v[166:169], v[182:185], v[98:101]
	v_mfma_f32_16x16x32_bf16 v[102:105], v[158:161], v[182:185], v[102:105]
	v_mfma_f32_16x16x32_bf16 v[86:89], v[158:161], v[190:193], v[86:89]
	v_mfma_f32_16x16x32_bf16 v[82:85], v[166:169], v[190:193], v[82:85]
	v_mfma_f32_16x16x32_bf16 v[66:69], v[166:169], v[206:209], v[66:69]
	v_mfma_f32_16x16x32_bf16 v[70:73], v[158:161], v[206:209], v[70:73]
	s_barrier
	s_setprio 0
	s_mov_b32 m0, s53
	s_add_i32 s74, s16, 0x80
	ds_read_b128 v[170:173], v140 offset:49152
	ds_read_b128 v[174:177], v140 offset:50176
	ds_read_b128 v[178:181], v140 offset:51200
	ds_read_b128 v[182:185], v140 offset:52224
	ds_read_b128 v[186:189], v140 offset:53248
	ds_read_b128 v[190:193], v140 offset:54272
	ds_read_b128 v[200:203], v140 offset:55296
	ds_read_b128 v[206:209], v140 offset:56320
	buffer_load_dwordx4 v134, s[40:43], s74 offen lds
	s_mov_b32 m0, s60
	s_add_i32 s16, s16, 0x80080
	buffer_load_dwordx4 v136, s[40:43], s74 offen lds
	s_mov_b32 m0, s63
	s_addk_i32 s17, 0x80
	buffer_load_dwordx4 v134, s[40:43], s16 offen lds
	s_mov_b32 m0, s66
	s_nop 0
	buffer_load_dwordx4 v136, s[40:43], s16 offen lds
	s_mov_b32 m0, s61
	s_nop 0
	buffer_load_dwordx4 v0, s[4:7], s17 offen lds
	s_waitcnt vmcnt(7) lgkmcnt(0)
	s_setprio 1
	s_barrier
	v_mfma_f32_16x16x32_bf16 v[62:65], v[130:133], v[170:173], v[62:65]
	v_mfma_f32_16x16x32_bf16 v[58:61], v[146:149], v[170:173], v[58:61]
	v_mfma_f32_16x16x32_bf16 v[42:45], v[146:149], v[178:181], v[42:45]
	v_mfma_f32_16x16x32_bf16 v[46:49], v[130:133], v[178:181], v[46:49]
	v_mfma_f32_16x16x32_bf16 v[30:33], v[130:133], v[186:189], v[30:33]
	v_mfma_f32_16x16x32_bf16 v[26:29], v[146:149], v[186:189], v[26:29]
	v_mfma_f32_16x16x32_bf16 v[10:13], v[146:149], v[200:203], v[10:13]
	v_mfma_f32_16x16x32_bf16 v[14:17], v[130:133], v[200:203], v[14:17]
	v_mfma_f32_16x16x32_bf16 v[62:65], v[142:145], v[174:177], v[62:65]
	v_mfma_f32_16x16x32_bf16 v[58:61], v[150:153], v[174:177], v[58:61]
	v_mfma_f32_16x16x32_bf16 v[42:45], v[150:153], v[182:185], v[42:45]
	v_mfma_f32_16x16x32_bf16 v[46:49], v[142:145], v[182:185], v[46:49]
	v_mfma_f32_16x16x32_bf16 v[30:33], v[142:145], v[190:193], v[30:33]
	v_mfma_f32_16x16x32_bf16 v[26:29], v[150:153], v[190:193], v[26:29]
	v_mfma_f32_16x16x32_bf16 v[10:13], v[150:153], v[206:209], v[10:13]
	v_mfma_f32_16x16x32_bf16 v[14:17], v[142:145], v[206:209], v[14:17]
	v_mfma_f32_16x16x32_bf16 v[54:57], v[154:157], v[170:173], v[54:57]
	v_mfma_f32_16x16x32_bf16 v[50:53], v[162:165], v[170:173], v[50:53]
	v_mfma_f32_16x16x32_bf16 v[34:37], v[162:165], v[178:181], v[34:37]
	v_mfma_f32_16x16x32_bf16 v[38:41], v[154:157], v[178:181], v[38:41]
	v_mfma_f32_16x16x32_bf16 v[22:25], v[154:157], v[186:189], v[22:25]
	v_mfma_f32_16x16x32_bf16 v[18:21], v[162:165], v[186:189], v[18:21]
	v_mfma_f32_16x16x32_bf16 v[2:5], v[162:165], v[200:203], v[2:5]
	v_mfma_f32_16x16x32_bf16 v[6:9], v[154:157], v[200:203], v[6:9]
	v_mfma_f32_16x16x32_bf16 v[54:57], v[158:161], v[174:177], v[54:57]
	v_mfma_f32_16x16x32_bf16 v[50:53], v[166:169], v[174:177], v[50:53]
	v_mfma_f32_16x16x32_bf16 v[34:37], v[166:169], v[182:185], v[34:37]
	v_mfma_f32_16x16x32_bf16 v[38:41], v[158:161], v[182:185], v[38:41]
	v_mfma_f32_16x16x32_bf16 v[22:25], v[158:161], v[190:193], v[22:25]
	v_mfma_f32_16x16x32_bf16 v[18:21], v[166:169], v[190:193], v[18:21]
	v_mfma_f32_16x16x32_bf16 v[2:5], v[166:169], v[206:209], v[2:5]
	v_mfma_f32_16x16x32_bf16 v[6:9], v[158:161], v[206:209], v[6:9]
	s_barrier
	s_setprio 0
	s_add_i32 s73, s73, 2
	s_add_u32 s19, s19, 0x100
	s_addc_u32 s21, s21, 0
	s_cmp_gt_u32 s73, 29
	s_mov_b64 s[16:17], s[38:39]
	s_cbranch_scc0 .LBB0_1514
	s_and_b64 vcc, exec, s[12:13]
	s_cbranch_vccz .LBB0_1517
	s_barrier

; #define PG8_STAGE(bufoff, gbase, voff) do { const int so_ = (int)(unsigned)((const char*)(gbase) - base_##voff); _Pragma("unroll") for (int _i = 0; _i < 2; ++_i) \
;         __builtin_amdgcn_raw_ptr_buffer_load_lds(rs_##voff, (PG8_LAS unsigned*)(lds + (bufoff) + ldsw + _i * 8192), 16, (int)(voff)[_i], so_, 0, 0); } while (0)
; #define PG8_LDA(dst, b, h) do { _Pragma("unroll") for (int m = 0; m < 4; ++m) _Pragma("unroll") for (int k = 0; k < 2; ++k) dst[m][k] = *(const PG8_LAS bf16x8*)(lds + PG8_SA(b, h) + aoff + m * 2048 + k * 1024); } while (0)
; #define PG8_LDB(dst, b, h) do { _Pragma("unroll") for (int n = 0; n < 2; ++n) _Pragma("unroll") for (int k = 0; k < 2; ++k) dst[n][k] = *(const PG8_LAS bf16x8*)(lds + PG8_SB(b, h) + boff + n * 2048 + k * 1024); } while (0)
; #define PG8_MMA(ai, bj, At, Bt) do { __builtin_amdgcn_s_setprio(1); _Pragma("unroll") for (int m = 0; m < 4; ++m) _Pragma("unroll") for (int n = 0; n < 2; ++n) _Pragma("unroll") for (int k = 0; k < 2; ++k) \
;         acc[ai][bj][m][n] = __builtin_amdgcn_mfma_f32_16x16x32_bf16(Bt[n][k], At[m][k], acc[ai][bj][m][n], 0, 0, 0); __builtin_amdgcn_s_setprio(0); } while (0)
; #define PG8_WAIT_V(n) asm volatile("s_waitcnt vmcnt(" #n ")" ::: "memory")
; #define PG8_WAIT_L(n) asm volatile("s_waitcnt lgkmcnt(" #n ")" ::: "memory")
; #define PG8_BAR __builtin_amdgcn_s_barrier()
; #define PG8_SCHED __builtin_amdgcn_sched_barrier(0)
; template <class Epi, class Sched, bool ALIGN_EPI = false, bool SP2 = false>
; __device__ __forceinline__ void gemm_phase(PG8_LAS unsigned char* lds, const Gemm g, const Sched& S, const Epi& E, int tid_in) {
;     ...
;             PG8_LDB(B0, 0, 0); PG8_LDB(B1, 0, 1); PG8_SCHED; PG8_LDA(At, 0, 0); PG8_STAGE(PG8_SA(1, 1), a1 + hstepA, voffA);
;             PG8_WAIT_V(8); PG8_WAIT_L(0); PG8_BAR; PG8_MMA(0, 0, At, B0); PG8_MMA(0, 1, At, B1); PG8_BAR; PG8_SCHED;
;             PG8_LDA(At, 0, 1); PG8_STAGE(PG8_SB(0, 0), b2, voffB); PG8_STAGE(PG8_SB(0, 1), b2 + hstepB, voffB); PG8_STAGE(PG8_SA(0, 0), a2, voffA);
;             PG8_WAIT_V(8); PG8_WAIT_L(0); PG8_BAR; PG8_MMA(1, 0, At, B0); PG8_MMA(1, 1, At, B1); PG8_BAR; PG8_SCHED;
.LBB0_1584:
	v_add_u32_e32 v133, 0x10000, v131
	ds_read_b128 v[134:137], v133
	ds_read_b128 v[138:141], v133 offset:1024
	ds_read_b128 v[142:145], v133 offset:2048
	ds_read_b128 v[146:149], v133 offset:3072
	v_add_u32_e32 v133, 0x14000, v131
	ds_read_b128 v[150:153], v133
	ds_read_b128 v[154:157], v133 offset:1024
	ds_read_b128 v[158:161], v133 offset:2048
	ds_read_b128 v[166:169], v133 offset:3072
	s_add_i32 s43, s38, s22
	s_add_i32 s42, s14, s22
	s_add_i32 s76, s12, s22
	s_addk_i32 s43, 0xff80
	s_sub_i32 s78, s43, 0x160000
	s_cmpk_eq_i32 s39, 0x54
	s_cselect_b32 s77, s16, s42
	s_mov_b32 m0, s68
	ds_read_b128 v[170:173], v132
	ds_read_b128 v[174:177], v132 offset:1024
	ds_read_b128 v[178:181], v132 offset:2048
	ds_read_b128 v[182:185], v132 offset:3072
	ds_read_b128 v[186:189], v132 offset:4096
	ds_read_b128 v[190:193], v132 offset:5120
	ds_read_b128 v[200:203], v132 offset:6144
	ds_read_b128 v[206:209], v132 offset:7168
	s_mov_b32 m0, s63
	s_nop 0
	buffer_load_dwordx4 v130, s[4:7], s78 offen lds
	s_mov_b32 m0, s68
	s_nop 0
	buffer_load_dwordx4 v0, s[4:7], s43 offen lds
	s_mov_b32 m0, s69
	s_nop 0
	buffer_load_dwordx4 v130, s[4:7], s43 offen lds
	s_waitcnt vmcnt(8) lgkmcnt(0)
	s_setprio 1
	s_barrier
	v_mfma_f32_16x16x32_bf16 v[22:25], v[134:137], v[170:173], v[22:25]
	v_mfma_f32_16x16x32_bf16 v[14:17], v[142:145], v[170:173], v[14:17]
	v_mfma_f32_16x16x32_bf16 v[54:57], v[142:145], v[178:181], v[54:57]
	v_mfma_f32_16x16x32_bf16 v[74:77], v[134:137], v[178:181], v[74:77]
	v_mfma_f32_16x16x32_bf16 v[106:109], v[134:137], v[186:189], v[106:109]
	v_mfma_f32_16x16x32_bf16 v[102:105], v[142:145], v[186:189], v[102:105]
	v_mfma_f32_16x16x32_bf16 v[118:121], v[142:145], v[200:203], v[118:121]
	v_mfma_f32_16x16x32_bf16 v[122:125], v[134:137], v[200:203], v[122:125]
	v_mfma_f32_16x16x32_bf16 v[22:25], v[138:141], v[174:177], v[22:25]
	v_mfma_f32_16x16x32_bf16 v[14:17], v[146:149], v[174:177], v[14:17]
	v_mfma_f32_16x16x32_bf16 v[54:57], v[146:149], v[182:185], v[54:57]
	v_mfma_f32_16x16x32_bf16 v[74:77], v[138:141], v[182:185], v[74:77]
	v_mfma_f32_16x16x32_bf16 v[106:109], v[138:141], v[190:193], v[106:109]
	v_mfma_f32_16x16x32_bf16 v[102:105], v[146:149], v[190:193], v[102:105]
	v_mfma_f32_16x16x32_bf16 v[118:121], v[146:149], v[206:209], v[118:121]
	v_mfma_f32_16x16x32_bf16 v[122:125], v[138:141], v[206:209], v[122:125]
	v_mfma_f32_16x16x32_bf16 v[6:9], v[150:153], v[170:173], v[6:9]
	v_mfma_f32_16x16x32_bf16 v[18:21], v[158:161], v[170:173], v[18:21]
	v_mfma_f32_16x16x32_bf16 v[78:81], v[158:161], v[178:181], v[78:81]
	v_mfma_f32_16x16x32_bf16 v[50:53], v[150:153], v[178:181], v[50:53]
	v_mfma_f32_16x16x32_bf16 v[98:101], v[150:153], v[186:189], v[98:101]
	v_mfma_f32_16x16x32_bf16 v[110:113], v[158:161], v[186:189], v[110:113]
	v_mfma_f32_16x16x32_bf16 v[126:129], v[158:161], v[200:203], v[126:129]
	v_mfma_f32_16x16x32_bf16 v[114:117], v[150:153], v[200:203], v[114:117]
	v_mfma_f32_16x16x32_bf16 v[6:9], v[154:157], v[174:177], v[6:9]
	v_mfma_f32_16x16x32_bf16 v[18:21], v[166:169], v[174:177], v[18:21]
	v_mfma_f32_16x16x32_bf16 v[78:81], v[166:169], v[182:185], v[78:81]
	v_mfma_f32_16x16x32_bf16 v[50:53], v[154:157], v[182:185], v[50:53]
	v_mfma_f32_16x16x32_bf16 v[98:101], v[154:157], v[190:193], v[98:101]
	v_mfma_f32_16x16x32_bf16 v[110:113], v[166:169], v[190:193], v[110:113]
	v_mfma_f32_16x16x32_bf16 v[126:129], v[166:169], v[206:209], v[126:129]
	v_mfma_f32_16x16x32_bf16 v[114:117], v[154:157], v[206:209], v[114:117]
	s_barrier
	s_setprio 0
	s_cselect_b32 s76, s20, s76
	s_mov_b32 m0, s26
	s_mov_b32 s42, s6
	s_mov_b32 s43, s7
	s_sub_i32 s76, s76, s40
	ds_read_b128 v[170:173], v132 offset:16384
	ds_read_b128 v[174:177], v132 offset:17408
	ds_read_b128 v[178:181], v132 offset:18432
	ds_read_b128 v[182:185], v132 offset:19456
	ds_read_b128 v[186:189], v132 offset:20480
	ds_read_b128 v[190:193], v132 offset:21504
	ds_read_b128 v[200:203], v132 offset:22528
	ds_read_b128 v[206:209], v132 offset:23552
	buffer_load_dwordx4 v0, s[40:43], s76 offen lds
	s_mov_b32 m0, s44
	s_add_i32 s78, s76, 0x160000
	buffer_load_dwordx4 v130, s[40:43], s76 offen lds
	s_mov_b32 m0, s45
	s_sub_i32 s77, s77, s4
	buffer_load_dwordx4 v0, s[40:43], s78 offen lds
	s_mov_b32 m0, s46
	s_nop 0
	buffer_load_dwordx4 v130, s[40:43], s78 offen lds
	s_mov_b32 m0, s19
	s_nop 0
	buffer_load_dwordx4 v0, s[4:7], s77 offen lds
	s_waitcnt vmcnt(7) lgkmcnt(0)
	s_setprio 1
	s_barrier
	v_mfma_f32_16x16x32_bf16 v[62:65], v[134:137], v[170:173], v[62:65]
	v_mfma_f32_16x16x32_bf16 v[46:49], v[142:145], v[170:173], v[46:49]
	v_mfma_f32_16x16x32_bf16 v[70:73], v[142:145], v[178:181], v[70:73]
	v_mfma_f32_16x16x32_bf16 v[82:85], v[134:137], v[178:181], v[82:85]
	v_mfma_f32_16x16x32_bf16 v[94:97], v[134:137], v[186:189], v[94:97]
	v_mfma_f32_16x16x32_bf16 v[90:93], v[142:145], v[186:189], v[90:93]
	v_mfma_f32_16x16x32_bf16 v[26:29], v[142:145], v[200:203], v[26:29]
	v_mfma_f32_16x16x32_bf16 v[38:41], v[134:137], v[200:203], v[38:41]
	v_mfma_f32_16x16x32_bf16 v[62:65], v[138:141], v[174:177], v[62:65]
	v_mfma_f32_16x16x32_bf16 v[46:49], v[146:149], v[174:177], v[46:49]
	v_mfma_f32_16x16x32_bf16 v[70:73], v[146:149], v[182:185], v[70:73]
	v_mfma_f32_16x16x32_bf16 v[82:85], v[138:141], v[182:185], v[82:85]
	v_mfma_f32_16x16x32_bf16 v[94:97], v[138:141], v[190:193], v[94:97]
	v_mfma_f32_16x16x32_bf16 v[90:93], v[146:149], v[190:193], v[90:93]
	v_mfma_f32_16x16x32_bf16 v[26:29], v[146:149], v[206:209], v[26:29]
	v_mfma_f32_16x16x32_bf16 v[38:41], v[138:141], v[206:209], v[38:41]
	v_mfma_f32_16x16x32_bf16 v[42:45], v[150:153], v[170:173], v[42:45]
	v_mfma_f32_16x16x32_bf16 v[30:33], v[158:161], v[170:173], v[30:33]
	v_mfma_f32_16x16x32_bf16 v[86:89], v[158:161], v[178:181], v[86:89]
	v_mfma_f32_16x16x32_bf16 v[66:69], v[150:153], v[178:181], v[66:69]
	v_mfma_f32_16x16x32_bf16 v[58:61], v[150:153], v[186:189], v[58:61]
	v_mfma_f32_16x16x32_bf16 v[34:37], v[158:161], v[186:189], v[34:37]
	v_mfma_f32_16x16x32_bf16 v[2:5], v[158:161], v[200:203], v[2:5]
	v_mfma_f32_16x16x32_bf16 v[10:13], v[150:153], v[200:203], v[10:13]
	v_mfma_f32_16x16x32_bf16 v[42:45], v[154:157], v[174:177], v[42:45]
	v_mfma_f32_16x16x32_bf16 v[30:33], v[166:169], v[174:177], v[30:33]
	v_mfma_f32_16x16x32_bf16 v[86:89], v[166:169], v[182:185], v[86:89]
	v_mfma_f32_16x16x32_bf16 v[66:69], v[154:157], v[182:185], v[66:69]
	v_mfma_f32_16x16x32_bf16 v[58:61], v[154:157], v[190:193], v[58:61]
	v_mfma_f32_16x16x32_bf16 v[34:37], v[166:169], v[190:193], v[34:37]
	v_mfma_f32_16x16x32_bf16 v[2:5], v[166:169], v[206:209], v[2:5]
	v_mfma_f32_16x16x32_bf16 v[10:13], v[154:157], v[206:209], v[10:13]
	s_barrier
; #define PG8_STAGE(bufoff, gbase, voff) do { const int so_ = (int)(unsigned)((const char*)(gbase) - base_##voff); _Pragma("unroll") for (int _i = 0; _i < 2; ++_i) \
;         __builtin_amdgcn_raw_ptr_buffer_load_lds(rs_##voff, (PG8_LAS unsigned*)(lds + (bufoff) + ldsw + _i * 8192), 16, (int)(voff)[_i], so_, 0, 0); } while (0)
; #define PG8_LDA(dst, b, h) do { _Pragma("unroll") for (int m = 0; m < 4; ++m) _Pragma("unroll") for (int k = 0; k < 2; ++k) dst[m][k] = *(const PG8_LAS bf16x8*)(lds + PG8_SA(b, h) + aoff + m * 2048 + k * 1024); } while (0)
; #define PG8_LDB(dst, b, h) do { _Pragma("unroll") for (int n = 0; n < 2; ++n) _Pragma("unroll") for (int k = 0; k < 2; ++k) dst[n][k] = *(const PG8_LAS bf16x8*)(lds + PG8_SB(b, h) + boff + n * 2048 + k * 1024); } while (0)
; #define PG8_MMA(ai, bj, At, Bt) do { __builtin_amdgcn_s_setprio(1); _Pragma("unroll") for (int m = 0; m < 4; ++m) _Pragma("unroll") for (int n = 0; n < 2; ++n) _Pragma("unroll") for (int k = 0; k < 2; ++k) \
;         acc[ai][bj][m][n] = __builtin_amdgcn_mfma_f32_16x16x32_bf16(Bt[n][k], At[m][k], acc[ai][bj][m][n], 0, 0, 0); __builtin_amdgcn_s_setprio(0); } while (0)
; #define PG8_WAIT_V(n) asm volatile("s_waitcnt vmcnt(" #n ")" ::: "memory")
; #define PG8_WAIT_L(n) asm volatile("s_waitcnt lgkmcnt(" #n ")" ::: "memory")
; #define PG8_BAR __builtin_amdgcn_s_barrier()
; #define PG8_SCHED __builtin_amdgcn_sched_barrier(0)
; template <class Epi, class Sched, bool ALIGN_EPI = false, bool SP2 = false>
; __device__ __forceinline__ void gemm_phase(PG8_LAS unsigned char* lds, const Gemm g, const Sched& S, const Epi& E, int tid_in) {
;     ...
;             PG8_LDB(B0, 1, 0); PG8_LDB(B1, 1, 1); PG8_SCHED; PG8_LDA(At, 1, 0); PG8_STAGE(PG8_SA(0, 1), a2 + hstepA, voffA);
;             PG8_WAIT_V(8); PG8_WAIT_L(0); PG8_BAR; PG8_MMA(0, 0, At, B0); PG8_MMA(0, 1, At, B1); PG8_BAR; PG8_SCHED;
;             PG8_LDA(At, 1, 1); PG8_STAGE(PG8_SB(1, 0), b3, voffB); PG8_STAGE(PG8_SB(1, 1), b3 + hstepB, voffB); PG8_STAGE(PG8_SA(1, 0), a3, voffA);
;             PG8_WAIT_V(8); PG8_WAIT_L(0); PG8_BAR; PG8_MMA(1, 0, At, B0); PG8_MMA(1, 1, At, B1); PG8_BAR; PG8_SCHED;
	s_setprio 0
	v_add_u32_e32 v133, 0x18000, v131
	ds_read_b128 v[134:137], v133
	ds_read_b128 v[138:141], v133 offset:1024
	ds_read_b128 v[142:145], v133 offset:2048
	ds_read_b128 v[146:149], v133 offset:3072
	v_add_u32_e32 v133, 0x1c000, v131
	ds_read_b128 v[150:153], v133
	ds_read_b128 v[154:157], v133 offset:1024
	ds_read_b128 v[158:161], v133 offset:2048
	ds_read_b128 v[166:169], v133 offset:3072
	s_add_i32 s78, s77, 0x160000
	s_mov_b32 m0, s48
	ds_read_b128 v[170:173], v132 offset:32768
	ds_read_b128 v[174:177], v132 offset:33792
	ds_read_b128 v[178:181], v132 offset:34816
	ds_read_b128 v[182:185], v132 offset:35840
	ds_read_b128 v[186:189], v132 offset:36864
	ds_read_b128 v[190:193], v132 offset:37888
	ds_read_b128 v[200:203], v132 offset:38912
	ds_read_b128 v[206:209], v132 offset:39936
	s_mov_b32 m0, s47
	s_nop 0
	buffer_load_dwordx4 v130, s[4:7], s77 offen lds
	s_mov_b32 m0, s48
	s_nop 0
	buffer_load_dwordx4 v0, s[4:7], s78 offen lds
	s_mov_b32 m0, s49
	s_nop 0
	buffer_load_dwordx4 v130, s[4:7], s78 offen lds
	s_waitcnt vmcnt(8) lgkmcnt(0)
	s_setprio 1
	s_barrier
	v_mfma_f32_16x16x32_bf16 v[22:25], v[134:137], v[170:173], v[22:25]
	v_mfma_f32_16x16x32_bf16 v[14:17], v[142:145], v[170:173], v[14:17]
	v_mfma_f32_16x16x32_bf16 v[54:57], v[142:145], v[178:181], v[54:57]
	v_mfma_f32_16x16x32_bf16 v[74:77], v[134:137], v[178:181], v[74:77]
	v_mfma_f32_16x16x32_bf16 v[106:109], v[134:137], v[186:189], v[106:109]
	v_mfma_f32_16x16x32_bf16 v[102:105], v[142:145], v[186:189], v[102:105]
	v_mfma_f32_16x16x32_bf16 v[118:121], v[142:145], v[200:203], v[118:121]
	v_mfma_f32_16x16x32_bf16 v[122:125], v[134:137], v[200:203], v[122:125]
	v_mfma_f32_16x16x32_bf16 v[22:25], v[138:141], v[174:177], v[22:25]
	v_mfma_f32_16x16x32_bf16 v[14:17], v[146:149], v[174:177], v[14:17]
	v_mfma_f32_16x16x32_bf16 v[54:57], v[146:149], v[182:185], v[54:57]
	v_mfma_f32_16x16x32_bf16 v[74:77], v[138:141], v[182:185], v[74:77]
	v_mfma_f32_16x16x32_bf16 v[106:109], v[138:141], v[190:193], v[106:109]
	v_mfma_f32_16x16x32_bf16 v[102:105], v[146:149], v[190:193], v[102:105]
	v_mfma_f32_16x16x32_bf16 v[118:121], v[146:149], v[206:209], v[118:121]
	v_mfma_f32_16x16x32_bf16 v[122:125], v[138:141], v[206:209], v[122:125]
	v_mfma_f32_16x16x32_bf16 v[6:9], v[150:153], v[170:173], v[6:9]
	v_mfma_f32_16x16x32_bf16 v[18:21], v[158:161], v[170:173], v[18:21]
	v_mfma_f32_16x16x32_bf16 v[78:81], v[158:161], v[178:181], v[78:81]
	v_mfma_f32_16x16x32_bf16 v[50:53], v[150:153], v[178:181], v[50:53]
	v_mfma_f32_16x16x32_bf16 v[98:101], v[150:153], v[186:189], v[98:101]
	v_mfma_f32_16x16x32_bf16 v[110:113], v[158:161], v[186:189], v[110:113]
	v_mfma_f32_16x16x32_bf16 v[126:129], v[158:161], v[200:203], v[126:129]
	v_mfma_f32_16x16x32_bf16 v[114:117], v[150:153], v[200:203], v[114:117]
	v_mfma_f32_16x16x32_bf16 v[6:9], v[154:157], v[174:177], v[6:9]
	v_mfma_f32_16x16x32_bf16 v[18:21], v[166:169], v[174:177], v[18:21]
	v_mfma_f32_16x16x32_bf16 v[78:81], v[166:169], v[182:185], v[78:81]
	v_mfma_f32_16x16x32_bf16 v[50:53], v[154:157], v[182:185], v[50:53]
	v_mfma_f32_16x16x32_bf16 v[98:101], v[154:157], v[190:193], v[98:101]
	v_mfma_f32_16x16x32_bf16 v[110:113], v[166:169], v[190:193], v[110:113]
	v_mfma_f32_16x16x32_bf16 v[126:129], v[166:169], v[206:209], v[126:129]
	v_mfma_f32_16x16x32_bf16 v[114:117], v[154:157], v[206:209], v[114:117]
	s_barrier
	s_setprio 0
	s_mov_b32 m0, s60
	s_add_i32 s78, s76, 0x80
	ds_read_b128 v[170:173], v132 offset:49152
	ds_read_b128 v[174:177], v132 offset:50176
	ds_read_b128 v[178:181], v132 offset:51200
	ds_read_b128 v[182:185], v132 offset:52224
	ds_read_b128 v[186:189], v132 offset:53248
	ds_read_b128 v[190:193], v132 offset:54272
	ds_read_b128 v[200:203], v132 offset:55296
	ds_read_b128 v[206:209], v132 offset:56320
	buffer_load_dwordx4 v0, s[40:43], s78 offen lds
	s_mov_b32 m0, s61
	s_add_i32 s76, s76, 0x160080
	buffer_load_dwordx4 v130, s[40:43], s78 offen lds
	s_mov_b32 m0, s66
	s_addk_i32 s77, 0x80
	buffer_load_dwordx4 v0, s[40:43], s76 offen lds
	s_mov_b32 m0, s67
	s_nop 0
	buffer_load_dwordx4 v130, s[40:43], s76 offen lds
	s_mov_b32 m0, s62
	s_nop 0
	buffer_load_dwordx4 v0, s[4:7], s77 offen lds
	s_waitcnt vmcnt(7) lgkmcnt(0)
	s_setprio 1
	s_barrier
;     static __device__ __forceinline__ bool last_of_chain(const Unit& u) { return (u.pn >> 3) == 2; }
; template <class Epi, class Sched, bool ALIGN_EPI = false, bool SP2 = false>
; __device__ __forceinline__ void gemm_phase(PG8_LAS unsigned char* lds, const Gemm g, const Sched& S, const Epi& E, int tid_in) {
;     ...
;             PG8_WAIT_V(8); PG8_WAIT_L(0); PG8_BAR; PG8_MMA(1, 0, At, B0); PG8_MMA(1, 1, At, B1); PG8_BAR; PG8_SCHED;
;             } else {
;             PG8_LDB(B0, 0, 0); PG8_SCHED; PG8_LDA(At, 0, 0); PG8_STAGE(PG8_SA(1, 1), a1 + hstepA, voffA);
;             PG8_WAIT_L(8); PG8_BAR; PG8_WAIT_L(0); PG8_MMA(0, 0, At, B0); PG8_BAR; PG8_SCHED;
;             PG8_LDB(B1, 0, 1); PG8_STAGE(PG8_SB(0, 0), b2, voffB);
;             PG8_BAR; PG8_WAIT_L(0); PG8_MMA(0, 1, At, B1); PG8_BAR;
;             PG8_LDA(At, 0, 1); PG8_STAGE(PG8_SA(0, 0), a2, voffA);
;             PG8_BAR; PG8_WAIT_L(0); PG8_MMA(1, 0, At, B0); PG8_BAR; PG8_SCHED;
;             PG8_STAGE(PG8_SB(0, 1), b2 + hstepB, voffB);
;             PG8_WAIT_V(6); PG8_BAR; PG8_MMA(1, 1, At, B1); PG8_BAR;
;             PG8_LDB(B0, 1, 0); PG8_SCHED; PG8_LDA(At, 1, 0); PG8_STAGE(PG8_SA(0, 1), a2 + hstepA, voffA);
;             PG8_WAIT_L(8); PG8_BAR; PG8_WAIT_L(0); PG8_MMA(0, 0, At, B0); PG8_BAR; PG8_SCHED;
;             PG8_LDB(B1, 1, 1); PG8_STAGE(PG8_SB(1, 0), b3, voffB);
;             PG8_BAR; PG8_WAIT_L(0); PG8_MMA(0, 1, At, B1); PG8_BAR;
;             PG8_LDA(At, 1, 1); PG8_STAGE(PG8_SA(1, 0), a3, voffA);
;             PG8_BAR; PG8_WAIT_L(0); PG8_MMA(1, 0, At, B0); PG8_BAR; PG8_SCHED;
;             PG8_STAGE(PG8_SB(1, 1), b3 + hstepB, voffB);
;             PG8_WAIT_V(6); PG8_BAR; PG8_MMA(1, 1, At, B1); PG8_BAR;
;             }
;         }
;         if constexpr (ALIGN_EPI) { if (wr == 0) PG8_BAR; }
;         if constexpr (!Epi::AFTER_DRAIN) { E(acc, cur, wr, wc, fr, fq); S.done(cur); }
;         if (!has_next) break;
;         bool zero_acc = true; if constexpr (Epi::CHAIN) zero_acc = Epi::last_of_chain(cur);
;         if (zero_acc) {
; #pragma unroll
;         for (int a = 0; a < 2; ++a)
; #pragma unroll
;             for (int b = 0; b < 2; ++b)
; #pragma unroll
;                 for (int m = 0; m < 4; ++m)
; #pragma unroll
;                     for (int n = 0; n < 2; ++n) acc[a][b][m][n] = (f32x4){0.f, 0.f, 0.f, 0.f};
;         }
;         cur = nxt; cA = nA; cB = nB; ++ui;
	v_mfma_f32_16x16x32_bf16 v[62:65], v[134:137], v[170:173], v[62:65]
	v_mfma_f32_16x16x32_bf16 v[46:49], v[142:145], v[170:173], v[46:49]
	v_mfma_f32_16x16x32_bf16 v[70:73], v[142:145], v[178:181], v[70:73]
	v_mfma_f32_16x16x32_bf16 v[82:85], v[134:137], v[178:181], v[82:85]
	v_mfma_f32_16x16x32_bf16 v[94:97], v[134:137], v[186:189], v[94:97]
	v_mfma_f32_16x16x32_bf16 v[90:93], v[142:145], v[186:189], v[90:93]
	v_mfma_f32_16x16x32_bf16 v[26:29], v[142:145], v[200:203], v[26:29]
	v_mfma_f32_16x16x32_bf16 v[38:41], v[134:137], v[200:203], v[38:41]
	v_mfma_f32_16x16x32_bf16 v[62:65], v[138:141], v[174:177], v[62:65]
	v_mfma_f32_16x16x32_bf16 v[46:49], v[146:149], v[174:177], v[46:49]
	v_mfma_f32_16x16x32_bf16 v[70:73], v[146:149], v[182:185], v[70:73]
	v_mfma_f32_16x16x32_bf16 v[82:85], v[138:141], v[182:185], v[82:85]
	v_mfma_f32_16x16x32_bf16 v[94:97], v[138:141], v[190:193], v[94:97]
	v_mfma_f32_16x16x32_bf16 v[90:93], v[146:149], v[190:193], v[90:93]
	v_mfma_f32_16x16x32_bf16 v[26:29], v[146:149], v[206:209], v[26:29]
	v_mfma_f32_16x16x32_bf16 v[38:41], v[138:141], v[206:209], v[38:41]
	v_mfma_f32_16x16x32_bf16 v[42:45], v[150:153], v[170:173], v[42:45]
	v_mfma_f32_16x16x32_bf16 v[30:33], v[158:161], v[170:173], v[30:33]
	v_mfma_f32_16x16x32_bf16 v[86:89], v[158:161], v[178:181], v[86:89]
	v_mfma_f32_16x16x32_bf16 v[66:69], v[150:153], v[178:181], v[66:69]
	v_mfma_f32_16x16x32_bf16 v[58:61], v[150:153], v[186:189], v[58:61]
	v_mfma_f32_16x16x32_bf16 v[34:37], v[158:161], v[186:189], v[34:37]
	v_mfma_f32_16x16x32_bf16 v[2:5], v[158:161], v[200:203], v[2:5]
	v_mfma_f32_16x16x32_bf16 v[10:13], v[150:153], v[200:203], v[10:13]
	v_mfma_f32_16x16x32_bf16 v[42:45], v[154:157], v[174:177], v[42:45]
	v_mfma_f32_16x16x32_bf16 v[30:33], v[166:169], v[174:177], v[30:33]
	v_mfma_f32_16x16x32_bf16 v[86:89], v[166:169], v[182:185], v[86:89]
	v_mfma_f32_16x16x32_bf16 v[66:69], v[154:157], v[182:185], v[66:69]
	v_mfma_f32_16x16x32_bf16 v[58:61], v[154:157], v[190:193], v[58:61]
	v_mfma_f32_16x16x32_bf16 v[34:37], v[166:169], v[190:193], v[34:37]
	v_mfma_f32_16x16x32_bf16 v[2:5], v[166:169], v[206:209], v[2:5]
	v_mfma_f32_16x16x32_bf16 v[10:13], v[154:157], v[206:209], v[10:13]
	s_barrier
	s_setprio 0
	s_add_i32 s39, s39, 2
	s_add_u32 s22, s22, 0x100
	s_addc_u32 s23, s23, 0
	s_cmpk_gt_u32 s39, 0x55
	s_cbranch_scc0 .LBB0_1584
	s_and_b64 vcc, exec, s[36:37]
	s_cbranch_vccnz .LBB0_1572
	v_mov_b32_e32 v2, 0
	s_mov_b32 s10, s73
	s_mov_b32 s25, s74
	s_mov_b64 s[12:13], s[20:21]
	s_mov_b64 s[14:15], s[16:17]
	s_mov_b32 s72, s75
	v_mov_b32_e32 v3, v2
	v_mov_b32_e32 v4, v2
	v_mov_b32_e32 v5, v2
	v_mov_b32_e32 v10, v2
	v_mov_b32_e32 v11, v2
	v_mov_b32_e32 v12, v2
	v_mov_b32_e32 v13, v2
	v_mov_b32_e32 v34, v2
	v_mov_b32_e32 v35, v2
	v_mov_b32_e32 v36, v2
	v_mov_b32_e32 v37, v2
	v_mov_b32_e32 v58, v2
	v_mov_b32_e32 v59, v2
	v_mov_b32_e32 v60, v2
	v_mov_b32_e32 v61, v2
	v_mov_b32_e32 v86, v2
	v_mov_b32_e32 v87, v2
	v_mov_b32_e32 v88, v2
	v_mov_b32_e32 v89, v2
	v_mov_b32_e32 v66, v2
	v_mov_b32_e32 v67, v2
	v_mov_b32_e32 v68, v2
	v_mov_b32_e32 v69, v2
	v_mov_b32_e32 v30, v2
	v_mov_b32_e32 v31, v2
	v_mov_b32_e32 v32, v2
	v_mov_b32_e32 v33, v2
	v_mov_b32_e32 v42, v2
	v_mov_b32_e32 v43, v2
	v_mov_b32_e32 v44, v2
	v_mov_b32_e32 v45, v2
	v_mov_b32_e32 v26, v2
	v_mov_b32_e32 v27, v2
	v_mov_b32_e32 v28, v2
	v_mov_b32_e32 v29, v2
	v_mov_b32_e32 v38, v2
	v_mov_b32_e32 v39, v2
	v_mov_b32_e32 v40, v2
	v_mov_b32_e32 v41, v2
	v_mov_b32_e32 v90, v2
	v_mov_b32_e32 v91, v2
	v_mov_b32_e32 v92, v2
	v_mov_b32_e32 v93, v2
	v_mov_b32_e32 v94, v2
	v_mov_b32_e32 v95, v2
	v_mov_b32_e32 v96, v2
	v_mov_b32_e32 v97, v2
	v_mov_b32_e32 v70, v2
	v_mov_b32_e32 v71, v2
	v_mov_b32_e32 v72, v2
	v_mov_b32_e32 v73, v2
	v_mov_b32_e32 v82, v2
	v_mov_b32_e32 v83, v2
	v_mov_b32_e32 v84, v2
	v_mov_b32_e32 v85, v2
	v_mov_b32_e32 v46, v2
	v_mov_b32_e32 v47, v2
	v_mov_b32_e32 v48, v2
	v_mov_b32_e32 v49, v2
	v_mov_b32_e32 v62, v2
	v_mov_b32_e32 v63, v2
	v_mov_b32_e32 v64, v2
	v_mov_b32_e32 v65, v2
	v_mov_b32_e32 v126, v2
	v_mov_b32_e32 v127, v2
	v_mov_b32_e32 v128, v2
	v_mov_b32_e32 v129, v2
	v_mov_b32_e32 v114, v2
	v_mov_b32_e32 v115, v2
	v_mov_b32_e32 v116, v2
	v_mov_b32_e32 v117, v2
	v_mov_b32_e32 v110, v2
	v_mov_b32_e32 v111, v2
	v_mov_b32_e32 v112, v2
	v_mov_b32_e32 v113, v2
	v_mov_b32_e32 v98, v2
	v_mov_b32_e32 v99, v2
	v_mov_b32_e32 v100, v2
	v_mov_b32_e32 v101, v2
	v_mov_b32_e32 v78, v2
	v_mov_b32_e32 v79, v2
	v_mov_b32_e32 v80, v2
	v_mov_b32_e32 v81, v2
	v_mov_b32_e32 v50, v2
	v_mov_b32_e32 v51, v2
	v_mov_b32_e32 v52, v2
	v_mov_b32_e32 v53, v2
	v_mov_b32_e32 v18, v2
	v_mov_b32_e32 v19, v2
	v_mov_b32_e32 v20, v2
	v_mov_b32_e32 v21, v2
	v_mov_b32_e32 v6, v2
	v_mov_b32_e32 v7, v2
	v_mov_b32_e32 v8, v2
	v_mov_b32_e32 v9, v2
	v_mov_b32_e32 v118, v2
	v_mov_b32_e32 v119, v2
	v_mov_b32_e32 v120, v2
	v_mov_b32_e32 v121, v2
	v_mov_b32_e32 v122, v2
	v_mov_b32_e32 v123, v2
	v_mov_b32_e32 v124, v2
	v_mov_b32_e32 v125, v2
	v_mov_b32_e32 v102, v2
	v_mov_b32_e32 v103, v2
	v_mov_b32_e32 v104, v2
	v_mov_b32_e32 v105, v2
	v_mov_b32_e32 v106, v2
	v_mov_b32_e32 v107, v2
	v_mov_b32_e32 v108, v2
	v_mov_b32_e32 v109, v2
	v_mov_b32_e32 v54, v2
	v_mov_b32_e32 v55, v2
	v_mov_b32_e32 v56, v2
	v_mov_b32_e32 v57, v2
	v_mov_b32_e32 v74, v2
	v_mov_b32_e32 v75, v2
	v_mov_b32_e32 v76, v2
	v_mov_b32_e32 v77, v2
	v_mov_b32_e32 v14, v2
	v_mov_b32_e32 v15, v2
	v_mov_b32_e32 v16, v2
	v_mov_b32_e32 v17, v2
	v_mov_b32_e32 v22, v2
	v_mov_b32_e32 v23, v2
	v_mov_b32_e32 v24, v2
	v_mov_b32_e32 v25, v2
	s_branch .LBB0_1572
